# v16 + GEMM K-loop load segments: fragment ds_reads issued first, before pointer SALU and LDS-DMA address/issue
# speedup vs baseline: 1.0034x; 1.0034x over previous
.LBB0_849:
	ds_read_b128 v[146:149], v155
	ds_read_b128 v[160:163], v155 offset:1024
	ds_read_b128 v[164:167], v155 offset:2048
	ds_read_b128 v[168:171], v155 offset:3072
	ds_read_b128 v[172:175], v156
	ds_read_b128 v[176:179], v156 offset:1024
	ds_read_b128 v[180:183], v156 offset:2048
	ds_read_b128 v[184:187], v156 offset:3072
	ds_read_b128 v[188:191], v157
	ds_read_b128 v[192:195], v157 offset:1024
	ds_read_b128 v[196:199], v157 offset:2048
	ds_read_b128 v[200:203], v157 offset:3072
	ds_read_b128 v[204:207], v157 offset:4096
	ds_read_b128 v[208:211], v157 offset:5120
	ds_read_b128 v[212:215], v157 offset:6144
	ds_read_b128 v[216:219], v157 offset:7168
	s_add_u32 s74, s72, 0xfff80080
	s_addc_u32 s75, s73, -1
	s_cmp_eq_u32 s85, 28
	s_cselect_b32 s77, s63, s75
	s_cselect_b32 s76, s69, s74
	s_cselect_b32 s75, s57, s84
	s_cselect_b32 s74, s71, s83
	v_lshl_add_u64 v[220:221], s[72:73], 0, v[138:139]
	s_add_i32 m0, s3, 0xc000
	s_nop 0
	global_load_lds_dwordx4 v[220:221], off
	v_lshl_add_u64 v[220:221], s[72:73], 0, v[140:141]
	s_add_i32 m0, s3, 0xe000
	s_nop 0
	global_load_lds_dwordx4 v[220:221], off
	s_waitcnt vmcnt(8)
	s_waitcnt lgkmcnt(0)
	s_barrier
	s_setprio 1
	s_waitcnt lgkmcnt(0)
	v_mfma_f32_16x16x32_bf16 v[124:127], v[146:149], v[188:191], v[124:127]
	v_mfma_f32_16x16x32_bf16 v[120:123], v[164:167], v[188:191], v[120:123]
	v_mfma_f32_16x16x32_bf16 v[108:111], v[146:149], v[196:199], v[108:111]
	v_mfma_f32_16x16x32_bf16 v[104:107], v[164:167], v[196:199], v[104:107]
	v_mfma_f32_16x16x32_bf16 v[92:95], v[146:149], v[204:207], v[92:95]
	v_mfma_f32_16x16x32_bf16 v[88:91], v[164:167], v[204:207], v[88:91]
	v_mfma_f32_16x16x32_bf16 v[76:79], v[146:149], v[212:215], v[76:79]
	v_mfma_f32_16x16x32_bf16 v[72:75], v[164:167], v[212:215], v[72:75]
	v_mfma_f32_16x16x32_bf16 v[124:127], v[160:163], v[192:195], v[124:127]
	v_mfma_f32_16x16x32_bf16 v[120:123], v[168:171], v[192:195], v[120:123]
	v_mfma_f32_16x16x32_bf16 v[108:111], v[160:163], v[200:203], v[108:111]
	v_mfma_f32_16x16x32_bf16 v[104:107], v[168:171], v[200:203], v[104:107]
	v_mfma_f32_16x16x32_bf16 v[92:95], v[160:163], v[208:211], v[92:95]
	v_mfma_f32_16x16x32_bf16 v[88:91], v[168:171], v[208:211], v[88:91]
	v_mfma_f32_16x16x32_bf16 v[76:79], v[160:163], v[216:219], v[76:79]
	v_mfma_f32_16x16x32_bf16 v[72:75], v[168:171], v[216:219], v[72:75]
	v_mfma_f32_16x16x32_bf16 v[116:119], v[172:175], v[188:191], v[116:119]
	v_mfma_f32_16x16x32_bf16 v[112:115], v[180:183], v[188:191], v[112:115]
	v_mfma_f32_16x16x32_bf16 v[100:103], v[172:175], v[196:199], v[100:103]
	v_mfma_f32_16x16x32_bf16 v[96:99], v[180:183], v[196:199], v[96:99]
	v_mfma_f32_16x16x32_bf16 v[84:87], v[172:175], v[204:207], v[84:87]
	v_mfma_f32_16x16x32_bf16 v[80:83], v[180:183], v[204:207], v[80:83]
	v_mfma_f32_16x16x32_bf16 v[68:71], v[172:175], v[212:215], v[68:71]
	v_mfma_f32_16x16x32_bf16 v[64:67], v[180:183], v[212:215], v[64:67]
	v_mfma_f32_16x16x32_bf16 v[116:119], v[176:179], v[192:195], v[116:119]
	v_mfma_f32_16x16x32_bf16 v[112:115], v[184:187], v[192:195], v[112:115]
	v_mfma_f32_16x16x32_bf16 v[100:103], v[176:179], v[200:203], v[100:103]
	v_mfma_f32_16x16x32_bf16 v[96:99], v[184:187], v[200:203], v[96:99]
	v_mfma_f32_16x16x32_bf16 v[84:87], v[176:179], v[208:211], v[84:87]
	v_mfma_f32_16x16x32_bf16 v[80:83], v[184:187], v[208:211], v[80:83]
	v_mfma_f32_16x16x32_bf16 v[68:71], v[176:179], v[216:219], v[68:71]
	v_mfma_f32_16x16x32_bf16 v[64:67], v[184:187], v[216:219], v[64:67]
	s_setprio 0
	s_barrier
	ds_read_b128 v[188:191], v157 offset:16384
	ds_read_b128 v[192:195], v157 offset:17408
	ds_read_b128 v[196:199], v157 offset:18432
	ds_read_b128 v[200:203], v157 offset:19456
	ds_read_b128 v[204:207], v157 offset:20480
	ds_read_b128 v[208:211], v157 offset:21504
	ds_read_b128 v[212:215], v157 offset:22528
	ds_read_b128 v[216:219], v157 offset:23552
	s_add_i32 s86, s79, s94
	v_lshl_add_u64 v[220:221], s[74:75], 0, v[130:131]
	s_mov_b32 m0, s86
	s_nop 0
	global_load_lds_dwordx4 v[220:221], off
	s_add_i32 m0, s86, 0x2000
	s_add_u32 s86, s74, 0x80000
	v_lshl_add_u64 v[222:223], s[74:75], 0, v[134:135]
	s_addc_u32 s87, s75, 0
	s_add_i32 s88, s81, s94
	global_load_lds_dwordx4 v[222:223], off
	v_lshl_add_u64 v[224:225], s[86:87], 0, v[130:131]
	s_mov_b32 m0, s88
	v_lshl_add_u64 v[226:227], s[76:77], 0, v[132:133]
	global_load_lds_dwordx4 v[224:225], off
	v_lshl_add_u64 v[224:225], s[86:87], 0, v[134:135]
	s_add_i32 m0, s88, 0x2000
	s_nop 0
	global_load_lds_dwordx4 v[224:225], off
	v_lshl_add_u64 v[224:225], s[76:77], 0, v[128:129]
	s_mov_b32 m0, s3
	s_nop 0
	global_load_lds_dwordx4 v[224:225], off
	s_mov_b32 m0, s6
	s_nop 0
	global_load_lds_dwordx4 v[226:227], off
	s_waitcnt vmcnt(8)
	s_waitcnt lgkmcnt(0)
	s_barrier
	s_setprio 1
	s_waitcnt lgkmcnt(0)
	v_mfma_f32_16x16x32_bf16 v[60:63], v[146:149], v[188:191], v[60:63]
	v_mfma_f32_16x16x32_bf16 v[56:59], v[164:167], v[188:191], v[56:59]
	v_mfma_f32_16x16x32_bf16 v[44:47], v[146:149], v[196:199], v[44:47]
	v_mfma_f32_16x16x32_bf16 v[40:43], v[164:167], v[196:199], v[40:43]
	v_mfma_f32_16x16x32_bf16 v[28:31], v[146:149], v[204:207], v[28:31]
	v_mfma_f32_16x16x32_bf16 v[24:27], v[164:167], v[204:207], v[24:27]
	v_mfma_f32_16x16x32_bf16 v[12:15], v[146:149], v[212:215], v[12:15]
	v_mfma_f32_16x16x32_bf16 v[8:11], v[164:167], v[212:215], v[8:11]
	v_mfma_f32_16x16x32_bf16 v[60:63], v[160:163], v[192:195], v[60:63]
	v_mfma_f32_16x16x32_bf16 v[56:59], v[168:171], v[192:195], v[56:59]
	v_mfma_f32_16x16x32_bf16 v[44:47], v[160:163], v[200:203], v[44:47]
	v_mfma_f32_16x16x32_bf16 v[40:43], v[168:171], v[200:203], v[40:43]
	v_mfma_f32_16x16x32_bf16 v[28:31], v[160:163], v[208:211], v[28:31]
	v_mfma_f32_16x16x32_bf16 v[24:27], v[168:171], v[208:211], v[24:27]
	v_mfma_f32_16x16x32_bf16 v[12:15], v[160:163], v[216:219], v[12:15]
	v_mfma_f32_16x16x32_bf16 v[8:11], v[168:171], v[216:219], v[8:11]
	v_mfma_f32_16x16x32_bf16 v[52:55], v[172:175], v[188:191], v[52:55]
	v_mfma_f32_16x16x32_bf16 v[48:51], v[180:183], v[188:191], v[48:51]
	v_mfma_f32_16x16x32_bf16 v[36:39], v[172:175], v[196:199], v[36:39]
	v_mfma_f32_16x16x32_bf16 v[32:35], v[180:183], v[196:199], v[32:35]
	v_mfma_f32_16x16x32_bf16 v[20:23], v[172:175], v[204:207], v[20:23]
	v_mfma_f32_16x16x32_bf16 v[16:19], v[180:183], v[204:207], v[16:19]
	v_mfma_f32_16x16x32_bf16 v[4:7], v[172:175], v[212:215], v[4:7]
	v_mfma_f32_16x16x32_bf16 v[0:3], v[180:183], v[212:215], v[0:3]
	v_mfma_f32_16x16x32_bf16 v[52:55], v[176:179], v[192:195], v[52:55]
	v_mfma_f32_16x16x32_bf16 v[48:51], v[184:187], v[192:195], v[48:51]
	v_mfma_f32_16x16x32_bf16 v[36:39], v[176:179], v[200:203], v[36:39]
	v_mfma_f32_16x16x32_bf16 v[32:35], v[184:187], v[200:203], v[32:35]
	v_mfma_f32_16x16x32_bf16 v[20:23], v[176:179], v[208:211], v[20:23]
	v_mfma_f32_16x16x32_bf16 v[16:19], v[184:187], v[208:211], v[16:19]
	v_mfma_f32_16x16x32_bf16 v[4:7], v[176:179], v[216:219], v[4:7]
	v_mfma_f32_16x16x32_bf16 v[0:3], v[184:187], v[216:219], v[0:3]
	s_setprio 0
	s_barrier
	s_add_i32 s86, 0, 0x18000
	v_add_u32_e32 v159, s86, v151
	ds_read_b128 v[146:149], v159
	ds_read_b128 v[160:163], v159 offset:1024
	ds_read_b128 v[164:167], v159 offset:2048
	ds_read_b128 v[168:171], v159 offset:3072
	s_add_i32 s87, 0, 0x1c000
	v_add_u32_e32 v159, s87, v151
	ds_read_b128 v[172:175], v159
	ds_read_b128 v[176:179], v159 offset:1024
	ds_read_b128 v[180:183], v159 offset:2048
	ds_read_b128 v[184:187], v159 offset:3072
	ds_read_b128 v[188:191], v157 offset:32768
	ds_read_b128 v[192:195], v157 offset:33792
	ds_read_b128 v[196:199], v157 offset:34816
	ds_read_b128 v[200:203], v157 offset:35840
	ds_read_b128 v[204:207], v157 offset:36864
	ds_read_b128 v[208:211], v157 offset:37888
	ds_read_b128 v[212:215], v157 offset:38912
	ds_read_b128 v[216:219], v157 offset:39936
	s_add_u32 s76, s76, 0x80000
	s_addc_u32 s77, s77, 0
	s_mov_b32 m0, s7
	v_lshl_add_u64 v[228:229], s[76:77], 0, v[128:129]
	global_load_lds_dwordx4 v[228:229], off
	v_lshl_add_u64 v[228:229], s[76:77], 0, v[132:133]
	s_mov_b32 m0, s29
	s_nop 0
	global_load_lds_dwordx4 v[228:229], off
	s_waitcnt vmcnt(8)
	s_waitcnt lgkmcnt(0)
	s_barrier
	s_setprio 1
	s_waitcnt lgkmcnt(0)
	v_mfma_f32_16x16x32_bf16 v[124:127], v[146:149], v[188:191], v[124:127]
	v_mfma_f32_16x16x32_bf16 v[120:123], v[164:167], v[188:191], v[120:123]
	v_mfma_f32_16x16x32_bf16 v[108:111], v[146:149], v[196:199], v[108:111]
	v_mfma_f32_16x16x32_bf16 v[104:107], v[164:167], v[196:199], v[104:107]
	v_mfma_f32_16x16x32_bf16 v[92:95], v[146:149], v[204:207], v[92:95]
	v_mfma_f32_16x16x32_bf16 v[88:91], v[164:167], v[204:207], v[88:91]
	v_mfma_f32_16x16x32_bf16 v[76:79], v[146:149], v[212:215], v[76:79]
	v_mfma_f32_16x16x32_bf16 v[72:75], v[164:167], v[212:215], v[72:75]
	v_mfma_f32_16x16x32_bf16 v[124:127], v[160:163], v[192:195], v[124:127]
	v_mfma_f32_16x16x32_bf16 v[120:123], v[168:171], v[192:195], v[120:123]
	v_mfma_f32_16x16x32_bf16 v[108:111], v[160:163], v[200:203], v[108:111]
	v_mfma_f32_16x16x32_bf16 v[104:107], v[168:171], v[200:203], v[104:107]
	v_mfma_f32_16x16x32_bf16 v[92:95], v[160:163], v[208:211], v[92:95]
	v_mfma_f32_16x16x32_bf16 v[88:91], v[168:171], v[208:211], v[88:91]
	v_mfma_f32_16x16x32_bf16 v[76:79], v[160:163], v[216:219], v[76:79]
	v_mfma_f32_16x16x32_bf16 v[72:75], v[168:171], v[216:219], v[72:75]
	v_mfma_f32_16x16x32_bf16 v[116:119], v[172:175], v[188:191], v[116:119]
	v_mfma_f32_16x16x32_bf16 v[112:115], v[180:183], v[188:191], v[112:115]
	v_mfma_f32_16x16x32_bf16 v[100:103], v[172:175], v[196:199], v[100:103]
	v_mfma_f32_16x16x32_bf16 v[96:99], v[180:183], v[196:199], v[96:99]
	v_mfma_f32_16x16x32_bf16 v[84:87], v[172:175], v[204:207], v[84:87]
	v_mfma_f32_16x16x32_bf16 v[80:83], v[180:183], v[204:207], v[80:83]
	v_mfma_f32_16x16x32_bf16 v[68:71], v[172:175], v[212:215], v[68:71]
	v_mfma_f32_16x16x32_bf16 v[64:67], v[180:183], v[212:215], v[64:67]
	v_mfma_f32_16x16x32_bf16 v[116:119], v[176:179], v[192:195], v[116:119]
	v_mfma_f32_16x16x32_bf16 v[112:115], v[184:187], v[192:195], v[112:115]
	v_mfma_f32_16x16x32_bf16 v[100:103], v[176:179], v[200:203], v[100:103]
	v_mfma_f32_16x16x32_bf16 v[96:99], v[184:187], v[200:203], v[96:99]
	v_mfma_f32_16x16x32_bf16 v[84:87], v[176:179], v[208:211], v[84:87]
	v_mfma_f32_16x16x32_bf16 v[80:83], v[184:187], v[208:211], v[80:83]
	v_mfma_f32_16x16x32_bf16 v[68:71], v[176:179], v[216:219], v[68:71]
	v_mfma_f32_16x16x32_bf16 v[64:67], v[184:187], v[216:219], v[64:67]
	s_setprio 0
	s_barrier
	ds_read_b128 v[188:191], v157 offset:49152
	ds_read_b128 v[192:195], v157 offset:50176
	ds_read_b128 v[196:199], v157 offset:51200
	ds_read_b128 v[200:203], v157 offset:52224
	ds_read_b128 v[204:207], v157 offset:53248
	ds_read_b128 v[208:211], v157 offset:54272
	ds_read_b128 v[212:215], v157 offset:55296
	ds_read_b128 v[216:219], v157 offset:56320
	s_add_i32 s76, s86, s94
	v_lshl_add_u64 v[220:221], v[220:221], 0, s[18:19]
	s_mov_b32 m0, s76
	s_nop 0
	global_load_lds_dwordx4 v[220:221], off
	s_add_i32 m0, s76, 0x2000
	s_add_u32 s74, s74, 0x80080
	v_lshl_add_u64 v[220:221], v[222:223], 0, s[18:19]
	s_addc_u32 s75, s75, 0
	s_add_i32 s76, s87, s94
	global_load_lds_dwordx4 v[220:221], off
	v_lshl_add_u64 v[220:221], s[74:75], 0, v[130:131]
	s_mov_b32 m0, s76
	s_nop 0
	global_load_lds_dwordx4 v[220:221], off
	v_lshl_add_u64 v[220:221], s[74:75], 0, v[134:135]
	s_add_i32 m0, s76, 0x2000
	s_nop 0
	global_load_lds_dwordx4 v[220:221], off
	v_lshl_add_u64 v[220:221], v[224:225], 0, s[18:19]
	s_mov_b32 m0, s34
	s_nop 0
	global_load_lds_dwordx4 v[220:221], off
	v_lshl_add_u64 v[220:221], v[226:227], 0, s[18:19]
	s_mov_b32 m0, s35
	s_nop 0
	global_load_lds_dwordx4 v[220:221], off
	s_waitcnt vmcnt(8)
	s_waitcnt lgkmcnt(0)
	s_barrier
	s_setprio 1
	s_waitcnt lgkmcnt(0)
	v_mfma_f32_16x16x32_bf16 v[60:63], v[146:149], v[188:191], v[60:63]
	v_mfma_f32_16x16x32_bf16 v[56:59], v[164:167], v[188:191], v[56:59]
	v_mfma_f32_16x16x32_bf16 v[44:47], v[146:149], v[196:199], v[44:47]
	v_mfma_f32_16x16x32_bf16 v[40:43], v[164:167], v[196:199], v[40:43]
	v_mfma_f32_16x16x32_bf16 v[28:31], v[146:149], v[204:207], v[28:31]
	v_mfma_f32_16x16x32_bf16 v[24:27], v[164:167], v[204:207], v[24:27]
	v_mfma_f32_16x16x32_bf16 v[12:15], v[146:149], v[212:215], v[12:15]
	v_mfma_f32_16x16x32_bf16 v[8:11], v[164:167], v[212:215], v[8:11]
	v_mfma_f32_16x16x32_bf16 v[60:63], v[160:163], v[192:195], v[60:63]
	v_mfma_f32_16x16x32_bf16 v[56:59], v[168:171], v[192:195], v[56:59]
	v_mfma_f32_16x16x32_bf16 v[44:47], v[160:163], v[200:203], v[44:47]
	v_mfma_f32_16x16x32_bf16 v[40:43], v[168:171], v[200:203], v[40:43]
	v_mfma_f32_16x16x32_bf16 v[28:31], v[160:163], v[208:211], v[28:31]
	v_mfma_f32_16x16x32_bf16 v[24:27], v[168:171], v[208:211], v[24:27]
	v_mfma_f32_16x16x32_bf16 v[12:15], v[160:163], v[216:219], v[12:15]
	v_mfma_f32_16x16x32_bf16 v[8:11], v[168:171], v[216:219], v[8:11]
	v_mfma_f32_16x16x32_bf16 v[52:55], v[172:175], v[188:191], v[52:55]
	v_mfma_f32_16x16x32_bf16 v[48:51], v[180:183], v[188:191], v[48:51]
	v_mfma_f32_16x16x32_bf16 v[36:39], v[172:175], v[196:199], v[36:39]
	v_mfma_f32_16x16x32_bf16 v[32:35], v[180:183], v[196:199], v[32:35]
	v_mfma_f32_16x16x32_bf16 v[20:23], v[172:175], v[204:207], v[20:23]
	v_mfma_f32_16x16x32_bf16 v[16:19], v[180:183], v[204:207], v[16:19]
	v_mfma_f32_16x16x32_bf16 v[4:7], v[172:175], v[212:215], v[4:7]
	v_mfma_f32_16x16x32_bf16 v[0:3], v[180:183], v[212:215], v[0:3]
	v_mfma_f32_16x16x32_bf16 v[52:55], v[176:179], v[192:195], v[52:55]
	v_mfma_f32_16x16x32_bf16 v[48:51], v[184:187], v[192:195], v[48:51]
	v_mfma_f32_16x16x32_bf16 v[36:39], v[176:179], v[200:203], v[36:39]
	v_mfma_f32_16x16x32_bf16 v[32:35], v[184:187], v[200:203], v[32:35]
	v_mfma_f32_16x16x32_bf16 v[20:23], v[176:179], v[208:211], v[20:23]
	v_mfma_f32_16x16x32_bf16 v[16:19], v[184:187], v[208:211], v[16:19]
	v_mfma_f32_16x16x32_bf16 v[4:7], v[176:179], v[216:219], v[4:7]
	v_mfma_f32_16x16x32_bf16 v[0:3], v[184:187], v[216:219], v[0:3]
	s_setprio 0
	s_barrier
	s_add_i32 s85, s85, 2
	s_add_u32 s72, s72, 0x100
	s_addc_u32 s73, s73, 0
	s_add_u32 s83, s83, 0x100
	s_addc_u32 s84, s84, 0
	s_cmp_gt_u32 s85, 29
	s_cbranch_scc0 .LBB0_849
	s_and_b64 vcc, exec, s[20:21]
	s_cbranch_vccz .LBB0_852
	s_barrier

.LBB0_946:
	ds_read_b128 v[148:151], v143
	ds_read_b128 v[152:155], v143 offset:1024
	ds_read_b128 v[156:159], v143 offset:2048
	ds_read_b128 v[160:163], v143 offset:3072
	ds_read_b128 v[164:167], v144
	ds_read_b128 v[168:171], v144 offset:1024
	ds_read_b128 v[172:175], v144 offset:2048
	ds_read_b128 v[176:179], v144 offset:3072
	ds_read_b128 v[180:183], v145
	ds_read_b128 v[184:187], v145 offset:1024
	ds_read_b128 v[188:191], v145 offset:2048
	ds_read_b128 v[192:195], v145 offset:3072
	ds_read_b128 v[196:199], v145 offset:4096
	ds_read_b128 v[200:203], v145 offset:5120
	ds_read_b128 v[204:207], v145 offset:6144
	ds_read_b128 v[208:211], v145 offset:7168
	s_add_u32 s18, s14, s16
	s_addc_u32 s19, s15, s17
	s_add_u32 s18, s18, 0x7498100
	s_addc_u32 s19, s19, 0
	s_add_u32 s20, s24, s16
	s_addc_u32 s21, s25, s17
	s_add_u32 s69, s20, 0x1308100
	s_addc_u32 s70, s21, 0
	s_cmpk_eq_i32 s16, 0xf00
	s_cselect_b32 s21, s11, s19
	s_cselect_b32 s20, s10, s18
	s_cselect_b32 s19, s9, s70
	s_cselect_b32 s18, s8, s69
	s_mov_b32 m0, s46
	v_lshl_add_u64 v[212:213], v[136:137], 0, s[16:17]
	global_load_lds_dwordx4 v[212:213], off
	v_lshl_add_u64 v[212:213], v[138:139], 0, s[16:17]
	s_mov_b32 m0, s56
	s_nop 0
	global_load_lds_dwordx4 v[212:213], off
	s_waitcnt vmcnt(8)
	s_waitcnt lgkmcnt(0)
	s_barrier
	s_setprio 1
	s_waitcnt lgkmcnt(0)
	v_mfma_f32_16x16x32_bf16 v[124:127], v[148:151], v[180:183], v[124:127]
	v_mfma_f32_16x16x32_bf16 v[120:123], v[156:159], v[180:183], v[120:123]
	v_mfma_f32_16x16x32_bf16 v[108:111], v[148:151], v[188:191], v[108:111]
	v_mfma_f32_16x16x32_bf16 v[104:107], v[156:159], v[188:191], v[104:107]
	v_mfma_f32_16x16x32_bf16 v[92:95], v[148:151], v[196:199], v[92:95]
	v_mfma_f32_16x16x32_bf16 v[88:91], v[156:159], v[196:199], v[88:91]
	v_mfma_f32_16x16x32_bf16 v[76:79], v[148:151], v[204:207], v[76:79]
	v_mfma_f32_16x16x32_bf16 v[72:75], v[156:159], v[204:207], v[72:75]
	v_mfma_f32_16x16x32_bf16 v[124:127], v[152:155], v[184:187], v[124:127]
	v_mfma_f32_16x16x32_bf16 v[120:123], v[160:163], v[184:187], v[120:123]
	v_mfma_f32_16x16x32_bf16 v[108:111], v[152:155], v[192:195], v[108:111]
	v_mfma_f32_16x16x32_bf16 v[104:107], v[160:163], v[192:195], v[104:107]
	v_mfma_f32_16x16x32_bf16 v[92:95], v[152:155], v[200:203], v[92:95]
	v_mfma_f32_16x16x32_bf16 v[88:91], v[160:163], v[200:203], v[88:91]
	v_mfma_f32_16x16x32_bf16 v[76:79], v[152:155], v[208:211], v[76:79]
	v_mfma_f32_16x16x32_bf16 v[72:75], v[160:163], v[208:211], v[72:75]
	v_mfma_f32_16x16x32_bf16 v[116:119], v[164:167], v[180:183], v[116:119]
	v_mfma_f32_16x16x32_bf16 v[112:115], v[172:175], v[180:183], v[112:115]
	v_mfma_f32_16x16x32_bf16 v[100:103], v[164:167], v[188:191], v[100:103]
	v_mfma_f32_16x16x32_bf16 v[96:99], v[172:175], v[188:191], v[96:99]
	v_mfma_f32_16x16x32_bf16 v[84:87], v[164:167], v[196:199], v[84:87]
	v_mfma_f32_16x16x32_bf16 v[80:83], v[172:175], v[196:199], v[80:83]
	v_mfma_f32_16x16x32_bf16 v[68:71], v[164:167], v[204:207], v[68:71]
	v_mfma_f32_16x16x32_bf16 v[64:67], v[172:175], v[204:207], v[64:67]
	v_mfma_f32_16x16x32_bf16 v[116:119], v[168:171], v[184:187], v[116:119]
	v_mfma_f32_16x16x32_bf16 v[112:115], v[176:179], v[184:187], v[112:115]
	v_mfma_f32_16x16x32_bf16 v[100:103], v[168:171], v[192:195], v[100:103]
	v_mfma_f32_16x16x32_bf16 v[96:99], v[176:179], v[192:195], v[96:99]
	v_mfma_f32_16x16x32_bf16 v[84:87], v[168:171], v[200:203], v[84:87]
	v_mfma_f32_16x16x32_bf16 v[80:83], v[176:179], v[200:203], v[80:83]
	v_mfma_f32_16x16x32_bf16 v[68:71], v[168:171], v[208:211], v[68:71]
	v_mfma_f32_16x16x32_bf16 v[64:67], v[176:179], v[208:211], v[64:67]
	s_setprio 0
	s_barrier
	ds_read_b128 v[180:183], v145 offset:16384
	ds_read_b128 v[184:187], v145 offset:17408
	ds_read_b128 v[188:191], v145 offset:18432
	ds_read_b128 v[192:195], v145 offset:19456
	ds_read_b128 v[196:199], v145 offset:20480
	ds_read_b128 v[200:203], v145 offset:21504
	ds_read_b128 v[204:207], v145 offset:22528
	ds_read_b128 v[208:211], v145 offset:23552
	s_mov_b32 m0, s57
	v_lshl_add_u64 v[212:213], s[18:19], 0, v[132:133]
	s_add_u32 s70, s18, 0x80000
	global_load_lds_dwordx4 v[212:213], off
	v_lshl_add_u64 v[214:215], s[18:19], 0, v[128:129]
	s_mov_b32 m0, s62
	s_addc_u32 s71, s19, 0
	global_load_lds_dwordx4 v[214:215], off
	v_lshl_add_u64 v[216:217], s[70:71], 0, v[132:133]
	s_mov_b32 m0, s63
	v_lshl_add_u64 v[218:219], s[20:21], 0, v[130:131]
	global_load_lds_dwordx4 v[216:217], off
	v_lshl_add_u64 v[216:217], s[70:71], 0, v[128:129]
	s_mov_b32 m0, s64
	s_nop 0
	global_load_lds_dwordx4 v[216:217], off
	v_lshl_add_u64 v[216:217], s[20:21], 0, v[134:135]
	s_mov_b32 m0, s3
	s_nop 0
	global_load_lds_dwordx4 v[216:217], off
	s_mov_b32 m0, s6
	s_nop 0
	global_load_lds_dwordx4 v[218:219], off
	s_waitcnt vmcnt(8)
	s_waitcnt lgkmcnt(0)
	s_barrier
	s_setprio 1
	s_waitcnt lgkmcnt(0)
	v_mfma_f32_16x16x32_bf16 v[60:63], v[148:151], v[180:183], v[60:63]
	v_mfma_f32_16x16x32_bf16 v[56:59], v[156:159], v[180:183], v[56:59]
	v_mfma_f32_16x16x32_bf16 v[44:47], v[148:151], v[188:191], v[44:47]
	v_mfma_f32_16x16x32_bf16 v[40:43], v[156:159], v[188:191], v[40:43]
	v_mfma_f32_16x16x32_bf16 v[28:31], v[148:151], v[196:199], v[28:31]
	v_mfma_f32_16x16x32_bf16 v[24:27], v[156:159], v[196:199], v[24:27]
	v_mfma_f32_16x16x32_bf16 v[12:15], v[148:151], v[204:207], v[12:15]
	v_mfma_f32_16x16x32_bf16 v[8:11], v[156:159], v[204:207], v[8:11]
	v_mfma_f32_16x16x32_bf16 v[60:63], v[152:155], v[184:187], v[60:63]
	v_mfma_f32_16x16x32_bf16 v[56:59], v[160:163], v[184:187], v[56:59]
	v_mfma_f32_16x16x32_bf16 v[44:47], v[152:155], v[192:195], v[44:47]
	v_mfma_f32_16x16x32_bf16 v[40:43], v[160:163], v[192:195], v[40:43]
	v_mfma_f32_16x16x32_bf16 v[28:31], v[152:155], v[200:203], v[28:31]
	v_mfma_f32_16x16x32_bf16 v[24:27], v[160:163], v[200:203], v[24:27]
	v_mfma_f32_16x16x32_bf16 v[12:15], v[152:155], v[208:211], v[12:15]
	v_mfma_f32_16x16x32_bf16 v[8:11], v[160:163], v[208:211], v[8:11]
	v_mfma_f32_16x16x32_bf16 v[52:55], v[164:167], v[180:183], v[52:55]
	v_mfma_f32_16x16x32_bf16 v[48:51], v[172:175], v[180:183], v[48:51]
	v_mfma_f32_16x16x32_bf16 v[36:39], v[164:167], v[188:191], v[36:39]
	v_mfma_f32_16x16x32_bf16 v[32:35], v[172:175], v[188:191], v[32:35]
	v_mfma_f32_16x16x32_bf16 v[20:23], v[164:167], v[196:199], v[20:23]
	v_mfma_f32_16x16x32_bf16 v[16:19], v[172:175], v[196:199], v[16:19]
	v_mfma_f32_16x16x32_bf16 v[4:7], v[164:167], v[204:207], v[4:7]
	v_mfma_f32_16x16x32_bf16 v[0:3], v[172:175], v[204:207], v[0:3]
	v_mfma_f32_16x16x32_bf16 v[52:55], v[168:171], v[184:187], v[52:55]
	v_mfma_f32_16x16x32_bf16 v[48:51], v[176:179], v[184:187], v[48:51]
	v_mfma_f32_16x16x32_bf16 v[36:39], v[168:171], v[192:195], v[36:39]
	v_mfma_f32_16x16x32_bf16 v[32:35], v[176:179], v[192:195], v[32:35]
	v_mfma_f32_16x16x32_bf16 v[20:23], v[168:171], v[200:203], v[20:23]
	v_mfma_f32_16x16x32_bf16 v[16:19], v[176:179], v[200:203], v[16:19]
	v_mfma_f32_16x16x32_bf16 v[4:7], v[168:171], v[208:211], v[4:7]
	v_mfma_f32_16x16x32_bf16 v[0:3], v[176:179], v[208:211], v[0:3]
	s_setprio 0
	s_barrier
	ds_read_b128 v[148:151], v146
	ds_read_b128 v[152:155], v146 offset:1024
	ds_read_b128 v[156:159], v146 offset:2048
	ds_read_b128 v[160:163], v146 offset:3072
	ds_read_b128 v[164:167], v147
	ds_read_b128 v[168:171], v147 offset:1024
	ds_read_b128 v[172:175], v147 offset:2048
	ds_read_b128 v[176:179], v147 offset:3072
	ds_read_b128 v[180:183], v145 offset:32768
	ds_read_b128 v[184:187], v145 offset:33792
	ds_read_b128 v[188:191], v145 offset:34816
	ds_read_b128 v[192:195], v145 offset:35840
	ds_read_b128 v[196:199], v145 offset:36864
	ds_read_b128 v[200:203], v145 offset:37888
	ds_read_b128 v[204:207], v145 offset:38912
	ds_read_b128 v[208:211], v145 offset:39936
	s_add_u32 s20, s20, 0x80000
	s_addc_u32 s21, s21, 0
	s_mov_b32 m0, s7
	v_lshl_add_u64 v[220:221], s[20:21], 0, v[134:135]
	global_load_lds_dwordx4 v[220:221], off
	v_lshl_add_u64 v[220:221], s[20:21], 0, v[130:131]
	s_mov_b32 m0, s29
	s_nop 0
	global_load_lds_dwordx4 v[220:221], off
	s_waitcnt vmcnt(8)
	s_waitcnt lgkmcnt(0)
	s_barrier
	s_setprio 1
	s_waitcnt lgkmcnt(0)
	v_mfma_f32_16x16x32_bf16 v[124:127], v[148:151], v[180:183], v[124:127]
	v_mfma_f32_16x16x32_bf16 v[120:123], v[156:159], v[180:183], v[120:123]
	v_mfma_f32_16x16x32_bf16 v[108:111], v[148:151], v[188:191], v[108:111]
	v_mfma_f32_16x16x32_bf16 v[104:107], v[156:159], v[188:191], v[104:107]
	v_mfma_f32_16x16x32_bf16 v[92:95], v[148:151], v[196:199], v[92:95]
	v_mfma_f32_16x16x32_bf16 v[88:91], v[156:159], v[196:199], v[88:91]
	v_mfma_f32_16x16x32_bf16 v[76:79], v[148:151], v[204:207], v[76:79]
	v_mfma_f32_16x16x32_bf16 v[72:75], v[156:159], v[204:207], v[72:75]
	v_mfma_f32_16x16x32_bf16 v[124:127], v[152:155], v[184:187], v[124:127]
	v_mfma_f32_16x16x32_bf16 v[120:123], v[160:163], v[184:187], v[120:123]
	v_mfma_f32_16x16x32_bf16 v[108:111], v[152:155], v[192:195], v[108:111]
	v_mfma_f32_16x16x32_bf16 v[104:107], v[160:163], v[192:195], v[104:107]
	v_mfma_f32_16x16x32_bf16 v[92:95], v[152:155], v[200:203], v[92:95]
	v_mfma_f32_16x16x32_bf16 v[88:91], v[160:163], v[200:203], v[88:91]
	v_mfma_f32_16x16x32_bf16 v[76:79], v[152:155], v[208:211], v[76:79]
	v_mfma_f32_16x16x32_bf16 v[72:75], v[160:163], v[208:211], v[72:75]
	v_mfma_f32_16x16x32_bf16 v[116:119], v[164:167], v[180:183], v[116:119]
	v_mfma_f32_16x16x32_bf16 v[112:115], v[172:175], v[180:183], v[112:115]
	v_mfma_f32_16x16x32_bf16 v[100:103], v[164:167], v[188:191], v[100:103]
	v_mfma_f32_16x16x32_bf16 v[96:99], v[172:175], v[188:191], v[96:99]
	v_mfma_f32_16x16x32_bf16 v[84:87], v[164:167], v[196:199], v[84:87]
	v_mfma_f32_16x16x32_bf16 v[80:83], v[172:175], v[196:199], v[80:83]
	v_mfma_f32_16x16x32_bf16 v[68:71], v[164:167], v[204:207], v[68:71]
	v_mfma_f32_16x16x32_bf16 v[64:67], v[172:175], v[204:207], v[64:67]
	v_mfma_f32_16x16x32_bf16 v[116:119], v[168:171], v[184:187], v[116:119]
	v_mfma_f32_16x16x32_bf16 v[112:115], v[176:179], v[184:187], v[112:115]
	v_mfma_f32_16x16x32_bf16 v[100:103], v[168:171], v[192:195], v[100:103]
	v_mfma_f32_16x16x32_bf16 v[96:99], v[176:179], v[192:195], v[96:99]
	v_mfma_f32_16x16x32_bf16 v[84:87], v[168:171], v[200:203], v[84:87]
	v_mfma_f32_16x16x32_bf16 v[80:83], v[176:179], v[200:203], v[80:83]
	v_mfma_f32_16x16x32_bf16 v[68:71], v[168:171], v[208:211], v[68:71]
	v_mfma_f32_16x16x32_bf16 v[64:67], v[176:179], v[208:211], v[64:67]
	s_setprio 0
	s_barrier
	ds_read_b128 v[180:183], v145 offset:49152
	ds_read_b128 v[184:187], v145 offset:50176
	ds_read_b128 v[188:191], v145 offset:51200
	ds_read_b128 v[192:195], v145 offset:52224
	ds_read_b128 v[196:199], v145 offset:53248
	ds_read_b128 v[200:203], v145 offset:54272
	ds_read_b128 v[204:207], v145 offset:55296
	ds_read_b128 v[208:211], v145 offset:56320
	s_mov_b32 m0, s65
	v_lshl_add_u64 v[212:213], v[212:213], 0, s[12:13]
	s_add_u32 s18, s18, 0x80080
	global_load_lds_dwordx4 v[212:213], off
	v_lshl_add_u64 v[212:213], v[214:215], 0, s[12:13]
	s_mov_b32 m0, s66
	s_addc_u32 s19, s19, 0
	global_load_lds_dwordx4 v[212:213], off
	v_lshl_add_u64 v[212:213], s[18:19], 0, v[132:133]
	s_mov_b32 m0, s67
	s_nop 0
	global_load_lds_dwordx4 v[212:213], off
	v_lshl_add_u64 v[212:213], s[18:19], 0, v[128:129]
	s_mov_b32 m0, s68
	s_nop 0
	global_load_lds_dwordx4 v[212:213], off
	v_lshl_add_u64 v[212:213], v[216:217], 0, s[12:13]
	s_mov_b32 m0, s30
	s_nop 0
	global_load_lds_dwordx4 v[212:213], off
	v_lshl_add_u64 v[212:213], v[218:219], 0, s[12:13]
	s_mov_b32 m0, s34
	s_nop 0
	global_load_lds_dwordx4 v[212:213], off
	s_waitcnt vmcnt(8)
	s_waitcnt lgkmcnt(0)
	s_barrier
	s_setprio 1
	s_waitcnt lgkmcnt(0)
	v_mfma_f32_16x16x32_bf16 v[60:63], v[148:151], v[180:183], v[60:63]
	v_mfma_f32_16x16x32_bf16 v[56:59], v[156:159], v[180:183], v[56:59]
	v_mfma_f32_16x16x32_bf16 v[44:47], v[148:151], v[188:191], v[44:47]
	v_mfma_f32_16x16x32_bf16 v[40:43], v[156:159], v[188:191], v[40:43]
	v_mfma_f32_16x16x32_bf16 v[28:31], v[148:151], v[196:199], v[28:31]
	v_mfma_f32_16x16x32_bf16 v[24:27], v[156:159], v[196:199], v[24:27]
	v_mfma_f32_16x16x32_bf16 v[12:15], v[148:151], v[204:207], v[12:15]
	v_mfma_f32_16x16x32_bf16 v[8:11], v[156:159], v[204:207], v[8:11]
	v_mfma_f32_16x16x32_bf16 v[60:63], v[152:155], v[184:187], v[60:63]
	v_mfma_f32_16x16x32_bf16 v[56:59], v[160:163], v[184:187], v[56:59]
	v_mfma_f32_16x16x32_bf16 v[44:47], v[152:155], v[192:195], v[44:47]
	v_mfma_f32_16x16x32_bf16 v[40:43], v[160:163], v[192:195], v[40:43]
	v_mfma_f32_16x16x32_bf16 v[28:31], v[152:155], v[200:203], v[28:31]
	v_mfma_f32_16x16x32_bf16 v[24:27], v[160:163], v[200:203], v[24:27]
	v_mfma_f32_16x16x32_bf16 v[12:15], v[152:155], v[208:211], v[12:15]
	v_mfma_f32_16x16x32_bf16 v[8:11], v[160:163], v[208:211], v[8:11]
	v_mfma_f32_16x16x32_bf16 v[52:55], v[164:167], v[180:183], v[52:55]
	v_mfma_f32_16x16x32_bf16 v[48:51], v[172:175], v[180:183], v[48:51]
	v_mfma_f32_16x16x32_bf16 v[36:39], v[164:167], v[188:191], v[36:39]
	v_mfma_f32_16x16x32_bf16 v[32:35], v[172:175], v[188:191], v[32:35]
	v_mfma_f32_16x16x32_bf16 v[20:23], v[164:167], v[196:199], v[20:23]
	v_mfma_f32_16x16x32_bf16 v[16:19], v[172:175], v[196:199], v[16:19]
	v_mfma_f32_16x16x32_bf16 v[4:7], v[164:167], v[204:207], v[4:7]
	v_mfma_f32_16x16x32_bf16 v[0:3], v[172:175], v[204:207], v[0:3]
	v_mfma_f32_16x16x32_bf16 v[52:55], v[168:171], v[184:187], v[52:55]
	v_mfma_f32_16x16x32_bf16 v[48:51], v[176:179], v[184:187], v[48:51]
	v_mfma_f32_16x16x32_bf16 v[36:39], v[168:171], v[192:195], v[36:39]
	v_mfma_f32_16x16x32_bf16 v[32:35], v[176:179], v[192:195], v[32:35]
	v_mfma_f32_16x16x32_bf16 v[20:23], v[168:171], v[200:203], v[20:23]
	v_mfma_f32_16x16x32_bf16 v[16:19], v[176:179], v[200:203], v[16:19]
	v_mfma_f32_16x16x32_bf16 v[4:7], v[168:171], v[208:211], v[4:7]
	v_mfma_f32_16x16x32_bf16 v[0:3], v[176:179], v[208:211], v[0:3]
	s_setprio 0
	s_barrier
	s_add_i32 s35, s35, 2
	s_add_u32 s16, s16, 0x100
	s_addc_u32 s17, s17, 0
	s_cmp_gt_u32 s35, 29
	s_cbranch_scc0 .LBB0_946
	s_cmpk_lt_u32 s80, 0x100
	s_cbranch_scc0 .LBB0_949
	s_barrier

.LBB0_1693:
	ds_read_b128 v[140:143], v149
	ds_read_b128 v[152:155], v149 offset:1024
	ds_read_b128 v[156:159], v149 offset:2048
	ds_read_b128 v[160:163], v149 offset:3072
	ds_read_b128 v[164:167], v150
	ds_read_b128 v[168:171], v150 offset:1024
	ds_read_b128 v[172:175], v150 offset:2048
	ds_read_b128 v[176:179], v150 offset:3072
	ds_read_b128 v[180:183], v151
	ds_read_b128 v[184:187], v151 offset:1024
	ds_read_b128 v[188:191], v151 offset:2048
	ds_read_b128 v[192:195], v151 offset:3072
	ds_read_b128 v[196:199], v151 offset:4096
	ds_read_b128 v[200:203], v151 offset:5120
	ds_read_b128 v[204:207], v151 offset:6144
	ds_read_b128 v[208:211], v151 offset:7168
	s_add_u32 s76, s74, 0xfff80080
	s_addc_u32 s77, s75, -1
	s_cmp_eq_u32 s86, 28
	s_cselect_b32 s79, s67, s77
	s_cselect_b32 s78, s73, s76
	s_cselect_b32 s77, s65, s85
	s_cselect_b32 s76, s83, s84
	v_lshl_add_u64 v[212:213], s[74:75], 0, v[132:133]
	s_add_i32 m0, s6, 0xc000
	s_nop 0
	global_load_lds_dwordx4 v[212:213], off
	v_lshl_add_u64 v[212:213], s[74:75], 0, v[134:135]
	s_add_i32 m0, s6, 0xe000
	s_nop 0
	global_load_lds_dwordx4 v[212:213], off
	s_waitcnt vmcnt(8)
	s_waitcnt lgkmcnt(0)
	s_barrier
	s_setprio 1
	s_waitcnt lgkmcnt(0)
	v_mfma_f32_16x16x32_bf16 v[124:127], v[140:143], v[180:183], v[124:127]
	v_mfma_f32_16x16x32_bf16 v[120:123], v[156:159], v[180:183], v[120:123]
	v_mfma_f32_16x16x32_bf16 v[108:111], v[140:143], v[188:191], v[108:111]
	v_mfma_f32_16x16x32_bf16 v[104:107], v[156:159], v[188:191], v[104:107]
	v_mfma_f32_16x16x32_bf16 v[92:95], v[140:143], v[196:199], v[92:95]
	v_mfma_f32_16x16x32_bf16 v[88:91], v[156:159], v[196:199], v[88:91]
	v_mfma_f32_16x16x32_bf16 v[76:79], v[140:143], v[204:207], v[76:79]
	v_mfma_f32_16x16x32_bf16 v[72:75], v[156:159], v[204:207], v[72:75]
	v_mfma_f32_16x16x32_bf16 v[124:127], v[152:155], v[184:187], v[124:127]
	v_mfma_f32_16x16x32_bf16 v[120:123], v[160:163], v[184:187], v[120:123]
	v_mfma_f32_16x16x32_bf16 v[108:111], v[152:155], v[192:195], v[108:111]
	v_mfma_f32_16x16x32_bf16 v[104:107], v[160:163], v[192:195], v[104:107]
	v_mfma_f32_16x16x32_bf16 v[92:95], v[152:155], v[200:203], v[92:95]
	v_mfma_f32_16x16x32_bf16 v[88:91], v[160:163], v[200:203], v[88:91]
	v_mfma_f32_16x16x32_bf16 v[76:79], v[152:155], v[208:211], v[76:79]
	v_mfma_f32_16x16x32_bf16 v[72:75], v[160:163], v[208:211], v[72:75]
	v_mfma_f32_16x16x32_bf16 v[116:119], v[164:167], v[180:183], v[116:119]
	v_mfma_f32_16x16x32_bf16 v[112:115], v[172:175], v[180:183], v[112:115]
	v_mfma_f32_16x16x32_bf16 v[100:103], v[164:167], v[188:191], v[100:103]
	v_mfma_f32_16x16x32_bf16 v[96:99], v[172:175], v[188:191], v[96:99]
	v_mfma_f32_16x16x32_bf16 v[84:87], v[164:167], v[196:199], v[84:87]
	v_mfma_f32_16x16x32_bf16 v[80:83], v[172:175], v[196:199], v[80:83]
	v_mfma_f32_16x16x32_bf16 v[68:71], v[164:167], v[204:207], v[68:71]
	v_mfma_f32_16x16x32_bf16 v[64:67], v[172:175], v[204:207], v[64:67]
	v_mfma_f32_16x16x32_bf16 v[116:119], v[168:171], v[184:187], v[116:119]
	v_mfma_f32_16x16x32_bf16 v[112:115], v[176:179], v[184:187], v[112:115]
	v_mfma_f32_16x16x32_bf16 v[100:103], v[168:171], v[192:195], v[100:103]
	v_mfma_f32_16x16x32_bf16 v[96:99], v[176:179], v[192:195], v[96:99]
	v_mfma_f32_16x16x32_bf16 v[84:87], v[168:171], v[200:203], v[84:87]
	v_mfma_f32_16x16x32_bf16 v[80:83], v[176:179], v[200:203], v[80:83]
	v_mfma_f32_16x16x32_bf16 v[68:71], v[168:171], v[208:211], v[68:71]
	v_mfma_f32_16x16x32_bf16 v[64:67], v[176:179], v[208:211], v[64:67]
	s_setprio 0
	s_barrier
	ds_read_b128 v[180:183], v151 offset:16384
	ds_read_b128 v[184:187], v151 offset:17408
	ds_read_b128 v[188:191], v151 offset:18432
	ds_read_b128 v[192:195], v151 offset:19456
	ds_read_b128 v[196:199], v151 offset:20480
	ds_read_b128 v[200:203], v151 offset:21504
	ds_read_b128 v[204:207], v151 offset:22528
	ds_read_b128 v[208:211], v151 offset:23552
	s_add_i32 s87, s57, s94
	v_lshl_add_u64 v[212:213], s[76:77], 0, v[128:129]
	s_mov_b32 m0, s87
	s_nop 0
	global_load_lds_dwordx4 v[212:213], off
	s_add_i32 m0, s87, 0x2000
	s_add_u32 s88, s76, 0x80000
	v_lshl_add_u64 v[214:215], s[76:77], 0, v[130:131]
	s_addc_u32 s89, s77, 0
	s_add_i32 s87, s81, s94
	global_load_lds_dwordx4 v[214:215], off
	v_lshl_add_u64 v[216:217], s[88:89], 0, v[128:129]
	s_mov_b32 m0, s87
	v_lshl_add_u64 v[218:219], s[78:79], 0, v[130:131]
	global_load_lds_dwordx4 v[216:217], off
	v_lshl_add_u64 v[216:217], s[88:89], 0, v[130:131]
	s_add_i32 m0, s87, 0x2000
	s_nop 0
	global_load_lds_dwordx4 v[216:217], off
	v_lshl_add_u64 v[216:217], s[78:79], 0, v[128:129]
	s_mov_b32 m0, s6
	s_nop 0
	global_load_lds_dwordx4 v[216:217], off
	s_mov_b32 m0, s7
	s_nop 0
	global_load_lds_dwordx4 v[218:219], off
	s_waitcnt vmcnt(8)
	s_waitcnt lgkmcnt(0)
	s_barrier
	s_setprio 1
	s_waitcnt lgkmcnt(0)
	v_mfma_f32_16x16x32_bf16 v[60:63], v[140:143], v[180:183], v[60:63]
	v_mfma_f32_16x16x32_bf16 v[56:59], v[156:159], v[180:183], v[56:59]
	v_mfma_f32_16x16x32_bf16 v[44:47], v[140:143], v[188:191], v[44:47]
	v_mfma_f32_16x16x32_bf16 v[40:43], v[156:159], v[188:191], v[40:43]
	v_mfma_f32_16x16x32_bf16 v[28:31], v[140:143], v[196:199], v[28:31]
	v_mfma_f32_16x16x32_bf16 v[24:27], v[156:159], v[196:199], v[24:27]
	v_mfma_f32_16x16x32_bf16 v[12:15], v[140:143], v[204:207], v[12:15]
	v_mfma_f32_16x16x32_bf16 v[8:11], v[156:159], v[204:207], v[8:11]
	v_mfma_f32_16x16x32_bf16 v[60:63], v[152:155], v[184:187], v[60:63]
	v_mfma_f32_16x16x32_bf16 v[56:59], v[160:163], v[184:187], v[56:59]
	v_mfma_f32_16x16x32_bf16 v[44:47], v[152:155], v[192:195], v[44:47]
	v_mfma_f32_16x16x32_bf16 v[40:43], v[160:163], v[192:195], v[40:43]
	v_mfma_f32_16x16x32_bf16 v[28:31], v[152:155], v[200:203], v[28:31]
	v_mfma_f32_16x16x32_bf16 v[24:27], v[160:163], v[200:203], v[24:27]
	v_mfma_f32_16x16x32_bf16 v[12:15], v[152:155], v[208:211], v[12:15]
	v_mfma_f32_16x16x32_bf16 v[8:11], v[160:163], v[208:211], v[8:11]
	v_mfma_f32_16x16x32_bf16 v[52:55], v[164:167], v[180:183], v[52:55]
	v_mfma_f32_16x16x32_bf16 v[48:51], v[172:175], v[180:183], v[48:51]
	v_mfma_f32_16x16x32_bf16 v[36:39], v[164:167], v[188:191], v[36:39]
	v_mfma_f32_16x16x32_bf16 v[32:35], v[172:175], v[188:191], v[32:35]
	v_mfma_f32_16x16x32_bf16 v[20:23], v[164:167], v[196:199], v[20:23]
	v_mfma_f32_16x16x32_bf16 v[16:19], v[172:175], v[196:199], v[16:19]
	v_mfma_f32_16x16x32_bf16 v[4:7], v[164:167], v[204:207], v[4:7]
	v_mfma_f32_16x16x32_bf16 v[0:3], v[172:175], v[204:207], v[0:3]
	v_mfma_f32_16x16x32_bf16 v[52:55], v[168:171], v[184:187], v[52:55]
	v_mfma_f32_16x16x32_bf16 v[48:51], v[176:179], v[184:187], v[48:51]
	v_mfma_f32_16x16x32_bf16 v[36:39], v[168:171], v[192:195], v[36:39]
	v_mfma_f32_16x16x32_bf16 v[32:35], v[176:179], v[192:195], v[32:35]
	v_mfma_f32_16x16x32_bf16 v[20:23], v[168:171], v[200:203], v[20:23]
	v_mfma_f32_16x16x32_bf16 v[16:19], v[176:179], v[200:203], v[16:19]
	v_mfma_f32_16x16x32_bf16 v[4:7], v[168:171], v[208:211], v[4:7]
	v_mfma_f32_16x16x32_bf16 v[0:3], v[176:179], v[208:211], v[0:3]
	s_setprio 0
	s_barrier
	s_add_i32 s87, 0, 0x18000
	s_add_i32 s88, 0, 0x1c000
	v_add_u32_e32 v160, s87, v145
	ds_read_b128 v[140:143], v160
	ds_read_b128 v[152:155], v160 offset:1024
	ds_read_b128 v[156:159], v160 offset:2048
	ds_read_b128 v[160:163], v160 offset:3072
	v_add_u32_e32 v176, s88, v145
	ds_read_b128 v[164:167], v176
	ds_read_b128 v[168:171], v176 offset:1024
	ds_read_b128 v[172:175], v176 offset:2048
	ds_read_b128 v[176:179], v176 offset:3072
	ds_read_b128 v[180:183], v151 offset:32768
	ds_read_b128 v[184:187], v151 offset:33792
	ds_read_b128 v[188:191], v151 offset:34816
	ds_read_b128 v[192:195], v151 offset:35840
	ds_read_b128 v[196:199], v151 offset:36864
	ds_read_b128 v[200:203], v151 offset:37888
	ds_read_b128 v[204:207], v151 offset:38912
	ds_read_b128 v[208:211], v151 offset:39936
	s_add_u32 s78, s78, 0x80000
	s_addc_u32 s79, s79, 0
	s_mov_b32 m0, s29
	v_lshl_add_u64 v[220:221], s[78:79], 0, v[128:129]
	global_load_lds_dwordx4 v[220:221], off
	v_lshl_add_u64 v[220:221], s[78:79], 0, v[130:131]
	s_mov_b32 m0, s30
	s_nop 0
	global_load_lds_dwordx4 v[220:221], off
	s_waitcnt vmcnt(8)
	s_waitcnt lgkmcnt(0)
	s_barrier
	s_setprio 1
	s_waitcnt lgkmcnt(0)
	v_mfma_f32_16x16x32_bf16 v[124:127], v[140:143], v[180:183], v[124:127]
	v_mfma_f32_16x16x32_bf16 v[120:123], v[156:159], v[180:183], v[120:123]
	v_mfma_f32_16x16x32_bf16 v[108:111], v[140:143], v[188:191], v[108:111]
	v_mfma_f32_16x16x32_bf16 v[104:107], v[156:159], v[188:191], v[104:107]
	v_mfma_f32_16x16x32_bf16 v[92:95], v[140:143], v[196:199], v[92:95]
	v_mfma_f32_16x16x32_bf16 v[88:91], v[156:159], v[196:199], v[88:91]
	v_mfma_f32_16x16x32_bf16 v[76:79], v[140:143], v[204:207], v[76:79]
	v_mfma_f32_16x16x32_bf16 v[72:75], v[156:159], v[204:207], v[72:75]
	v_mfma_f32_16x16x32_bf16 v[124:127], v[152:155], v[184:187], v[124:127]
	v_mfma_f32_16x16x32_bf16 v[120:123], v[160:163], v[184:187], v[120:123]
	v_mfma_f32_16x16x32_bf16 v[108:111], v[152:155], v[192:195], v[108:111]
	v_mfma_f32_16x16x32_bf16 v[104:107], v[160:163], v[192:195], v[104:107]
	v_mfma_f32_16x16x32_bf16 v[92:95], v[152:155], v[200:203], v[92:95]
	v_mfma_f32_16x16x32_bf16 v[88:91], v[160:163], v[200:203], v[88:91]
	v_mfma_f32_16x16x32_bf16 v[76:79], v[152:155], v[208:211], v[76:79]
	v_mfma_f32_16x16x32_bf16 v[72:75], v[160:163], v[208:211], v[72:75]
	v_mfma_f32_16x16x32_bf16 v[116:119], v[164:167], v[180:183], v[116:119]
	v_mfma_f32_16x16x32_bf16 v[112:115], v[172:175], v[180:183], v[112:115]
	v_mfma_f32_16x16x32_bf16 v[100:103], v[164:167], v[188:191], v[100:103]
	v_mfma_f32_16x16x32_bf16 v[96:99], v[172:175], v[188:191], v[96:99]
	v_mfma_f32_16x16x32_bf16 v[84:87], v[164:167], v[196:199], v[84:87]
	v_mfma_f32_16x16x32_bf16 v[80:83], v[172:175], v[196:199], v[80:83]
	v_mfma_f32_16x16x32_bf16 v[68:71], v[164:167], v[204:207], v[68:71]
	v_mfma_f32_16x16x32_bf16 v[64:67], v[172:175], v[204:207], v[64:67]
	v_mfma_f32_16x16x32_bf16 v[116:119], v[168:171], v[184:187], v[116:119]
	v_mfma_f32_16x16x32_bf16 v[112:115], v[176:179], v[184:187], v[112:115]
	v_mfma_f32_16x16x32_bf16 v[100:103], v[168:171], v[192:195], v[100:103]
	v_mfma_f32_16x16x32_bf16 v[96:99], v[176:179], v[192:195], v[96:99]
	v_mfma_f32_16x16x32_bf16 v[84:87], v[168:171], v[200:203], v[84:87]
	v_mfma_f32_16x16x32_bf16 v[80:83], v[176:179], v[200:203], v[80:83]
	v_mfma_f32_16x16x32_bf16 v[68:71], v[168:171], v[208:211], v[68:71]
	v_mfma_f32_16x16x32_bf16 v[64:67], v[176:179], v[208:211], v[64:67]
	s_setprio 0
	s_barrier
	ds_read_b128 v[180:183], v151 offset:49152
	ds_read_b128 v[184:187], v151 offset:50176
	ds_read_b128 v[188:191], v151 offset:51200
	ds_read_b128 v[192:195], v151 offset:52224
	ds_read_b128 v[196:199], v151 offset:53248
	ds_read_b128 v[200:203], v151 offset:54272
	ds_read_b128 v[204:207], v151 offset:55296
	ds_read_b128 v[208:211], v151 offset:56320
	s_add_i32 s78, s87, s94
	v_lshl_add_u64 v[212:213], v[212:213], 0, s[58:59]
	s_mov_b32 m0, s78
	s_nop 0
	global_load_lds_dwordx4 v[212:213], off
	s_add_i32 m0, s78, 0x2000
	s_add_u32 s76, s76, 0x80080
	v_lshl_add_u64 v[212:213], v[214:215], 0, s[58:59]
	s_addc_u32 s77, s77, 0
	s_add_i32 s78, s88, s94
	global_load_lds_dwordx4 v[212:213], off
	v_lshl_add_u64 v[212:213], s[76:77], 0, v[128:129]
	s_mov_b32 m0, s78
	s_nop 0
	global_load_lds_dwordx4 v[212:213], off
	v_lshl_add_u64 v[212:213], s[76:77], 0, v[130:131]
	s_add_i32 m0, s78, 0x2000
	s_nop 0
	global_load_lds_dwordx4 v[212:213], off
	v_lshl_add_u64 v[212:213], v[216:217], 0, s[58:59]
	s_mov_b32 m0, s34
	s_nop 0
	global_load_lds_dwordx4 v[212:213], off
	v_lshl_add_u64 v[212:213], v[218:219], 0, s[58:59]
	s_mov_b32 m0, s35
	s_nop 0
	global_load_lds_dwordx4 v[212:213], off
	s_waitcnt vmcnt(8)
	s_waitcnt lgkmcnt(0)
	s_barrier
	s_setprio 1
	s_waitcnt lgkmcnt(0)
	v_mfma_f32_16x16x32_bf16 v[60:63], v[140:143], v[180:183], v[60:63]
	v_mfma_f32_16x16x32_bf16 v[56:59], v[156:159], v[180:183], v[56:59]
	v_mfma_f32_16x16x32_bf16 v[44:47], v[140:143], v[188:191], v[44:47]
	v_mfma_f32_16x16x32_bf16 v[40:43], v[156:159], v[188:191], v[40:43]
	v_mfma_f32_16x16x32_bf16 v[28:31], v[140:143], v[196:199], v[28:31]
	v_mfma_f32_16x16x32_bf16 v[24:27], v[156:159], v[196:199], v[24:27]
	v_mfma_f32_16x16x32_bf16 v[12:15], v[140:143], v[204:207], v[12:15]
	v_mfma_f32_16x16x32_bf16 v[8:11], v[156:159], v[204:207], v[8:11]
	v_mfma_f32_16x16x32_bf16 v[60:63], v[152:155], v[184:187], v[60:63]
	v_mfma_f32_16x16x32_bf16 v[56:59], v[160:163], v[184:187], v[56:59]
	v_mfma_f32_16x16x32_bf16 v[44:47], v[152:155], v[192:195], v[44:47]
	v_mfma_f32_16x16x32_bf16 v[40:43], v[160:163], v[192:195], v[40:43]
	v_mfma_f32_16x16x32_bf16 v[28:31], v[152:155], v[200:203], v[28:31]
	v_mfma_f32_16x16x32_bf16 v[24:27], v[160:163], v[200:203], v[24:27]
	v_mfma_f32_16x16x32_bf16 v[12:15], v[152:155], v[208:211], v[12:15]
	v_mfma_f32_16x16x32_bf16 v[8:11], v[160:163], v[208:211], v[8:11]
	v_mfma_f32_16x16x32_bf16 v[52:55], v[164:167], v[180:183], v[52:55]
	v_mfma_f32_16x16x32_bf16 v[48:51], v[172:175], v[180:183], v[48:51]
	v_mfma_f32_16x16x32_bf16 v[36:39], v[164:167], v[188:191], v[36:39]
	v_mfma_f32_16x16x32_bf16 v[32:35], v[172:175], v[188:191], v[32:35]
	v_mfma_f32_16x16x32_bf16 v[20:23], v[164:167], v[196:199], v[20:23]
	v_mfma_f32_16x16x32_bf16 v[16:19], v[172:175], v[196:199], v[16:19]
	v_mfma_f32_16x16x32_bf16 v[4:7], v[164:167], v[204:207], v[4:7]
	v_mfma_f32_16x16x32_bf16 v[0:3], v[172:175], v[204:207], v[0:3]
	v_mfma_f32_16x16x32_bf16 v[52:55], v[168:171], v[184:187], v[52:55]
	v_mfma_f32_16x16x32_bf16 v[48:51], v[176:179], v[184:187], v[48:51]
	v_mfma_f32_16x16x32_bf16 v[36:39], v[168:171], v[192:195], v[36:39]
	v_mfma_f32_16x16x32_bf16 v[32:35], v[176:179], v[192:195], v[32:35]
	v_mfma_f32_16x16x32_bf16 v[20:23], v[168:171], v[200:203], v[20:23]
	v_mfma_f32_16x16x32_bf16 v[16:19], v[176:179], v[200:203], v[16:19]
	v_mfma_f32_16x16x32_bf16 v[4:7], v[168:171], v[208:211], v[4:7]
	v_mfma_f32_16x16x32_bf16 v[0:3], v[176:179], v[208:211], v[0:3]
	s_setprio 0
	s_barrier
	s_add_i32 s86, s86, 2
	s_add_u32 s74, s74, 0x100
	s_addc_u32 s75, s75, 0
	s_add_u32 s84, s84, 0x100
	s_addc_u32 s85, s85, 0
	s_cmp_gt_u32 s86, 29
	s_cbranch_scc0 .LBB0_1693
	s_and_b64 vcc, exec, s[60:61]
	s_cbranch_vccz .LBB0_1696
	s_barrier

.LBB0_1785:
	ds_read_b128 v[146:149], v155
	ds_read_b128 v[160:163], v155 offset:1024
	ds_read_b128 v[164:167], v155 offset:2048
	ds_read_b128 v[168:171], v155 offset:3072
	ds_read_b128 v[172:175], v156
	ds_read_b128 v[176:179], v156 offset:1024
	ds_read_b128 v[180:183], v156 offset:2048
	ds_read_b128 v[184:187], v156 offset:3072
	ds_read_b128 v[188:191], v157
	ds_read_b128 v[192:195], v157 offset:1024
	ds_read_b128 v[196:199], v157 offset:2048
	ds_read_b128 v[200:203], v157 offset:3072
	ds_read_b128 v[204:207], v157 offset:4096
	ds_read_b128 v[208:211], v157 offset:5120
	ds_read_b128 v[212:215], v157 offset:6144
	ds_read_b128 v[216:219], v157 offset:7168
	s_add_u32 s60, s72, 0xfff80080
	s_addc_u32 s61, s73, -1
	s_cmp_eq_u32 s78, 28
	s_cselect_b32 s77, s56, s61
	s_cselect_b32 s76, s57, s60
	s_cselect_b32 s75, s23, s71
	s_cselect_b32 s74, s63, s69
	v_lshl_add_u64 v[220:221], s[72:73], 0, v[138:139]
	s_add_i32 m0, s6, 0xc000
	s_nop 0
	global_load_lds_dwordx4 v[220:221], off
	v_lshl_add_u64 v[220:221], s[72:73], 0, v[140:141]
	s_add_i32 m0, s6, 0xe000
	s_nop 0
	global_load_lds_dwordx4 v[220:221], off
	s_waitcnt vmcnt(8)
	s_waitcnt lgkmcnt(0)
	s_barrier
	s_setprio 1
	s_waitcnt lgkmcnt(0)
	v_mfma_f32_16x16x32_bf16 v[124:127], v[146:149], v[188:191], v[124:127]
	v_mfma_f32_16x16x32_bf16 v[120:123], v[164:167], v[188:191], v[120:123]
	v_mfma_f32_16x16x32_bf16 v[108:111], v[146:149], v[196:199], v[108:111]
	v_mfma_f32_16x16x32_bf16 v[104:107], v[164:167], v[196:199], v[104:107]
	v_mfma_f32_16x16x32_bf16 v[92:95], v[146:149], v[204:207], v[92:95]
	v_mfma_f32_16x16x32_bf16 v[88:91], v[164:167], v[204:207], v[88:91]
	v_mfma_f32_16x16x32_bf16 v[76:79], v[146:149], v[212:215], v[76:79]
	v_mfma_f32_16x16x32_bf16 v[72:75], v[164:167], v[212:215], v[72:75]
	v_mfma_f32_16x16x32_bf16 v[124:127], v[160:163], v[192:195], v[124:127]
	v_mfma_f32_16x16x32_bf16 v[120:123], v[168:171], v[192:195], v[120:123]
	v_mfma_f32_16x16x32_bf16 v[108:111], v[160:163], v[200:203], v[108:111]
	v_mfma_f32_16x16x32_bf16 v[104:107], v[168:171], v[200:203], v[104:107]
	v_mfma_f32_16x16x32_bf16 v[92:95], v[160:163], v[208:211], v[92:95]
	v_mfma_f32_16x16x32_bf16 v[88:91], v[168:171], v[208:211], v[88:91]
	v_mfma_f32_16x16x32_bf16 v[76:79], v[160:163], v[216:219], v[76:79]
	v_mfma_f32_16x16x32_bf16 v[72:75], v[168:171], v[216:219], v[72:75]
	v_mfma_f32_16x16x32_bf16 v[116:119], v[172:175], v[188:191], v[116:119]
	v_mfma_f32_16x16x32_bf16 v[112:115], v[180:183], v[188:191], v[112:115]
	v_mfma_f32_16x16x32_bf16 v[100:103], v[172:175], v[196:199], v[100:103]
	v_mfma_f32_16x16x32_bf16 v[96:99], v[180:183], v[196:199], v[96:99]
	v_mfma_f32_16x16x32_bf16 v[84:87], v[172:175], v[204:207], v[84:87]
	v_mfma_f32_16x16x32_bf16 v[80:83], v[180:183], v[204:207], v[80:83]
	v_mfma_f32_16x16x32_bf16 v[68:71], v[172:175], v[212:215], v[68:71]
	v_mfma_f32_16x16x32_bf16 v[64:67], v[180:183], v[212:215], v[64:67]
	v_mfma_f32_16x16x32_bf16 v[116:119], v[176:179], v[192:195], v[116:119]
	v_mfma_f32_16x16x32_bf16 v[112:115], v[184:187], v[192:195], v[112:115]
	v_mfma_f32_16x16x32_bf16 v[100:103], v[176:179], v[200:203], v[100:103]
	v_mfma_f32_16x16x32_bf16 v[96:99], v[184:187], v[200:203], v[96:99]
	v_mfma_f32_16x16x32_bf16 v[84:87], v[176:179], v[208:211], v[84:87]
	v_mfma_f32_16x16x32_bf16 v[80:83], v[184:187], v[208:211], v[80:83]
	v_mfma_f32_16x16x32_bf16 v[68:71], v[176:179], v[216:219], v[68:71]
	v_mfma_f32_16x16x32_bf16 v[64:67], v[184:187], v[216:219], v[64:67]
	s_setprio 0
	s_barrier
	ds_read_b128 v[188:191], v157 offset:16384
	ds_read_b128 v[192:195], v157 offset:17408
	ds_read_b128 v[196:199], v157 offset:18432
	ds_read_b128 v[200:203], v157 offset:19456
	ds_read_b128 v[204:207], v157 offset:20480
	ds_read_b128 v[208:211], v157 offset:21504
	ds_read_b128 v[212:215], v157 offset:22528
	ds_read_b128 v[216:219], v157 offset:23552
	s_add_i32 s60, s35, s94
	v_lshl_add_u64 v[220:221], s[74:75], 0, v[130:131]
	s_mov_b32 m0, s60
	s_nop 0
	global_load_lds_dwordx4 v[220:221], off
	s_add_i32 m0, s60, 0x2000
	s_add_u32 s80, s74, 0x80000
	v_lshl_add_u64 v[222:223], s[74:75], 0, v[134:135]
	s_addc_u32 s81, s75, 0
	s_add_i32 s60, s46, s94
	global_load_lds_dwordx4 v[222:223], off
	v_lshl_add_u64 v[224:225], s[80:81], 0, v[130:131]
	s_mov_b32 m0, s60
	v_lshl_add_u64 v[226:227], s[76:77], 0, v[132:133]
	global_load_lds_dwordx4 v[224:225], off
	v_lshl_add_u64 v[224:225], s[80:81], 0, v[134:135]
	s_add_i32 m0, s60, 0x2000
	s_nop 0
	global_load_lds_dwordx4 v[224:225], off
	v_lshl_add_u64 v[224:225], s[76:77], 0, v[128:129]
	s_mov_b32 m0, s6
	s_nop 0
	global_load_lds_dwordx4 v[224:225], off
	s_mov_b32 m0, s7
	s_nop 0
	global_load_lds_dwordx4 v[226:227], off
	s_waitcnt vmcnt(8)
	s_waitcnt lgkmcnt(0)
	s_barrier
	s_setprio 1
	s_waitcnt lgkmcnt(0)
	v_mfma_f32_16x16x32_bf16 v[60:63], v[146:149], v[188:191], v[60:63]
	v_mfma_f32_16x16x32_bf16 v[56:59], v[164:167], v[188:191], v[56:59]
	v_mfma_f32_16x16x32_bf16 v[44:47], v[146:149], v[196:199], v[44:47]
	v_mfma_f32_16x16x32_bf16 v[40:43], v[164:167], v[196:199], v[40:43]
	v_mfma_f32_16x16x32_bf16 v[28:31], v[146:149], v[204:207], v[28:31]
	v_mfma_f32_16x16x32_bf16 v[24:27], v[164:167], v[204:207], v[24:27]
	v_mfma_f32_16x16x32_bf16 v[12:15], v[146:149], v[212:215], v[12:15]
	v_mfma_f32_16x16x32_bf16 v[8:11], v[164:167], v[212:215], v[8:11]
	v_mfma_f32_16x16x32_bf16 v[60:63], v[160:163], v[192:195], v[60:63]
	v_mfma_f32_16x16x32_bf16 v[56:59], v[168:171], v[192:195], v[56:59]
	v_mfma_f32_16x16x32_bf16 v[44:47], v[160:163], v[200:203], v[44:47]
	v_mfma_f32_16x16x32_bf16 v[40:43], v[168:171], v[200:203], v[40:43]
	v_mfma_f32_16x16x32_bf16 v[28:31], v[160:163], v[208:211], v[28:31]
	v_mfma_f32_16x16x32_bf16 v[24:27], v[168:171], v[208:211], v[24:27]
	v_mfma_f32_16x16x32_bf16 v[12:15], v[160:163], v[216:219], v[12:15]
	v_mfma_f32_16x16x32_bf16 v[8:11], v[168:171], v[216:219], v[8:11]
	v_mfma_f32_16x16x32_bf16 v[52:55], v[172:175], v[188:191], v[52:55]
	v_mfma_f32_16x16x32_bf16 v[48:51], v[180:183], v[188:191], v[48:51]
	v_mfma_f32_16x16x32_bf16 v[36:39], v[172:175], v[196:199], v[36:39]
	v_mfma_f32_16x16x32_bf16 v[32:35], v[180:183], v[196:199], v[32:35]
	v_mfma_f32_16x16x32_bf16 v[20:23], v[172:175], v[204:207], v[20:23]
	v_mfma_f32_16x16x32_bf16 v[16:19], v[180:183], v[204:207], v[16:19]
	v_mfma_f32_16x16x32_bf16 v[4:7], v[172:175], v[212:215], v[4:7]
	v_mfma_f32_16x16x32_bf16 v[0:3], v[180:183], v[212:215], v[0:3]
	v_mfma_f32_16x16x32_bf16 v[52:55], v[176:179], v[192:195], v[52:55]
	v_mfma_f32_16x16x32_bf16 v[48:51], v[184:187], v[192:195], v[48:51]
	v_mfma_f32_16x16x32_bf16 v[36:39], v[176:179], v[200:203], v[36:39]
	v_mfma_f32_16x16x32_bf16 v[32:35], v[184:187], v[200:203], v[32:35]
	v_mfma_f32_16x16x32_bf16 v[20:23], v[176:179], v[208:211], v[20:23]
	v_mfma_f32_16x16x32_bf16 v[16:19], v[184:187], v[208:211], v[16:19]
	v_mfma_f32_16x16x32_bf16 v[4:7], v[176:179], v[216:219], v[4:7]
	v_mfma_f32_16x16x32_bf16 v[0:3], v[184:187], v[216:219], v[0:3]
	s_setprio 0
	s_barrier
	s_add_i32 s60, 0, 0x18000
	v_add_u32_e32 v159, s60, v151
	ds_read_b128 v[146:149], v159
	ds_read_b128 v[160:163], v159 offset:1024
	ds_read_b128 v[164:167], v159 offset:2048
	ds_read_b128 v[168:171], v159 offset:3072
	s_add_i32 s61, 0, 0x1c000
	v_add_u32_e32 v159, s61, v151
	ds_read_b128 v[172:175], v159
	ds_read_b128 v[176:179], v159 offset:1024
	ds_read_b128 v[180:183], v159 offset:2048
	ds_read_b128 v[184:187], v159 offset:3072
	ds_read_b128 v[188:191], v157 offset:32768
	ds_read_b128 v[192:195], v157 offset:33792
	ds_read_b128 v[196:199], v157 offset:34816
	ds_read_b128 v[200:203], v157 offset:35840
	ds_read_b128 v[204:207], v157 offset:36864
	ds_read_b128 v[208:211], v157 offset:37888
	ds_read_b128 v[212:215], v157 offset:38912
	ds_read_b128 v[216:219], v157 offset:39936
	s_add_u32 s76, s76, 0x80000
	s_addc_u32 s77, s77, 0
	s_mov_b32 m0, s12
	v_lshl_add_u64 v[228:229], s[76:77], 0, v[128:129]
	global_load_lds_dwordx4 v[228:229], off
	v_lshl_add_u64 v[228:229], s[76:77], 0, v[132:133]
	s_mov_b32 m0, s13
	s_nop 0
	global_load_lds_dwordx4 v[228:229], off
	s_waitcnt vmcnt(8)
	s_waitcnt lgkmcnt(0)
	s_barrier
	s_setprio 1
	s_waitcnt lgkmcnt(0)
	v_mfma_f32_16x16x32_bf16 v[124:127], v[146:149], v[188:191], v[124:127]
	v_mfma_f32_16x16x32_bf16 v[120:123], v[164:167], v[188:191], v[120:123]
	v_mfma_f32_16x16x32_bf16 v[108:111], v[146:149], v[196:199], v[108:111]
	v_mfma_f32_16x16x32_bf16 v[104:107], v[164:167], v[196:199], v[104:107]
	v_mfma_f32_16x16x32_bf16 v[92:95], v[146:149], v[204:207], v[92:95]
	v_mfma_f32_16x16x32_bf16 v[88:91], v[164:167], v[204:207], v[88:91]
	v_mfma_f32_16x16x32_bf16 v[76:79], v[146:149], v[212:215], v[76:79]
	v_mfma_f32_16x16x32_bf16 v[72:75], v[164:167], v[212:215], v[72:75]
	v_mfma_f32_16x16x32_bf16 v[124:127], v[160:163], v[192:195], v[124:127]
	v_mfma_f32_16x16x32_bf16 v[120:123], v[168:171], v[192:195], v[120:123]
	v_mfma_f32_16x16x32_bf16 v[108:111], v[160:163], v[200:203], v[108:111]
	v_mfma_f32_16x16x32_bf16 v[104:107], v[168:171], v[200:203], v[104:107]
	v_mfma_f32_16x16x32_bf16 v[92:95], v[160:163], v[208:211], v[92:95]
	v_mfma_f32_16x16x32_bf16 v[88:91], v[168:171], v[208:211], v[88:91]
	v_mfma_f32_16x16x32_bf16 v[76:79], v[160:163], v[216:219], v[76:79]
	v_mfma_f32_16x16x32_bf16 v[72:75], v[168:171], v[216:219], v[72:75]
	v_mfma_f32_16x16x32_bf16 v[116:119], v[172:175], v[188:191], v[116:119]
	v_mfma_f32_16x16x32_bf16 v[112:115], v[180:183], v[188:191], v[112:115]
	v_mfma_f32_16x16x32_bf16 v[100:103], v[172:175], v[196:199], v[100:103]
	v_mfma_f32_16x16x32_bf16 v[96:99], v[180:183], v[196:199], v[96:99]
	v_mfma_f32_16x16x32_bf16 v[84:87], v[172:175], v[204:207], v[84:87]
	v_mfma_f32_16x16x32_bf16 v[80:83], v[180:183], v[204:207], v[80:83]
	v_mfma_f32_16x16x32_bf16 v[68:71], v[172:175], v[212:215], v[68:71]
	v_mfma_f32_16x16x32_bf16 v[64:67], v[180:183], v[212:215], v[64:67]
	v_mfma_f32_16x16x32_bf16 v[116:119], v[176:179], v[192:195], v[116:119]
	v_mfma_f32_16x16x32_bf16 v[112:115], v[184:187], v[192:195], v[112:115]
	v_mfma_f32_16x16x32_bf16 v[100:103], v[176:179], v[200:203], v[100:103]
	v_mfma_f32_16x16x32_bf16 v[96:99], v[184:187], v[200:203], v[96:99]
	v_mfma_f32_16x16x32_bf16 v[84:87], v[176:179], v[208:211], v[84:87]
	v_mfma_f32_16x16x32_bf16 v[80:83], v[184:187], v[208:211], v[80:83]
	v_mfma_f32_16x16x32_bf16 v[68:71], v[176:179], v[216:219], v[68:71]
	v_mfma_f32_16x16x32_bf16 v[64:67], v[184:187], v[216:219], v[64:67]
	s_setprio 0
	s_barrier
	ds_read_b128 v[188:191], v157 offset:49152
	ds_read_b128 v[192:195], v157 offset:50176
	ds_read_b128 v[196:199], v157 offset:51200
	ds_read_b128 v[200:203], v157 offset:52224
	ds_read_b128 v[204:207], v157 offset:53248
	ds_read_b128 v[208:211], v157 offset:54272
	ds_read_b128 v[212:215], v157 offset:55296
	ds_read_b128 v[216:219], v157 offset:56320
	s_add_i32 s60, s60, s94
	v_lshl_add_u64 v[220:221], v[220:221], 0, s[20:21]
	s_mov_b32 m0, s60
	s_nop 0
	global_load_lds_dwordx4 v[220:221], off
	s_add_i32 m0, s60, 0x2000
	s_add_u32 s74, s74, 0x80080
	v_lshl_add_u64 v[220:221], v[222:223], 0, s[20:21]
	s_addc_u32 s75, s75, 0
	s_add_i32 s60, s61, s94
	global_load_lds_dwordx4 v[220:221], off
	v_lshl_add_u64 v[220:221], s[74:75], 0, v[130:131]
	s_mov_b32 m0, s60
	s_nop 0
	global_load_lds_dwordx4 v[220:221], off
	v_lshl_add_u64 v[220:221], s[74:75], 0, v[134:135]
	s_add_i32 m0, s60, 0x2000
	s_nop 0
	global_load_lds_dwordx4 v[220:221], off
	v_lshl_add_u64 v[220:221], v[224:225], 0, s[20:21]
	s_mov_b32 m0, s30
	s_nop 0
	global_load_lds_dwordx4 v[220:221], off
	v_lshl_add_u64 v[220:221], v[226:227], 0, s[20:21]
	s_mov_b32 m0, s34
	s_nop 0
	global_load_lds_dwordx4 v[220:221], off
	s_waitcnt vmcnt(8)
	s_waitcnt lgkmcnt(0)
	s_barrier
	s_setprio 1
	s_waitcnt lgkmcnt(0)
	v_mfma_f32_16x16x32_bf16 v[60:63], v[146:149], v[188:191], v[60:63]
	v_mfma_f32_16x16x32_bf16 v[56:59], v[164:167], v[188:191], v[56:59]
	v_mfma_f32_16x16x32_bf16 v[44:47], v[146:149], v[196:199], v[44:47]
	v_mfma_f32_16x16x32_bf16 v[40:43], v[164:167], v[196:199], v[40:43]
	v_mfma_f32_16x16x32_bf16 v[28:31], v[146:149], v[204:207], v[28:31]
	v_mfma_f32_16x16x32_bf16 v[24:27], v[164:167], v[204:207], v[24:27]
	v_mfma_f32_16x16x32_bf16 v[12:15], v[146:149], v[212:215], v[12:15]
	v_mfma_f32_16x16x32_bf16 v[8:11], v[164:167], v[212:215], v[8:11]
	v_mfma_f32_16x16x32_bf16 v[60:63], v[160:163], v[192:195], v[60:63]
	v_mfma_f32_16x16x32_bf16 v[56:59], v[168:171], v[192:195], v[56:59]
	v_mfma_f32_16x16x32_bf16 v[44:47], v[160:163], v[200:203], v[44:47]
	v_mfma_f32_16x16x32_bf16 v[40:43], v[168:171], v[200:203], v[40:43]
	v_mfma_f32_16x16x32_bf16 v[28:31], v[160:163], v[208:211], v[28:31]
	v_mfma_f32_16x16x32_bf16 v[24:27], v[168:171], v[208:211], v[24:27]
	v_mfma_f32_16x16x32_bf16 v[12:15], v[160:163], v[216:219], v[12:15]
	v_mfma_f32_16x16x32_bf16 v[8:11], v[168:171], v[216:219], v[8:11]
	v_mfma_f32_16x16x32_bf16 v[52:55], v[172:175], v[188:191], v[52:55]
	v_mfma_f32_16x16x32_bf16 v[48:51], v[180:183], v[188:191], v[48:51]
	v_mfma_f32_16x16x32_bf16 v[36:39], v[172:175], v[196:199], v[36:39]
	v_mfma_f32_16x16x32_bf16 v[32:35], v[180:183], v[196:199], v[32:35]
	v_mfma_f32_16x16x32_bf16 v[20:23], v[172:175], v[204:207], v[20:23]
	v_mfma_f32_16x16x32_bf16 v[16:19], v[180:183], v[204:207], v[16:19]
	v_mfma_f32_16x16x32_bf16 v[4:7], v[172:175], v[212:215], v[4:7]
	v_mfma_f32_16x16x32_bf16 v[0:3], v[180:183], v[212:215], v[0:3]
	v_mfma_f32_16x16x32_bf16 v[52:55], v[176:179], v[192:195], v[52:55]
	v_mfma_f32_16x16x32_bf16 v[48:51], v[184:187], v[192:195], v[48:51]
	v_mfma_f32_16x16x32_bf16 v[36:39], v[176:179], v[200:203], v[36:39]
	v_mfma_f32_16x16x32_bf16 v[32:35], v[184:187], v[200:203], v[32:35]
	v_mfma_f32_16x16x32_bf16 v[20:23], v[176:179], v[208:211], v[20:23]
	v_mfma_f32_16x16x32_bf16 v[16:19], v[184:187], v[208:211], v[16:19]
	v_mfma_f32_16x16x32_bf16 v[4:7], v[176:179], v[216:219], v[4:7]
	v_mfma_f32_16x16x32_bf16 v[0:3], v[184:187], v[216:219], v[0:3]
	s_setprio 0
	s_barrier
	s_add_i32 s78, s78, 2
	s_add_u32 s72, s72, 0x100
	s_addc_u32 s73, s73, 0
	s_add_u32 s69, s69, 0x100
	s_addc_u32 s71, s71, 0
	s_cmp_gt_u32 s78, 29
	s_cbranch_scc0 .LBB0_1785
	s_and_b64 vcc, exec, s[58:59]
	s_cbranch_vccz .LBB0_1788
	s_barrier

.LBB0_1897:
	ds_read_b128 v[140:143], v149
	ds_read_b128 v[152:155], v149 offset:1024
	ds_read_b128 v[156:159], v149 offset:2048
	ds_read_b128 v[160:163], v149 offset:3072
	ds_read_b128 v[164:167], v150
	ds_read_b128 v[168:171], v150 offset:1024
	ds_read_b128 v[172:175], v150 offset:2048
	ds_read_b128 v[176:179], v150 offset:3072
	ds_read_b128 v[180:183], v151
	ds_read_b128 v[184:187], v151 offset:1024
	ds_read_b128 v[188:191], v151 offset:2048
	ds_read_b128 v[192:195], v151 offset:3072
	ds_read_b128 v[196:199], v151 offset:4096
	ds_read_b128 v[200:203], v151 offset:5120
	ds_read_b128 v[204:207], v151 offset:6144
	ds_read_b128 v[208:211], v151 offset:7168
	s_add_u32 s60, s72, 0xffe00080
	s_addc_u32 s61, s73, -1
	s_cmpk_eq_i32 s79, 0x7c
	s_cselect_b32 s77, s56, s61
	s_cselect_b32 s76, s57, s60
	s_cselect_b32 s75, s63, s78
	s_cselect_b32 s74, s65, s71
	v_lshl_add_u64 v[212:213], s[72:73], 0, v[132:133]
	s_add_i32 m0, s6, 0xc000
	s_nop 0
	global_load_lds_dwordx4 v[212:213], off
	v_lshl_add_u64 v[212:213], s[72:73], 0, v[134:135]
	s_add_i32 m0, s6, 0xe000
	s_nop 0
	global_load_lds_dwordx4 v[212:213], off
	s_waitcnt vmcnt(8)
	s_waitcnt lgkmcnt(0)
	s_barrier
	s_setprio 1
	s_waitcnt lgkmcnt(0)
	v_mfma_f32_16x16x32_bf16 v[124:127], v[140:143], v[180:183], v[124:127]
	v_mfma_f32_16x16x32_bf16 v[120:123], v[156:159], v[180:183], v[120:123]
	v_mfma_f32_16x16x32_bf16 v[108:111], v[140:143], v[188:191], v[108:111]
	v_mfma_f32_16x16x32_bf16 v[104:107], v[156:159], v[188:191], v[104:107]
	v_mfma_f32_16x16x32_bf16 v[92:95], v[140:143], v[196:199], v[92:95]
	v_mfma_f32_16x16x32_bf16 v[88:91], v[156:159], v[196:199], v[88:91]
	v_mfma_f32_16x16x32_bf16 v[76:79], v[140:143], v[204:207], v[76:79]
	v_mfma_f32_16x16x32_bf16 v[72:75], v[156:159], v[204:207], v[72:75]
	v_mfma_f32_16x16x32_bf16 v[124:127], v[152:155], v[184:187], v[124:127]
	v_mfma_f32_16x16x32_bf16 v[120:123], v[160:163], v[184:187], v[120:123]
	v_mfma_f32_16x16x32_bf16 v[108:111], v[152:155], v[192:195], v[108:111]
	v_mfma_f32_16x16x32_bf16 v[104:107], v[160:163], v[192:195], v[104:107]
	v_mfma_f32_16x16x32_bf16 v[92:95], v[152:155], v[200:203], v[92:95]
	v_mfma_f32_16x16x32_bf16 v[88:91], v[160:163], v[200:203], v[88:91]
	v_mfma_f32_16x16x32_bf16 v[76:79], v[152:155], v[208:211], v[76:79]
	v_mfma_f32_16x16x32_bf16 v[72:75], v[160:163], v[208:211], v[72:75]
	v_mfma_f32_16x16x32_bf16 v[116:119], v[164:167], v[180:183], v[116:119]
	v_mfma_f32_16x16x32_bf16 v[112:115], v[172:175], v[180:183], v[112:115]
	v_mfma_f32_16x16x32_bf16 v[100:103], v[164:167], v[188:191], v[100:103]
	v_mfma_f32_16x16x32_bf16 v[96:99], v[172:175], v[188:191], v[96:99]
	v_mfma_f32_16x16x32_bf16 v[84:87], v[164:167], v[196:199], v[84:87]
	v_mfma_f32_16x16x32_bf16 v[80:83], v[172:175], v[196:199], v[80:83]
	v_mfma_f32_16x16x32_bf16 v[68:71], v[164:167], v[204:207], v[68:71]
	v_mfma_f32_16x16x32_bf16 v[64:67], v[172:175], v[204:207], v[64:67]
	v_mfma_f32_16x16x32_bf16 v[116:119], v[168:171], v[184:187], v[116:119]
	v_mfma_f32_16x16x32_bf16 v[112:115], v[176:179], v[184:187], v[112:115]
	v_mfma_f32_16x16x32_bf16 v[100:103], v[168:171], v[192:195], v[100:103]
	v_mfma_f32_16x16x32_bf16 v[96:99], v[176:179], v[192:195], v[96:99]
	v_mfma_f32_16x16x32_bf16 v[84:87], v[168:171], v[200:203], v[84:87]
	v_mfma_f32_16x16x32_bf16 v[80:83], v[176:179], v[200:203], v[80:83]
	v_mfma_f32_16x16x32_bf16 v[68:71], v[168:171], v[208:211], v[68:71]
	v_mfma_f32_16x16x32_bf16 v[64:67], v[176:179], v[208:211], v[64:67]
	s_setprio 0
	s_barrier
	ds_read_b128 v[180:183], v151 offset:16384
	ds_read_b128 v[184:187], v151 offset:17408
	ds_read_b128 v[188:191], v151 offset:18432
	ds_read_b128 v[192:195], v151 offset:19456
	ds_read_b128 v[196:199], v151 offset:20480
	ds_read_b128 v[200:203], v151 offset:21504
	ds_read_b128 v[204:207], v151 offset:22528
	ds_read_b128 v[208:211], v151 offset:23552
	s_add_i32 s60, s34, s94
	v_lshl_add_u64 v[212:213], s[74:75], 0, v[128:129]
	s_mov_b32 m0, s60
	s_nop 0
	global_load_lds_dwordx4 v[212:213], off
	s_add_i32 m0, s60, 0x2000
	s_add_u32 s80, s74, 0x200000
	v_lshl_add_u64 v[214:215], s[74:75], 0, v[130:131]
	s_addc_u32 s81, s75, 0
	s_add_i32 s60, s35, s94
	global_load_lds_dwordx4 v[214:215], off
	v_lshl_add_u64 v[216:217], s[80:81], 0, v[128:129]
	s_mov_b32 m0, s60
	v_lshl_add_u64 v[218:219], s[76:77], 0, v[130:131]
	global_load_lds_dwordx4 v[216:217], off
	v_lshl_add_u64 v[216:217], s[80:81], 0, v[130:131]
	s_add_i32 m0, s60, 0x2000
	s_nop 0
	global_load_lds_dwordx4 v[216:217], off
	v_lshl_add_u64 v[216:217], s[76:77], 0, v[128:129]
	s_mov_b32 m0, s6
	s_nop 0
	global_load_lds_dwordx4 v[216:217], off
	s_mov_b32 m0, s7
	s_nop 0
	global_load_lds_dwordx4 v[218:219], off
	s_waitcnt vmcnt(8)
	s_waitcnt lgkmcnt(0)
	s_barrier
	s_setprio 1
	s_waitcnt lgkmcnt(0)
	v_mfma_f32_16x16x32_bf16 v[60:63], v[140:143], v[180:183], v[60:63]
	v_mfma_f32_16x16x32_bf16 v[56:59], v[156:159], v[180:183], v[56:59]
	v_mfma_f32_16x16x32_bf16 v[44:47], v[140:143], v[188:191], v[44:47]
	v_mfma_f32_16x16x32_bf16 v[40:43], v[156:159], v[188:191], v[40:43]
	v_mfma_f32_16x16x32_bf16 v[28:31], v[140:143], v[196:199], v[28:31]
	v_mfma_f32_16x16x32_bf16 v[24:27], v[156:159], v[196:199], v[24:27]
	v_mfma_f32_16x16x32_bf16 v[12:15], v[140:143], v[204:207], v[12:15]
	v_mfma_f32_16x16x32_bf16 v[8:11], v[156:159], v[204:207], v[8:11]
	v_mfma_f32_16x16x32_bf16 v[60:63], v[152:155], v[184:187], v[60:63]
	v_mfma_f32_16x16x32_bf16 v[56:59], v[160:163], v[184:187], v[56:59]
	v_mfma_f32_16x16x32_bf16 v[44:47], v[152:155], v[192:195], v[44:47]
	v_mfma_f32_16x16x32_bf16 v[40:43], v[160:163], v[192:195], v[40:43]
	v_mfma_f32_16x16x32_bf16 v[28:31], v[152:155], v[200:203], v[28:31]
	v_mfma_f32_16x16x32_bf16 v[24:27], v[160:163], v[200:203], v[24:27]
	v_mfma_f32_16x16x32_bf16 v[12:15], v[152:155], v[208:211], v[12:15]
	v_mfma_f32_16x16x32_bf16 v[8:11], v[160:163], v[208:211], v[8:11]
	v_mfma_f32_16x16x32_bf16 v[52:55], v[164:167], v[180:183], v[52:55]
	v_mfma_f32_16x16x32_bf16 v[48:51], v[172:175], v[180:183], v[48:51]
	v_mfma_f32_16x16x32_bf16 v[36:39], v[164:167], v[188:191], v[36:39]
	v_mfma_f32_16x16x32_bf16 v[32:35], v[172:175], v[188:191], v[32:35]
	v_mfma_f32_16x16x32_bf16 v[20:23], v[164:167], v[196:199], v[20:23]
	v_mfma_f32_16x16x32_bf16 v[16:19], v[172:175], v[196:199], v[16:19]
	v_mfma_f32_16x16x32_bf16 v[4:7], v[164:167], v[204:207], v[4:7]
	v_mfma_f32_16x16x32_bf16 v[0:3], v[172:175], v[204:207], v[0:3]
	v_mfma_f32_16x16x32_bf16 v[52:55], v[168:171], v[184:187], v[52:55]
	v_mfma_f32_16x16x32_bf16 v[48:51], v[176:179], v[184:187], v[48:51]
	v_mfma_f32_16x16x32_bf16 v[36:39], v[168:171], v[192:195], v[36:39]
	v_mfma_f32_16x16x32_bf16 v[32:35], v[176:179], v[192:195], v[32:35]
	v_mfma_f32_16x16x32_bf16 v[20:23], v[168:171], v[200:203], v[20:23]
	v_mfma_f32_16x16x32_bf16 v[16:19], v[176:179], v[200:203], v[16:19]
	v_mfma_f32_16x16x32_bf16 v[4:7], v[168:171], v[208:211], v[4:7]
	v_mfma_f32_16x16x32_bf16 v[0:3], v[176:179], v[208:211], v[0:3]
	s_setprio 0
	s_barrier
	s_add_i32 s60, 0, 0x18000
	s_add_i32 s61, 0, 0x1c000
	v_add_u32_e32 v160, s60, v145
	ds_read_b128 v[140:143], v160
	ds_read_b128 v[152:155], v160 offset:1024
	ds_read_b128 v[156:159], v160 offset:2048
	ds_read_b128 v[160:163], v160 offset:3072
	v_add_u32_e32 v176, s61, v145
	ds_read_b128 v[164:167], v176
	ds_read_b128 v[168:171], v176 offset:1024
	ds_read_b128 v[172:175], v176 offset:2048
	ds_read_b128 v[176:179], v176 offset:3072
	ds_read_b128 v[180:183], v151 offset:32768
	ds_read_b128 v[184:187], v151 offset:33792
	ds_read_b128 v[188:191], v151 offset:34816
	ds_read_b128 v[192:195], v151 offset:35840
	ds_read_b128 v[196:199], v151 offset:36864
	ds_read_b128 v[200:203], v151 offset:37888
	ds_read_b128 v[204:207], v151 offset:38912
	ds_read_b128 v[208:211], v151 offset:39936
	s_add_u32 s76, s76, 0x200000
	s_addc_u32 s77, s77, 0
	s_mov_b32 m0, s12
	v_lshl_add_u64 v[220:221], s[76:77], 0, v[128:129]
	global_load_lds_dwordx4 v[220:221], off
	v_lshl_add_u64 v[220:221], s[76:77], 0, v[130:131]
	s_mov_b32 m0, s13
	s_nop 0
	global_load_lds_dwordx4 v[220:221], off
	s_waitcnt vmcnt(8)
	s_waitcnt lgkmcnt(0)
	s_barrier
	s_setprio 1
	s_waitcnt lgkmcnt(0)
	v_mfma_f32_16x16x32_bf16 v[124:127], v[140:143], v[180:183], v[124:127]
	v_mfma_f32_16x16x32_bf16 v[120:123], v[156:159], v[180:183], v[120:123]
	v_mfma_f32_16x16x32_bf16 v[108:111], v[140:143], v[188:191], v[108:111]
	v_mfma_f32_16x16x32_bf16 v[104:107], v[156:159], v[188:191], v[104:107]
	v_mfma_f32_16x16x32_bf16 v[92:95], v[140:143], v[196:199], v[92:95]
	v_mfma_f32_16x16x32_bf16 v[88:91], v[156:159], v[196:199], v[88:91]
	v_mfma_f32_16x16x32_bf16 v[76:79], v[140:143], v[204:207], v[76:79]
	v_mfma_f32_16x16x32_bf16 v[72:75], v[156:159], v[204:207], v[72:75]
	v_mfma_f32_16x16x32_bf16 v[124:127], v[152:155], v[184:187], v[124:127]
	v_mfma_f32_16x16x32_bf16 v[120:123], v[160:163], v[184:187], v[120:123]
	v_mfma_f32_16x16x32_bf16 v[108:111], v[152:155], v[192:195], v[108:111]
	v_mfma_f32_16x16x32_bf16 v[104:107], v[160:163], v[192:195], v[104:107]
	v_mfma_f32_16x16x32_bf16 v[92:95], v[152:155], v[200:203], v[92:95]
	v_mfma_f32_16x16x32_bf16 v[88:91], v[160:163], v[200:203], v[88:91]
	v_mfma_f32_16x16x32_bf16 v[76:79], v[152:155], v[208:211], v[76:79]
	v_mfma_f32_16x16x32_bf16 v[72:75], v[160:163], v[208:211], v[72:75]
	v_mfma_f32_16x16x32_bf16 v[116:119], v[164:167], v[180:183], v[116:119]
	v_mfma_f32_16x16x32_bf16 v[112:115], v[172:175], v[180:183], v[112:115]
	v_mfma_f32_16x16x32_bf16 v[100:103], v[164:167], v[188:191], v[100:103]
	v_mfma_f32_16x16x32_bf16 v[96:99], v[172:175], v[188:191], v[96:99]
	v_mfma_f32_16x16x32_bf16 v[84:87], v[164:167], v[196:199], v[84:87]
	v_mfma_f32_16x16x32_bf16 v[80:83], v[172:175], v[196:199], v[80:83]
	v_mfma_f32_16x16x32_bf16 v[68:71], v[164:167], v[204:207], v[68:71]
	v_mfma_f32_16x16x32_bf16 v[64:67], v[172:175], v[204:207], v[64:67]
	v_mfma_f32_16x16x32_bf16 v[116:119], v[168:171], v[184:187], v[116:119]
	v_mfma_f32_16x16x32_bf16 v[112:115], v[176:179], v[184:187], v[112:115]
	v_mfma_f32_16x16x32_bf16 v[100:103], v[168:171], v[192:195], v[100:103]
	v_mfma_f32_16x16x32_bf16 v[96:99], v[176:179], v[192:195], v[96:99]
	v_mfma_f32_16x16x32_bf16 v[84:87], v[168:171], v[200:203], v[84:87]
	v_mfma_f32_16x16x32_bf16 v[80:83], v[176:179], v[200:203], v[80:83]
	v_mfma_f32_16x16x32_bf16 v[68:71], v[168:171], v[208:211], v[68:71]
	v_mfma_f32_16x16x32_bf16 v[64:67], v[176:179], v[208:211], v[64:67]
	s_setprio 0
	s_barrier
	ds_read_b128 v[180:183], v151 offset:49152
	ds_read_b128 v[184:187], v151 offset:50176
	ds_read_b128 v[188:191], v151 offset:51200
	ds_read_b128 v[192:195], v151 offset:52224
	ds_read_b128 v[196:199], v151 offset:53248
	ds_read_b128 v[200:203], v151 offset:54272
	ds_read_b128 v[204:207], v151 offset:55296
	ds_read_b128 v[208:211], v151 offset:56320
	s_add_i32 s60, s60, s94
	v_lshl_add_u64 v[212:213], v[212:213], 0, s[22:23]
	s_mov_b32 m0, s60
	s_nop 0
	global_load_lds_dwordx4 v[212:213], off
	s_add_i32 m0, s60, 0x2000
	s_add_u32 s74, s74, 0x200080
	v_lshl_add_u64 v[212:213], v[214:215], 0, s[22:23]
	s_addc_u32 s75, s75, 0
	s_add_i32 s60, s61, s94
	global_load_lds_dwordx4 v[212:213], off
	v_lshl_add_u64 v[212:213], s[74:75], 0, v[128:129]
	s_mov_b32 m0, s60
	s_nop 0
	global_load_lds_dwordx4 v[212:213], off
	v_lshl_add_u64 v[212:213], s[74:75], 0, v[130:131]
	s_add_i32 m0, s60, 0x2000
	s_nop 0
	global_load_lds_dwordx4 v[212:213], off
	v_lshl_add_u64 v[212:213], v[216:217], 0, s[22:23]
	s_mov_b32 m0, s29
	s_nop 0
	global_load_lds_dwordx4 v[212:213], off
	v_lshl_add_u64 v[212:213], v[218:219], 0, s[22:23]
	s_mov_b32 m0, s30
	s_nop 0
	global_load_lds_dwordx4 v[212:213], off
	s_waitcnt vmcnt(8)
	s_waitcnt lgkmcnt(0)
	s_barrier
	s_setprio 1
	s_waitcnt lgkmcnt(0)
	v_mfma_f32_16x16x32_bf16 v[60:63], v[140:143], v[180:183], v[60:63]
	v_mfma_f32_16x16x32_bf16 v[56:59], v[156:159], v[180:183], v[56:59]
	v_mfma_f32_16x16x32_bf16 v[44:47], v[140:143], v[188:191], v[44:47]
	v_mfma_f32_16x16x32_bf16 v[40:43], v[156:159], v[188:191], v[40:43]
	v_mfma_f32_16x16x32_bf16 v[28:31], v[140:143], v[196:199], v[28:31]
	v_mfma_f32_16x16x32_bf16 v[24:27], v[156:159], v[196:199], v[24:27]
	v_mfma_f32_16x16x32_bf16 v[12:15], v[140:143], v[204:207], v[12:15]
	v_mfma_f32_16x16x32_bf16 v[8:11], v[156:159], v[204:207], v[8:11]
	v_mfma_f32_16x16x32_bf16 v[60:63], v[152:155], v[184:187], v[60:63]
	v_mfma_f32_16x16x32_bf16 v[56:59], v[160:163], v[184:187], v[56:59]
	v_mfma_f32_16x16x32_bf16 v[44:47], v[152:155], v[192:195], v[44:47]
	v_mfma_f32_16x16x32_bf16 v[40:43], v[160:163], v[192:195], v[40:43]
	v_mfma_f32_16x16x32_bf16 v[28:31], v[152:155], v[200:203], v[28:31]
	v_mfma_f32_16x16x32_bf16 v[24:27], v[160:163], v[200:203], v[24:27]
	v_mfma_f32_16x16x32_bf16 v[12:15], v[152:155], v[208:211], v[12:15]
	v_mfma_f32_16x16x32_bf16 v[8:11], v[160:163], v[208:211], v[8:11]
	v_mfma_f32_16x16x32_bf16 v[52:55], v[164:167], v[180:183], v[52:55]
	v_mfma_f32_16x16x32_bf16 v[48:51], v[172:175], v[180:183], v[48:51]
	v_mfma_f32_16x16x32_bf16 v[36:39], v[164:167], v[188:191], v[36:39]
	v_mfma_f32_16x16x32_bf16 v[32:35], v[172:175], v[188:191], v[32:35]
	v_mfma_f32_16x16x32_bf16 v[20:23], v[164:167], v[196:199], v[20:23]
	v_mfma_f32_16x16x32_bf16 v[16:19], v[172:175], v[196:199], v[16:19]
	v_mfma_f32_16x16x32_bf16 v[4:7], v[164:167], v[204:207], v[4:7]
	v_mfma_f32_16x16x32_bf16 v[0:3], v[172:175], v[204:207], v[0:3]
	v_mfma_f32_16x16x32_bf16 v[52:55], v[168:171], v[184:187], v[52:55]
	v_mfma_f32_16x16x32_bf16 v[48:51], v[176:179], v[184:187], v[48:51]
	v_mfma_f32_16x16x32_bf16 v[36:39], v[168:171], v[192:195], v[36:39]
	v_mfma_f32_16x16x32_bf16 v[32:35], v[176:179], v[192:195], v[32:35]
	v_mfma_f32_16x16x32_bf16 v[20:23], v[168:171], v[200:203], v[20:23]
	v_mfma_f32_16x16x32_bf16 v[16:19], v[176:179], v[200:203], v[16:19]
	v_mfma_f32_16x16x32_bf16 v[4:7], v[168:171], v[208:211], v[4:7]
	v_mfma_f32_16x16x32_bf16 v[0:3], v[176:179], v[208:211], v[0:3]
	s_setprio 0
	s_barrier
	s_add_i32 s79, s79, 2
	s_add_u32 s72, s72, 0x100
	s_addc_u32 s73, s73, 0
	s_add_u32 s71, s71, 0x100
	s_addc_u32 s78, s78, 0
	s_cmpk_gt_u32 s79, 0x7d
	s_cbranch_scc0 .LBB0_1897
	s_and_b64 vcc, exec, s[58:59]
	s_cbranch_vccz .LBB0_1900
	s_barrier

.LBB0_2128:
	ds_read_b128 v[148:151], v179
	ds_read_b128 v[152:155], v179 offset:1024
	ds_read_b128 v[156:159], v179 offset:2048
	ds_read_b128 v[160:163], v179 offset:3072
	ds_read_b128 v[164:167], v180
	ds_read_b128 v[168:171], v180 offset:1024
	ds_read_b128 v[184:187], v180 offset:2048
	ds_read_b128 v[188:191], v180 offset:3072
	ds_read_b128 v[192:195], v181
	ds_read_b128 v[196:199], v181 offset:1024
	ds_read_b128 v[200:203], v181 offset:2048
	ds_read_b128 v[204:207], v181 offset:3072
	ds_read_b128 v[208:211], v181 offset:4096
	ds_read_b128 v[212:215], v181 offset:5120
	ds_read_b128 v[216:219], v181 offset:6144
	ds_read_b128 v[220:223], v181 offset:7168
	s_add_u32 s60, s84, 0xfff80080
	s_addc_u32 s61, s85, -1
	s_cmp_eq_u32 s95, 28
	s_cselect_b32 s89, s23, s61
	s_cselect_b32 s88, s79, s60
	s_cselect_b32 s87, s77, s97
	s_cselect_b32 s86, vcc_lo, vcc_hi
	v_lshl_add_u64 v[172:173], s[84:85], 0, v[140:141]
	s_add_i32 m0, s6, 0xc000
	s_nop 0
	global_load_lds_dwordx4 v[172:173], off
	v_lshl_add_u64 v[172:173], s[84:85], 0, v[142:143]
	s_add_i32 m0, s6, 0xe000
	s_nop 0
	global_load_lds_dwordx4 v[172:173], off
	s_waitcnt vmcnt(8)
	s_waitcnt lgkmcnt(0)
	s_barrier
	s_setprio 1
	s_waitcnt lgkmcnt(0)
	v_mfma_f32_16x16x32_bf16 v[124:127], v[148:151], v[192:195], v[124:127]
	v_mfma_f32_16x16x32_bf16 v[120:123], v[156:159], v[192:195], v[120:123]
	v_mfma_f32_16x16x32_bf16 v[108:111], v[148:151], v[200:203], v[108:111]
	v_mfma_f32_16x16x32_bf16 v[104:107], v[156:159], v[200:203], v[104:107]
	v_mfma_f32_16x16x32_bf16 v[92:95], v[148:151], v[208:211], v[92:95]
	v_mfma_f32_16x16x32_bf16 v[88:91], v[156:159], v[208:211], v[88:91]
	v_mfma_f32_16x16x32_bf16 v[76:79], v[148:151], v[216:219], v[76:79]
	v_mfma_f32_16x16x32_bf16 v[72:75], v[156:159], v[216:219], v[72:75]
	v_mfma_f32_16x16x32_bf16 v[124:127], v[152:155], v[196:199], v[124:127]
	v_mfma_f32_16x16x32_bf16 v[120:123], v[160:163], v[196:199], v[120:123]
	v_mfma_f32_16x16x32_bf16 v[108:111], v[152:155], v[204:207], v[108:111]
	v_mfma_f32_16x16x32_bf16 v[104:107], v[160:163], v[204:207], v[104:107]
	v_mfma_f32_16x16x32_bf16 v[92:95], v[152:155], v[212:215], v[92:95]
	v_mfma_f32_16x16x32_bf16 v[88:91], v[160:163], v[212:215], v[88:91]
	v_mfma_f32_16x16x32_bf16 v[76:79], v[152:155], v[220:223], v[76:79]
	v_mfma_f32_16x16x32_bf16 v[72:75], v[160:163], v[220:223], v[72:75]
	v_mfma_f32_16x16x32_bf16 v[116:119], v[164:167], v[192:195], v[116:119]
	v_mfma_f32_16x16x32_bf16 v[112:115], v[184:187], v[192:195], v[112:115]
	v_mfma_f32_16x16x32_bf16 v[100:103], v[164:167], v[200:203], v[100:103]
	v_mfma_f32_16x16x32_bf16 v[96:99], v[184:187], v[200:203], v[96:99]
	v_mfma_f32_16x16x32_bf16 v[84:87], v[164:167], v[208:211], v[84:87]
	v_mfma_f32_16x16x32_bf16 v[80:83], v[184:187], v[208:211], v[80:83]
	v_mfma_f32_16x16x32_bf16 v[68:71], v[164:167], v[216:219], v[68:71]
	v_mfma_f32_16x16x32_bf16 v[64:67], v[184:187], v[216:219], v[64:67]
	v_mfma_f32_16x16x32_bf16 v[116:119], v[168:171], v[196:199], v[116:119]
	v_mfma_f32_16x16x32_bf16 v[112:115], v[188:191], v[196:199], v[112:115]
	v_mfma_f32_16x16x32_bf16 v[100:103], v[168:171], v[204:207], v[100:103]
	v_mfma_f32_16x16x32_bf16 v[96:99], v[188:191], v[204:207], v[96:99]
	v_mfma_f32_16x16x32_bf16 v[84:87], v[168:171], v[212:215], v[84:87]
	v_mfma_f32_16x16x32_bf16 v[80:83], v[188:191], v[212:215], v[80:83]
	v_mfma_f32_16x16x32_bf16 v[68:71], v[168:171], v[220:223], v[68:71]
	v_mfma_f32_16x16x32_bf16 v[64:67], v[188:191], v[220:223], v[64:67]
	s_setprio 0
	s_barrier
	ds_read_b128 v[192:195], v181 offset:16384
	ds_read_b128 v[196:199], v181 offset:17408
	ds_read_b128 v[200:203], v181 offset:18432
	ds_read_b128 v[204:207], v181 offset:19456
	ds_read_b128 v[208:211], v181 offset:20480
	ds_read_b128 v[212:215], v181 offset:21504
	ds_read_b128 v[216:219], v181 offset:22528
	ds_read_b128 v[220:223], v181 offset:23552
	s_add_i32 s60, s12, s94
	v_lshl_add_u64 v[172:173], s[86:87], 0, v[130:131]
	s_mov_b32 m0, s60
	s_nop 0
	global_load_lds_dwordx4 v[172:173], off
	s_add_i32 m0, s60, 0x2000
	s_add_u32 s60, s86, 0x80000
	v_lshl_add_u64 v[224:225], s[86:87], 0, v[134:135]
	s_addc_u32 s61, s87, 0
	s_add_i32 s96, s13, s94
	global_load_lds_dwordx4 v[224:225], off
	v_lshl_add_u64 v[226:227], s[60:61], 0, v[130:131]
	s_mov_b32 m0, s96
	v_lshl_add_u64 v[228:229], s[88:89], 0, v[132:133]
	global_load_lds_dwordx4 v[226:227], off
	v_lshl_add_u64 v[226:227], s[60:61], 0, v[134:135]
	s_add_i32 m0, s96, 0x2000
	s_nop 0
	global_load_lds_dwordx4 v[226:227], off
	v_lshl_add_u64 v[226:227], s[88:89], 0, v[128:129]
	s_mov_b32 m0, s6
	s_nop 0
	global_load_lds_dwordx4 v[226:227], off
	s_mov_b32 m0, s7
	s_nop 0
	global_load_lds_dwordx4 v[228:229], off
	s_waitcnt vmcnt(8)
	s_waitcnt lgkmcnt(0)
	s_barrier
	s_setprio 1
	s_waitcnt lgkmcnt(0)
	v_mfma_f32_16x16x32_bf16 v[60:63], v[148:151], v[192:195], v[60:63]
	v_mfma_f32_16x16x32_bf16 v[56:59], v[156:159], v[192:195], v[56:59]
	v_mfma_f32_16x16x32_bf16 v[44:47], v[148:151], v[200:203], v[44:47]
	v_mfma_f32_16x16x32_bf16 v[40:43], v[156:159], v[200:203], v[40:43]
	v_mfma_f32_16x16x32_bf16 v[28:31], v[148:151], v[208:211], v[28:31]
	v_mfma_f32_16x16x32_bf16 v[24:27], v[156:159], v[208:211], v[24:27]
	v_mfma_f32_16x16x32_bf16 v[12:15], v[148:151], v[216:219], v[12:15]
	v_mfma_f32_16x16x32_bf16 v[8:11], v[156:159], v[216:219], v[8:11]
	v_mfma_f32_16x16x32_bf16 v[60:63], v[152:155], v[196:199], v[60:63]
	v_mfma_f32_16x16x32_bf16 v[56:59], v[160:163], v[196:199], v[56:59]
	v_mfma_f32_16x16x32_bf16 v[44:47], v[152:155], v[204:207], v[44:47]
	v_mfma_f32_16x16x32_bf16 v[40:43], v[160:163], v[204:207], v[40:43]
	v_mfma_f32_16x16x32_bf16 v[28:31], v[152:155], v[212:215], v[28:31]
	v_mfma_f32_16x16x32_bf16 v[24:27], v[160:163], v[212:215], v[24:27]
	v_mfma_f32_16x16x32_bf16 v[12:15], v[152:155], v[220:223], v[12:15]
	v_mfma_f32_16x16x32_bf16 v[8:11], v[160:163], v[220:223], v[8:11]
	v_mfma_f32_16x16x32_bf16 v[52:55], v[164:167], v[192:195], v[52:55]
	v_mfma_f32_16x16x32_bf16 v[48:51], v[184:187], v[192:195], v[48:51]
	v_mfma_f32_16x16x32_bf16 v[36:39], v[164:167], v[200:203], v[36:39]
	v_mfma_f32_16x16x32_bf16 v[32:35], v[184:187], v[200:203], v[32:35]
	v_mfma_f32_16x16x32_bf16 v[20:23], v[164:167], v[208:211], v[20:23]
	v_mfma_f32_16x16x32_bf16 v[16:19], v[184:187], v[208:211], v[16:19]
	v_mfma_f32_16x16x32_bf16 v[4:7], v[164:167], v[216:219], v[4:7]
	v_mfma_f32_16x16x32_bf16 v[0:3], v[184:187], v[216:219], v[0:3]
	v_mfma_f32_16x16x32_bf16 v[52:55], v[168:171], v[196:199], v[52:55]
	v_mfma_f32_16x16x32_bf16 v[48:51], v[188:191], v[196:199], v[48:51]
	v_mfma_f32_16x16x32_bf16 v[36:39], v[168:171], v[204:207], v[36:39]
	v_mfma_f32_16x16x32_bf16 v[32:35], v[188:191], v[204:207], v[32:35]
	v_mfma_f32_16x16x32_bf16 v[20:23], v[168:171], v[212:215], v[20:23]
	v_mfma_f32_16x16x32_bf16 v[16:19], v[188:191], v[212:215], v[16:19]
	v_mfma_f32_16x16x32_bf16 v[4:7], v[168:171], v[220:223], v[4:7]
	v_mfma_f32_16x16x32_bf16 v[0:3], v[188:191], v[220:223], v[0:3]
	s_setprio 0
	s_barrier
	s_add_i32 s96, 0, 0x18000
	v_add_u32_e32 v136, s96, v175
	ds_read_b128 v[148:151], v136
	ds_read_b128 v[152:155], v136 offset:1024
	ds_read_b128 v[156:159], v136 offset:2048
	ds_read_b128 v[160:163], v136 offset:3072
	s_add_i32 s8, 0, 0x1c000
	v_add_u32_e32 v136, s8, v175
	ds_read_b128 v[164:167], v136
	ds_read_b128 v[168:171], v136 offset:1024
	ds_read_b128 v[184:187], v136 offset:2048
	ds_read_b128 v[188:191], v136 offset:3072
	ds_read_b128 v[192:195], v181 offset:32768
	ds_read_b128 v[196:199], v181 offset:33792
	ds_read_b128 v[200:203], v181 offset:34816
	ds_read_b128 v[204:207], v181 offset:35840
	ds_read_b128 v[208:211], v181 offset:36864
	ds_read_b128 v[212:215], v181 offset:37888
	ds_read_b128 v[216:219], v181 offset:38912
	ds_read_b128 v[220:223], v181 offset:39936
	s_add_u32 s60, s88, 0x80000
	s_addc_u32 s61, s89, 0
	s_mov_b32 m0, s34
	v_lshl_add_u64 v[230:231], s[60:61], 0, v[128:129]
	global_load_lds_dwordx4 v[230:231], off
	v_lshl_add_u64 v[230:231], s[60:61], 0, v[132:133]
	s_mov_b32 m0, s46
	s_nop 0
	global_load_lds_dwordx4 v[230:231], off
	s_waitcnt vmcnt(8)
	s_waitcnt lgkmcnt(0)
	s_barrier
	s_setprio 1
	s_waitcnt lgkmcnt(0)
	v_mfma_f32_16x16x32_bf16 v[124:127], v[148:151], v[192:195], v[124:127]
	v_mfma_f32_16x16x32_bf16 v[120:123], v[156:159], v[192:195], v[120:123]
	v_mfma_f32_16x16x32_bf16 v[108:111], v[148:151], v[200:203], v[108:111]
	v_mfma_f32_16x16x32_bf16 v[104:107], v[156:159], v[200:203], v[104:107]
	v_mfma_f32_16x16x32_bf16 v[92:95], v[148:151], v[208:211], v[92:95]
	v_mfma_f32_16x16x32_bf16 v[88:91], v[156:159], v[208:211], v[88:91]
	v_mfma_f32_16x16x32_bf16 v[76:79], v[148:151], v[216:219], v[76:79]
	v_mfma_f32_16x16x32_bf16 v[72:75], v[156:159], v[216:219], v[72:75]
	v_mfma_f32_16x16x32_bf16 v[124:127], v[152:155], v[196:199], v[124:127]
	v_mfma_f32_16x16x32_bf16 v[120:123], v[160:163], v[196:199], v[120:123]
	v_mfma_f32_16x16x32_bf16 v[108:111], v[152:155], v[204:207], v[108:111]
	v_mfma_f32_16x16x32_bf16 v[104:107], v[160:163], v[204:207], v[104:107]
	v_mfma_f32_16x16x32_bf16 v[92:95], v[152:155], v[212:215], v[92:95]
	v_mfma_f32_16x16x32_bf16 v[88:91], v[160:163], v[212:215], v[88:91]
	v_mfma_f32_16x16x32_bf16 v[76:79], v[152:155], v[220:223], v[76:79]
	v_mfma_f32_16x16x32_bf16 v[72:75], v[160:163], v[220:223], v[72:75]
	v_mfma_f32_16x16x32_bf16 v[116:119], v[164:167], v[192:195], v[116:119]
	v_mfma_f32_16x16x32_bf16 v[112:115], v[184:187], v[192:195], v[112:115]
	v_mfma_f32_16x16x32_bf16 v[100:103], v[164:167], v[200:203], v[100:103]
	v_mfma_f32_16x16x32_bf16 v[96:99], v[184:187], v[200:203], v[96:99]
	v_mfma_f32_16x16x32_bf16 v[84:87], v[164:167], v[208:211], v[84:87]
	v_mfma_f32_16x16x32_bf16 v[80:83], v[184:187], v[208:211], v[80:83]
	v_mfma_f32_16x16x32_bf16 v[68:71], v[164:167], v[216:219], v[68:71]
	v_mfma_f32_16x16x32_bf16 v[64:67], v[184:187], v[216:219], v[64:67]
	v_mfma_f32_16x16x32_bf16 v[116:119], v[168:171], v[196:199], v[116:119]
	v_mfma_f32_16x16x32_bf16 v[112:115], v[188:191], v[196:199], v[112:115]
	v_mfma_f32_16x16x32_bf16 v[100:103], v[168:171], v[204:207], v[100:103]
	v_mfma_f32_16x16x32_bf16 v[96:99], v[188:191], v[204:207], v[96:99]
	v_mfma_f32_16x16x32_bf16 v[84:87], v[168:171], v[212:215], v[84:87]
	v_mfma_f32_16x16x32_bf16 v[80:83], v[188:191], v[212:215], v[80:83]
	v_mfma_f32_16x16x32_bf16 v[68:71], v[168:171], v[220:223], v[68:71]
	v_mfma_f32_16x16x32_bf16 v[64:67], v[188:191], v[220:223], v[64:67]
	s_setprio 0
	s_barrier
	ds_read_b128 v[192:195], v181 offset:49152
	ds_read_b128 v[196:199], v181 offset:50176
	ds_read_b128 v[200:203], v181 offset:51200
	ds_read_b128 v[204:207], v181 offset:52224
	ds_read_b128 v[208:211], v181 offset:53248
	ds_read_b128 v[212:215], v181 offset:54272
	ds_read_b128 v[216:219], v181 offset:55296
	ds_read_b128 v[220:223], v181 offset:56320
	s_add_i32 s9, s96, s94
	v_lshl_add_u64 v[172:173], v[172:173], 0, s[74:75]
	s_mov_b32 m0, s9
	s_nop 0
	global_load_lds_dwordx4 v[172:173], off
	s_add_i32 m0, s9, 0x2000
	s_add_u32 s60, s86, 0x80080
	v_lshl_add_u64 v[172:173], v[224:225], 0, s[74:75]
	s_addc_u32 s61, s87, 0
	s_add_i32 s8, s8, s94
	global_load_lds_dwordx4 v[172:173], off
	v_lshl_add_u64 v[172:173], s[60:61], 0, v[130:131]
	s_mov_b32 m0, s8
	s_nop 0
	global_load_lds_dwordx4 v[172:173], off
	v_lshl_add_u64 v[172:173], s[60:61], 0, v[134:135]
	s_add_i32 m0, s8, 0x2000
	s_nop 0
	global_load_lds_dwordx4 v[172:173], off
	v_lshl_add_u64 v[172:173], v[226:227], 0, s[74:75]
	s_mov_b32 m0, s56
	s_nop 0
	global_load_lds_dwordx4 v[172:173], off
	v_lshl_add_u64 v[172:173], v[228:229], 0, s[74:75]
	s_mov_b32 m0, s57
	s_nop 0
	global_load_lds_dwordx4 v[172:173], off
	s_waitcnt vmcnt(8)
	s_waitcnt lgkmcnt(0)
	s_barrier
	s_setprio 1
	s_waitcnt lgkmcnt(0)
	v_mfma_f32_16x16x32_bf16 v[60:63], v[148:151], v[192:195], v[60:63]
	v_mfma_f32_16x16x32_bf16 v[56:59], v[156:159], v[192:195], v[56:59]
	v_mfma_f32_16x16x32_bf16 v[44:47], v[148:151], v[200:203], v[44:47]
	v_mfma_f32_16x16x32_bf16 v[40:43], v[156:159], v[200:203], v[40:43]
	v_mfma_f32_16x16x32_bf16 v[28:31], v[148:151], v[208:211], v[28:31]
	v_mfma_f32_16x16x32_bf16 v[24:27], v[156:159], v[208:211], v[24:27]
	v_mfma_f32_16x16x32_bf16 v[12:15], v[148:151], v[216:219], v[12:15]
	v_mfma_f32_16x16x32_bf16 v[8:11], v[156:159], v[216:219], v[8:11]
	v_mfma_f32_16x16x32_bf16 v[60:63], v[152:155], v[196:199], v[60:63]
	v_mfma_f32_16x16x32_bf16 v[56:59], v[160:163], v[196:199], v[56:59]
	v_mfma_f32_16x16x32_bf16 v[44:47], v[152:155], v[204:207], v[44:47]
	v_mfma_f32_16x16x32_bf16 v[40:43], v[160:163], v[204:207], v[40:43]
	v_mfma_f32_16x16x32_bf16 v[28:31], v[152:155], v[212:215], v[28:31]
	v_mfma_f32_16x16x32_bf16 v[24:27], v[160:163], v[212:215], v[24:27]
	v_mfma_f32_16x16x32_bf16 v[12:15], v[152:155], v[220:223], v[12:15]
	v_mfma_f32_16x16x32_bf16 v[8:11], v[160:163], v[220:223], v[8:11]
	v_mfma_f32_16x16x32_bf16 v[52:55], v[164:167], v[192:195], v[52:55]
	v_mfma_f32_16x16x32_bf16 v[48:51], v[184:187], v[192:195], v[48:51]
	v_mfma_f32_16x16x32_bf16 v[36:39], v[164:167], v[200:203], v[36:39]
	v_mfma_f32_16x16x32_bf16 v[32:35], v[184:187], v[200:203], v[32:35]
	v_mfma_f32_16x16x32_bf16 v[20:23], v[164:167], v[208:211], v[20:23]
	v_mfma_f32_16x16x32_bf16 v[16:19], v[184:187], v[208:211], v[16:19]
	v_mfma_f32_16x16x32_bf16 v[4:7], v[164:167], v[216:219], v[4:7]
	v_mfma_f32_16x16x32_bf16 v[0:3], v[184:187], v[216:219], v[0:3]
	v_mfma_f32_16x16x32_bf16 v[52:55], v[168:171], v[196:199], v[52:55]
	v_mfma_f32_16x16x32_bf16 v[48:51], v[188:191], v[196:199], v[48:51]
	v_mfma_f32_16x16x32_bf16 v[36:39], v[168:171], v[204:207], v[36:39]
	v_mfma_f32_16x16x32_bf16 v[32:35], v[188:191], v[204:207], v[32:35]
	v_mfma_f32_16x16x32_bf16 v[20:23], v[168:171], v[212:215], v[20:23]
	v_mfma_f32_16x16x32_bf16 v[16:19], v[188:191], v[212:215], v[16:19]
	v_mfma_f32_16x16x32_bf16 v[4:7], v[168:171], v[220:223], v[4:7]
	v_mfma_f32_16x16x32_bf16 v[0:3], v[188:191], v[220:223], v[0:3]
	s_setprio 0
	s_barrier
	s_add_i32 s95, s95, 2
	s_add_u32 s84, s84, 0x100
	s_addc_u32 s85, s85, 0
	s_add_u32 vcc_hi, vcc_hi, 0x100
	s_addc_u32 s97, s97, 0
	s_cmp_gt_u32 s95, 29
	s_cbranch_scc0 .LBB0_2128
	s_and_b64 vcc, exec, s[58:59]
	s_cbranch_vccz .LBB0_2131
	s_barrier

.LBB0_2459:
	ds_read_b128 v[148:151], v163
	ds_read_b128 v[152:155], v163 offset:1024
	ds_read_b128 v[168:171], v163 offset:2048
	ds_read_b128 v[172:175], v163 offset:3072
	ds_read_b128 v[176:179], v164
	ds_read_b128 v[180:183], v164 offset:1024
	ds_read_b128 v[184:187], v164 offset:2048
	ds_read_b128 v[188:191], v164 offset:3072
	ds_read_b128 v[192:195], v165
	ds_read_b128 v[196:199], v165 offset:1024
	ds_read_b128 v[200:203], v165 offset:2048
	ds_read_b128 v[204:207], v165 offset:3072
	ds_read_b128 v[208:211], v165 offset:4096
	ds_read_b128 v[212:215], v165 offset:5120
	ds_read_b128 v[216:219], v165 offset:6144
	ds_read_b128 v[220:223], v165 offset:7168
	s_add_u32 s16, s70, 0x100
	s_addc_u32 s17, s71, 0
	s_cmp_eq_u32 s86, 8
	s_cselect_b32 s75, s23, s17
	s_cselect_b32 s74, s22, s16
	s_cselect_b32 s73, s49, s85
	s_cselect_b32 s72, s48, s84
	v_lshl_add_u64 v[156:157], s[70:71], 0, v[140:141]
	s_add_i32 m0, s12, 0xc000
	s_nop 0
	global_load_lds_dwordx4 v[156:157], off
	v_lshl_add_u64 v[156:157], s[70:71], 0, v[142:143]
	s_add_i32 m0, s12, 0xe000
	s_nop 0
	global_load_lds_dwordx4 v[156:157], off
	s_waitcnt vmcnt(8)
	s_waitcnt lgkmcnt(0)
	s_barrier
	s_setprio 1
	s_waitcnt lgkmcnt(0)
	v_mfma_f32_16x16x32_bf16 v[124:127], v[148:151], v[192:195], v[124:127]
	v_mfma_f32_16x16x32_bf16 v[120:123], v[168:171], v[192:195], v[120:123]
	v_mfma_f32_16x16x32_bf16 v[108:111], v[148:151], v[200:203], v[108:111]
	v_mfma_f32_16x16x32_bf16 v[104:107], v[168:171], v[200:203], v[104:107]
	v_mfma_f32_16x16x32_bf16 v[92:95], v[148:151], v[208:211], v[92:95]
	v_mfma_f32_16x16x32_bf16 v[88:91], v[168:171], v[208:211], v[88:91]
	v_mfma_f32_16x16x32_bf16 v[76:79], v[148:151], v[216:219], v[76:79]
	v_mfma_f32_16x16x32_bf16 v[72:75], v[168:171], v[216:219], v[72:75]
	v_mfma_f32_16x16x32_bf16 v[124:127], v[152:155], v[196:199], v[124:127]
	v_mfma_f32_16x16x32_bf16 v[120:123], v[172:175], v[196:199], v[120:123]
	v_mfma_f32_16x16x32_bf16 v[108:111], v[152:155], v[204:207], v[108:111]
	v_mfma_f32_16x16x32_bf16 v[104:107], v[172:175], v[204:207], v[104:107]
	v_mfma_f32_16x16x32_bf16 v[92:95], v[152:155], v[212:215], v[92:95]
	v_mfma_f32_16x16x32_bf16 v[88:91], v[172:175], v[212:215], v[88:91]
	v_mfma_f32_16x16x32_bf16 v[76:79], v[152:155], v[220:223], v[76:79]
	v_mfma_f32_16x16x32_bf16 v[72:75], v[172:175], v[220:223], v[72:75]
	v_mfma_f32_16x16x32_bf16 v[116:119], v[176:179], v[192:195], v[116:119]
	v_mfma_f32_16x16x32_bf16 v[112:115], v[184:187], v[192:195], v[112:115]
	v_mfma_f32_16x16x32_bf16 v[100:103], v[176:179], v[200:203], v[100:103]
	v_mfma_f32_16x16x32_bf16 v[96:99], v[184:187], v[200:203], v[96:99]
	v_mfma_f32_16x16x32_bf16 v[84:87], v[176:179], v[208:211], v[84:87]
	v_mfma_f32_16x16x32_bf16 v[80:83], v[184:187], v[208:211], v[80:83]
	v_mfma_f32_16x16x32_bf16 v[68:71], v[176:179], v[216:219], v[68:71]
	v_mfma_f32_16x16x32_bf16 v[64:67], v[184:187], v[216:219], v[64:67]
	v_mfma_f32_16x16x32_bf16 v[116:119], v[180:183], v[196:199], v[116:119]
	v_mfma_f32_16x16x32_bf16 v[112:115], v[188:191], v[196:199], v[112:115]
	v_mfma_f32_16x16x32_bf16 v[100:103], v[180:183], v[204:207], v[100:103]
	v_mfma_f32_16x16x32_bf16 v[96:99], v[188:191], v[204:207], v[96:99]
	v_mfma_f32_16x16x32_bf16 v[84:87], v[180:183], v[212:215], v[84:87]
	v_mfma_f32_16x16x32_bf16 v[80:83], v[188:191], v[212:215], v[80:83]
	v_mfma_f32_16x16x32_bf16 v[68:71], v[180:183], v[220:223], v[68:71]
	v_mfma_f32_16x16x32_bf16 v[64:67], v[188:191], v[220:223], v[64:67]
	s_setprio 0
	s_barrier
	ds_read_b128 v[192:195], v165 offset:16384
	ds_read_b128 v[196:199], v165 offset:17408
	ds_read_b128 v[200:203], v165 offset:18432
	ds_read_b128 v[204:207], v165 offset:19456
	ds_read_b128 v[208:211], v165 offset:20480
	ds_read_b128 v[212:215], v165 offset:21504
	ds_read_b128 v[216:219], v165 offset:22528
	ds_read_b128 v[220:223], v165 offset:23552
	s_add_i32 s8, s76, s94
	v_lshl_add_u64 v[156:157], s[72:73], 0, v[130:131]
	s_mov_b32 m0, s8
	s_nop 0
	global_load_lds_dwordx4 v[156:157], off
	s_add_i32 m0, s8, 0x2000
	s_add_u32 s60, s72, 0x30000
	v_lshl_add_u64 v[224:225], s[72:73], 0, v[134:135]
	s_addc_u32 s61, s73, 0
	s_add_i32 s8, s77, s94
	global_load_lds_dwordx4 v[224:225], off
	v_lshl_add_u64 v[226:227], s[60:61], 0, v[130:131]
	s_mov_b32 m0, s8
	v_lshl_add_u64 v[228:229], s[74:75], 0, v[132:133]
	global_load_lds_dwordx4 v[226:227], off
	v_lshl_add_u64 v[226:227], s[60:61], 0, v[134:135]
	s_add_i32 m0, s8, 0x2000
	s_nop 0
	global_load_lds_dwordx4 v[226:227], off
	v_lshl_add_u64 v[226:227], s[74:75], 0, v[128:129]
	s_mov_b32 m0, s12
	s_nop 0
	global_load_lds_dwordx4 v[226:227], off
	s_mov_b32 m0, s13
	s_nop 0
	global_load_lds_dwordx4 v[228:229], off
	s_waitcnt vmcnt(8)
	s_waitcnt lgkmcnt(0)
	s_barrier
	s_setprio 1
	s_waitcnt lgkmcnt(0)
	v_mfma_f32_16x16x32_bf16 v[60:63], v[148:151], v[192:195], v[60:63]
	v_mfma_f32_16x16x32_bf16 v[56:59], v[168:171], v[192:195], v[56:59]
	v_mfma_f32_16x16x32_bf16 v[44:47], v[148:151], v[200:203], v[44:47]
	v_mfma_f32_16x16x32_bf16 v[40:43], v[168:171], v[200:203], v[40:43]
	v_mfma_f32_16x16x32_bf16 v[28:31], v[148:151], v[208:211], v[28:31]
	v_mfma_f32_16x16x32_bf16 v[24:27], v[168:171], v[208:211], v[24:27]
	v_mfma_f32_16x16x32_bf16 v[12:15], v[148:151], v[216:219], v[12:15]
	v_mfma_f32_16x16x32_bf16 v[8:11], v[168:171], v[216:219], v[8:11]
	v_mfma_f32_16x16x32_bf16 v[60:63], v[152:155], v[196:199], v[60:63]
	v_mfma_f32_16x16x32_bf16 v[56:59], v[172:175], v[196:199], v[56:59]
	v_mfma_f32_16x16x32_bf16 v[44:47], v[152:155], v[204:207], v[44:47]
	v_mfma_f32_16x16x32_bf16 v[40:43], v[172:175], v[204:207], v[40:43]
	v_mfma_f32_16x16x32_bf16 v[28:31], v[152:155], v[212:215], v[28:31]
	v_mfma_f32_16x16x32_bf16 v[24:27], v[172:175], v[212:215], v[24:27]
	v_mfma_f32_16x16x32_bf16 v[12:15], v[152:155], v[220:223], v[12:15]
	v_mfma_f32_16x16x32_bf16 v[8:11], v[172:175], v[220:223], v[8:11]
	v_mfma_f32_16x16x32_bf16 v[52:55], v[176:179], v[192:195], v[52:55]
	v_mfma_f32_16x16x32_bf16 v[48:51], v[184:187], v[192:195], v[48:51]
	v_mfma_f32_16x16x32_bf16 v[36:39], v[176:179], v[200:203], v[36:39]
	v_mfma_f32_16x16x32_bf16 v[32:35], v[184:187], v[200:203], v[32:35]
	v_mfma_f32_16x16x32_bf16 v[20:23], v[176:179], v[208:211], v[20:23]
	v_mfma_f32_16x16x32_bf16 v[16:19], v[184:187], v[208:211], v[16:19]
	v_mfma_f32_16x16x32_bf16 v[4:7], v[176:179], v[216:219], v[4:7]
	v_mfma_f32_16x16x32_bf16 v[0:3], v[184:187], v[216:219], v[0:3]
	v_mfma_f32_16x16x32_bf16 v[52:55], v[180:183], v[196:199], v[52:55]
	v_mfma_f32_16x16x32_bf16 v[48:51], v[188:191], v[196:199], v[48:51]
	v_mfma_f32_16x16x32_bf16 v[36:39], v[180:183], v[204:207], v[36:39]
	v_mfma_f32_16x16x32_bf16 v[32:35], v[188:191], v[204:207], v[32:35]
	v_mfma_f32_16x16x32_bf16 v[20:23], v[180:183], v[212:215], v[20:23]
	v_mfma_f32_16x16x32_bf16 v[16:19], v[188:191], v[212:215], v[16:19]
	v_mfma_f32_16x16x32_bf16 v[4:7], v[180:183], v[220:223], v[4:7]
	v_mfma_f32_16x16x32_bf16 v[0:3], v[188:191], v[220:223], v[0:3]
	s_setprio 0
	s_barrier
	s_add_i32 s8, 0, 0x18000
	v_add_u32_e32 v136, s8, v159
	ds_read_b128 v[148:151], v136
	ds_read_b128 v[152:155], v136 offset:1024
	ds_read_b128 v[168:171], v136 offset:2048
	ds_read_b128 v[172:175], v136 offset:3072
	s_add_i32 s9, 0, 0x1c000
	v_add_u32_e32 v136, s9, v159
	ds_read_b128 v[176:179], v136
	ds_read_b128 v[180:183], v136 offset:1024
	ds_read_b128 v[184:187], v136 offset:2048
	ds_read_b128 v[188:191], v136 offset:3072
	ds_read_b128 v[192:195], v165 offset:32768
	ds_read_b128 v[196:199], v165 offset:33792
	ds_read_b128 v[200:203], v165 offset:34816
	ds_read_b128 v[204:207], v165 offset:35840
	ds_read_b128 v[208:211], v165 offset:36864
	ds_read_b128 v[212:215], v165 offset:37888
	ds_read_b128 v[216:219], v165 offset:38912
	ds_read_b128 v[220:223], v165 offset:39936
	s_add_u32 s60, s74, 0x60000
	s_addc_u32 s61, s75, 0
	s_mov_b32 m0, s29
	v_lshl_add_u64 v[230:231], s[60:61], 0, v[128:129]
	global_load_lds_dwordx4 v[230:231], off
	v_lshl_add_u64 v[230:231], s[60:61], 0, v[132:133]
	s_mov_b32 m0, s30
	s_nop 0
	global_load_lds_dwordx4 v[230:231], off
	s_waitcnt vmcnt(8)
	s_waitcnt lgkmcnt(0)
	s_barrier
	s_setprio 1
	s_waitcnt lgkmcnt(0)
	v_mfma_f32_16x16x32_bf16 v[124:127], v[148:151], v[192:195], v[124:127]
	v_mfma_f32_16x16x32_bf16 v[120:123], v[168:171], v[192:195], v[120:123]
	v_mfma_f32_16x16x32_bf16 v[108:111], v[148:151], v[200:203], v[108:111]
	v_mfma_f32_16x16x32_bf16 v[104:107], v[168:171], v[200:203], v[104:107]
	v_mfma_f32_16x16x32_bf16 v[92:95], v[148:151], v[208:211], v[92:95]
	v_mfma_f32_16x16x32_bf16 v[88:91], v[168:171], v[208:211], v[88:91]
	v_mfma_f32_16x16x32_bf16 v[76:79], v[148:151], v[216:219], v[76:79]
	v_mfma_f32_16x16x32_bf16 v[72:75], v[168:171], v[216:219], v[72:75]
	v_mfma_f32_16x16x32_bf16 v[124:127], v[152:155], v[196:199], v[124:127]
	v_mfma_f32_16x16x32_bf16 v[120:123], v[172:175], v[196:199], v[120:123]
	v_mfma_f32_16x16x32_bf16 v[108:111], v[152:155], v[204:207], v[108:111]
	v_mfma_f32_16x16x32_bf16 v[104:107], v[172:175], v[204:207], v[104:107]
	v_mfma_f32_16x16x32_bf16 v[92:95], v[152:155], v[212:215], v[92:95]
	v_mfma_f32_16x16x32_bf16 v[88:91], v[172:175], v[212:215], v[88:91]
	v_mfma_f32_16x16x32_bf16 v[76:79], v[152:155], v[220:223], v[76:79]
	v_mfma_f32_16x16x32_bf16 v[72:75], v[172:175], v[220:223], v[72:75]
	v_mfma_f32_16x16x32_bf16 v[116:119], v[176:179], v[192:195], v[116:119]
	v_mfma_f32_16x16x32_bf16 v[112:115], v[184:187], v[192:195], v[112:115]
	v_mfma_f32_16x16x32_bf16 v[100:103], v[176:179], v[200:203], v[100:103]
	v_mfma_f32_16x16x32_bf16 v[96:99], v[184:187], v[200:203], v[96:99]
	v_mfma_f32_16x16x32_bf16 v[84:87], v[176:179], v[208:211], v[84:87]
	v_mfma_f32_16x16x32_bf16 v[80:83], v[184:187], v[208:211], v[80:83]
	v_mfma_f32_16x16x32_bf16 v[68:71], v[176:179], v[216:219], v[68:71]
	v_mfma_f32_16x16x32_bf16 v[64:67], v[184:187], v[216:219], v[64:67]
	v_mfma_f32_16x16x32_bf16 v[116:119], v[180:183], v[196:199], v[116:119]
	v_mfma_f32_16x16x32_bf16 v[112:115], v[188:191], v[196:199], v[112:115]
	v_mfma_f32_16x16x32_bf16 v[100:103], v[180:183], v[204:207], v[100:103]
	v_mfma_f32_16x16x32_bf16 v[96:99], v[188:191], v[204:207], v[96:99]
	v_mfma_f32_16x16x32_bf16 v[84:87], v[180:183], v[212:215], v[84:87]
	v_mfma_f32_16x16x32_bf16 v[80:83], v[188:191], v[212:215], v[80:83]
	v_mfma_f32_16x16x32_bf16 v[68:71], v[180:183], v[220:223], v[68:71]
	v_mfma_f32_16x16x32_bf16 v[64:67], v[188:191], v[220:223], v[64:67]
	s_setprio 0
	s_barrier
	ds_read_b128 v[192:195], v165 offset:49152
	ds_read_b128 v[196:199], v165 offset:50176
	ds_read_b128 v[200:203], v165 offset:51200
	ds_read_b128 v[204:207], v165 offset:52224
	ds_read_b128 v[208:211], v165 offset:53248
	ds_read_b128 v[212:215], v165 offset:54272
	ds_read_b128 v[216:219], v165 offset:55296
	ds_read_b128 v[220:223], v165 offset:56320
	s_add_i32 s8, s8, s94
	v_lshl_add_u64 v[156:157], v[156:157], 0, s[20:21]
	s_mov_b32 m0, s8
	s_nop 0
	global_load_lds_dwordx4 v[156:157], off
	s_add_i32 m0, s8, 0x2000
	s_add_u32 s60, s72, 0x30080
	v_lshl_add_u64 v[156:157], v[224:225], 0, s[20:21]
	s_addc_u32 s61, s73, 0
	s_add_i32 s8, s9, s94
	global_load_lds_dwordx4 v[156:157], off
	v_lshl_add_u64 v[156:157], s[60:61], 0, v[130:131]
	s_mov_b32 m0, s8
	s_nop 0
	global_load_lds_dwordx4 v[156:157], off
	v_lshl_add_u64 v[156:157], s[60:61], 0, v[134:135]
	s_add_i32 m0, s8, 0x2000
	s_nop 0
	global_load_lds_dwordx4 v[156:157], off
	v_lshl_add_u64 v[156:157], v[226:227], 0, s[20:21]
	s_mov_b32 m0, s46
	s_nop 0
	global_load_lds_dwordx4 v[156:157], off
	v_lshl_add_u64 v[156:157], v[228:229], 0, s[20:21]
	s_mov_b32 m0, s56
	s_nop 0
	global_load_lds_dwordx4 v[156:157], off
	s_waitcnt vmcnt(8)
	s_waitcnt lgkmcnt(0)
	s_barrier
	s_setprio 1
	s_waitcnt lgkmcnt(0)
	v_mfma_f32_16x16x32_bf16 v[60:63], v[148:151], v[192:195], v[60:63]
	v_mfma_f32_16x16x32_bf16 v[56:59], v[168:171], v[192:195], v[56:59]
	v_mfma_f32_16x16x32_bf16 v[44:47], v[148:151], v[200:203], v[44:47]
	v_mfma_f32_16x16x32_bf16 v[40:43], v[168:171], v[200:203], v[40:43]
	v_mfma_f32_16x16x32_bf16 v[28:31], v[148:151], v[208:211], v[28:31]
	v_mfma_f32_16x16x32_bf16 v[24:27], v[168:171], v[208:211], v[24:27]
	v_mfma_f32_16x16x32_bf16 v[12:15], v[148:151], v[216:219], v[12:15]
	v_mfma_f32_16x16x32_bf16 v[8:11], v[168:171], v[216:219], v[8:11]
	v_mfma_f32_16x16x32_bf16 v[60:63], v[152:155], v[196:199], v[60:63]
	v_mfma_f32_16x16x32_bf16 v[56:59], v[172:175], v[196:199], v[56:59]
	v_mfma_f32_16x16x32_bf16 v[44:47], v[152:155], v[204:207], v[44:47]
	v_mfma_f32_16x16x32_bf16 v[40:43], v[172:175], v[204:207], v[40:43]
	v_mfma_f32_16x16x32_bf16 v[28:31], v[152:155], v[212:215], v[28:31]
	v_mfma_f32_16x16x32_bf16 v[24:27], v[172:175], v[212:215], v[24:27]
	v_mfma_f32_16x16x32_bf16 v[12:15], v[152:155], v[220:223], v[12:15]
	v_mfma_f32_16x16x32_bf16 v[8:11], v[172:175], v[220:223], v[8:11]
	v_mfma_f32_16x16x32_bf16 v[52:55], v[176:179], v[192:195], v[52:55]
	v_mfma_f32_16x16x32_bf16 v[48:51], v[184:187], v[192:195], v[48:51]
	v_mfma_f32_16x16x32_bf16 v[36:39], v[176:179], v[200:203], v[36:39]
	v_mfma_f32_16x16x32_bf16 v[32:35], v[184:187], v[200:203], v[32:35]
	v_mfma_f32_16x16x32_bf16 v[20:23], v[176:179], v[208:211], v[20:23]
	v_mfma_f32_16x16x32_bf16 v[16:19], v[184:187], v[208:211], v[16:19]
	v_mfma_f32_16x16x32_bf16 v[4:7], v[176:179], v[216:219], v[4:7]
	v_mfma_f32_16x16x32_bf16 v[0:3], v[184:187], v[216:219], v[0:3]
	v_mfma_f32_16x16x32_bf16 v[52:55], v[180:183], v[196:199], v[52:55]
	v_mfma_f32_16x16x32_bf16 v[48:51], v[188:191], v[196:199], v[48:51]
	v_mfma_f32_16x16x32_bf16 v[36:39], v[180:183], v[204:207], v[36:39]
	v_mfma_f32_16x16x32_bf16 v[32:35], v[188:191], v[204:207], v[32:35]
	v_mfma_f32_16x16x32_bf16 v[20:23], v[180:183], v[212:215], v[20:23]
	v_mfma_f32_16x16x32_bf16 v[16:19], v[188:191], v[212:215], v[16:19]
	v_mfma_f32_16x16x32_bf16 v[4:7], v[180:183], v[220:223], v[4:7]
	v_mfma_f32_16x16x32_bf16 v[0:3], v[188:191], v[220:223], v[0:3]
	s_setprio 0
	s_barrier
	s_add_i32 s86, s86, 2
	s_add_u32 s84, s84, 0x100
	s_addc_u32 s85, s85, 0
	s_cmp_gt_u32 s86, 9
	s_mov_b64 s[70:71], s[16:17]
	s_cbranch_scc0 .LBB0_2459
	s_and_b64 vcc, exec, s[58:59]
	s_cbranch_vccz .LBB0_2462
	s_barrier

.LBB0_2535:
	ds_read_b128 v[146:149], v155
	ds_read_b128 v[160:163], v155 offset:1024
	ds_read_b128 v[164:167], v155 offset:2048
	ds_read_b128 v[168:171], v155 offset:3072
	ds_read_b128 v[172:175], v156
	ds_read_b128 v[176:179], v156 offset:1024
	ds_read_b128 v[180:183], v156 offset:2048
	ds_read_b128 v[184:187], v156 offset:3072
	ds_read_b128 v[188:191], v157
	ds_read_b128 v[192:195], v157 offset:1024
	ds_read_b128 v[196:199], v157 offset:2048
	ds_read_b128 v[200:203], v157 offset:3072
	ds_read_b128 v[204:207], v157 offset:4096
	ds_read_b128 v[208:211], v157 offset:5120
	ds_read_b128 v[212:215], v157 offset:6144
	ds_read_b128 v[216:219], v157 offset:7168
	s_add_u32 s16, s68, 0x100
	s_addc_u32 s17, s69, 0
	s_cmp_eq_u32 s80, 4
	s_cselect_b32 s73, s49, s17
	s_cselect_b32 s72, s48, s16
	s_cselect_b32 s71, s43, s79
	s_cselect_b32 s70, s77, s78
	v_lshl_add_u64 v[220:221], s[68:69], 0, v[138:139]
	s_add_i32 m0, s29, 0xc000
	s_nop 0
	global_load_lds_dwordx4 v[220:221], off
	v_lshl_add_u64 v[220:221], s[68:69], 0, v[140:141]
	s_add_i32 m0, s29, 0xe000
	s_nop 0
	global_load_lds_dwordx4 v[220:221], off
	s_waitcnt vmcnt(8)
	s_waitcnt lgkmcnt(0)
	s_barrier
	s_setprio 1
	s_waitcnt lgkmcnt(0)
	v_mfma_f32_16x16x32_bf16 v[124:127], v[146:149], v[188:191], v[124:127]
	v_mfma_f32_16x16x32_bf16 v[120:123], v[164:167], v[188:191], v[120:123]
	v_mfma_f32_16x16x32_bf16 v[108:111], v[146:149], v[196:199], v[108:111]
	v_mfma_f32_16x16x32_bf16 v[104:107], v[164:167], v[196:199], v[104:107]
	v_mfma_f32_16x16x32_bf16 v[92:95], v[146:149], v[204:207], v[92:95]
	v_mfma_f32_16x16x32_bf16 v[88:91], v[164:167], v[204:207], v[88:91]
	v_mfma_f32_16x16x32_bf16 v[76:79], v[146:149], v[212:215], v[76:79]
	v_mfma_f32_16x16x32_bf16 v[72:75], v[164:167], v[212:215], v[72:75]
	v_mfma_f32_16x16x32_bf16 v[124:127], v[160:163], v[192:195], v[124:127]
	v_mfma_f32_16x16x32_bf16 v[120:123], v[168:171], v[192:195], v[120:123]
	v_mfma_f32_16x16x32_bf16 v[108:111], v[160:163], v[200:203], v[108:111]
	v_mfma_f32_16x16x32_bf16 v[104:107], v[168:171], v[200:203], v[104:107]
	v_mfma_f32_16x16x32_bf16 v[92:95], v[160:163], v[208:211], v[92:95]
	v_mfma_f32_16x16x32_bf16 v[88:91], v[168:171], v[208:211], v[88:91]
	v_mfma_f32_16x16x32_bf16 v[76:79], v[160:163], v[216:219], v[76:79]
	v_mfma_f32_16x16x32_bf16 v[72:75], v[168:171], v[216:219], v[72:75]
	v_mfma_f32_16x16x32_bf16 v[116:119], v[172:175], v[188:191], v[116:119]
	v_mfma_f32_16x16x32_bf16 v[112:115], v[180:183], v[188:191], v[112:115]
	v_mfma_f32_16x16x32_bf16 v[100:103], v[172:175], v[196:199], v[100:103]
	v_mfma_f32_16x16x32_bf16 v[96:99], v[180:183], v[196:199], v[96:99]
	v_mfma_f32_16x16x32_bf16 v[84:87], v[172:175], v[204:207], v[84:87]
	v_mfma_f32_16x16x32_bf16 v[80:83], v[180:183], v[204:207], v[80:83]
	v_mfma_f32_16x16x32_bf16 v[68:71], v[172:175], v[212:215], v[68:71]
	v_mfma_f32_16x16x32_bf16 v[64:67], v[180:183], v[212:215], v[64:67]
	v_mfma_f32_16x16x32_bf16 v[116:119], v[176:179], v[192:195], v[116:119]
	v_mfma_f32_16x16x32_bf16 v[112:115], v[184:187], v[192:195], v[112:115]
	v_mfma_f32_16x16x32_bf16 v[100:103], v[176:179], v[200:203], v[100:103]
	v_mfma_f32_16x16x32_bf16 v[96:99], v[184:187], v[200:203], v[96:99]
	v_mfma_f32_16x16x32_bf16 v[84:87], v[176:179], v[208:211], v[84:87]
	v_mfma_f32_16x16x32_bf16 v[80:83], v[184:187], v[208:211], v[80:83]
	v_mfma_f32_16x16x32_bf16 v[68:71], v[176:179], v[216:219], v[68:71]
	v_mfma_f32_16x16x32_bf16 v[64:67], v[184:187], v[216:219], v[64:67]
	s_setprio 0
	s_barrier
	ds_read_b128 v[188:191], v157 offset:16384
	ds_read_b128 v[192:195], v157 offset:17408
	ds_read_b128 v[196:199], v157 offset:18432
	ds_read_b128 v[200:203], v157 offset:19456
	ds_read_b128 v[204:207], v157 offset:20480
	ds_read_b128 v[208:211], v157 offset:21504
	ds_read_b128 v[212:215], v157 offset:22528
	ds_read_b128 v[216:219], v157 offset:23552
	s_add_i32 s8, s67, s94
	v_lshl_add_u64 v[220:221], s[70:71], 0, v[130:131]
	s_mov_b32 m0, s8
	s_nop 0
	global_load_lds_dwordx4 v[220:221], off
	s_add_i32 m0, s8, 0x2000
	s_add_u32 s60, s70, 0x20000
	v_lshl_add_u64 v[222:223], s[70:71], 0, v[134:135]
	s_addc_u32 s61, s71, 0
	s_add_i32 s8, s74, s94
	global_load_lds_dwordx4 v[222:223], off
	v_lshl_add_u64 v[224:225], s[60:61], 0, v[130:131]
	s_mov_b32 m0, s8
	v_lshl_add_u64 v[226:227], s[72:73], 0, v[132:133]
	global_load_lds_dwordx4 v[224:225], off
	v_lshl_add_u64 v[224:225], s[60:61], 0, v[134:135]
	s_add_i32 m0, s8, 0x2000
	s_nop 0
	global_load_lds_dwordx4 v[224:225], off
	v_lshl_add_u64 v[224:225], s[72:73], 0, v[128:129]
	s_mov_b32 m0, s29
	s_nop 0
	global_load_lds_dwordx4 v[224:225], off
	s_mov_b32 m0, s30
	s_nop 0
	global_load_lds_dwordx4 v[226:227], off
	s_waitcnt vmcnt(8)
	s_waitcnt lgkmcnt(0)
	s_barrier
	s_setprio 1
	s_waitcnt lgkmcnt(0)
	v_mfma_f32_16x16x32_bf16 v[60:63], v[146:149], v[188:191], v[60:63]
	v_mfma_f32_16x16x32_bf16 v[56:59], v[164:167], v[188:191], v[56:59]
	v_mfma_f32_16x16x32_bf16 v[44:47], v[146:149], v[196:199], v[44:47]
	v_mfma_f32_16x16x32_bf16 v[40:43], v[164:167], v[196:199], v[40:43]
	v_mfma_f32_16x16x32_bf16 v[28:31], v[146:149], v[204:207], v[28:31]
	v_mfma_f32_16x16x32_bf16 v[24:27], v[164:167], v[204:207], v[24:27]
	v_mfma_f32_16x16x32_bf16 v[12:15], v[146:149], v[212:215], v[12:15]
	v_mfma_f32_16x16x32_bf16 v[8:11], v[164:167], v[212:215], v[8:11]
	v_mfma_f32_16x16x32_bf16 v[60:63], v[160:163], v[192:195], v[60:63]
	v_mfma_f32_16x16x32_bf16 v[56:59], v[168:171], v[192:195], v[56:59]
	v_mfma_f32_16x16x32_bf16 v[44:47], v[160:163], v[200:203], v[44:47]
	v_mfma_f32_16x16x32_bf16 v[40:43], v[168:171], v[200:203], v[40:43]
	v_mfma_f32_16x16x32_bf16 v[28:31], v[160:163], v[208:211], v[28:31]
	v_mfma_f32_16x16x32_bf16 v[24:27], v[168:171], v[208:211], v[24:27]
	v_mfma_f32_16x16x32_bf16 v[12:15], v[160:163], v[216:219], v[12:15]
	v_mfma_f32_16x16x32_bf16 v[8:11], v[168:171], v[216:219], v[8:11]
	v_mfma_f32_16x16x32_bf16 v[52:55], v[172:175], v[188:191], v[52:55]
	v_mfma_f32_16x16x32_bf16 v[48:51], v[180:183], v[188:191], v[48:51]
	v_mfma_f32_16x16x32_bf16 v[36:39], v[172:175], v[196:199], v[36:39]
	v_mfma_f32_16x16x32_bf16 v[32:35], v[180:183], v[196:199], v[32:35]
	v_mfma_f32_16x16x32_bf16 v[20:23], v[172:175], v[204:207], v[20:23]
	v_mfma_f32_16x16x32_bf16 v[16:19], v[180:183], v[204:207], v[16:19]
	v_mfma_f32_16x16x32_bf16 v[4:7], v[172:175], v[212:215], v[4:7]
	v_mfma_f32_16x16x32_bf16 v[0:3], v[180:183], v[212:215], v[0:3]
	v_mfma_f32_16x16x32_bf16 v[52:55], v[176:179], v[192:195], v[52:55]
	v_mfma_f32_16x16x32_bf16 v[48:51], v[184:187], v[192:195], v[48:51]
	v_mfma_f32_16x16x32_bf16 v[36:39], v[176:179], v[200:203], v[36:39]
	v_mfma_f32_16x16x32_bf16 v[32:35], v[184:187], v[200:203], v[32:35]
	v_mfma_f32_16x16x32_bf16 v[20:23], v[176:179], v[208:211], v[20:23]
	v_mfma_f32_16x16x32_bf16 v[16:19], v[184:187], v[208:211], v[16:19]
	v_mfma_f32_16x16x32_bf16 v[4:7], v[176:179], v[216:219], v[4:7]
	v_mfma_f32_16x16x32_bf16 v[0:3], v[184:187], v[216:219], v[0:3]
	s_setprio 0
	s_barrier
	s_add_i32 s8, 0, 0x18000
	v_add_u32_e32 v159, s8, v151
	ds_read_b128 v[146:149], v159
	ds_read_b128 v[160:163], v159 offset:1024
	ds_read_b128 v[164:167], v159 offset:2048
	ds_read_b128 v[168:171], v159 offset:3072
	s_add_i32 s9, 0, 0x1c000
	v_add_u32_e32 v159, s9, v151
	ds_read_b128 v[172:175], v159
	ds_read_b128 v[176:179], v159 offset:1024
	ds_read_b128 v[180:183], v159 offset:2048
	ds_read_b128 v[184:187], v159 offset:3072
	ds_read_b128 v[188:191], v157 offset:32768
	ds_read_b128 v[192:195], v157 offset:33792
	ds_read_b128 v[196:199], v157 offset:34816
	ds_read_b128 v[200:203], v157 offset:35840
	ds_read_b128 v[204:207], v157 offset:36864
	ds_read_b128 v[208:211], v157 offset:37888
	ds_read_b128 v[212:215], v157 offset:38912
	ds_read_b128 v[216:219], v157 offset:39936
	s_add_u32 s60, s72, 0x60000
	s_addc_u32 s61, s73, 0
	s_mov_b32 m0, s34
	v_lshl_add_u64 v[228:229], s[60:61], 0, v[128:129]
	global_load_lds_dwordx4 v[228:229], off
	v_lshl_add_u64 v[228:229], s[60:61], 0, v[132:133]
	s_mov_b32 m0, s35
	s_nop 0
	global_load_lds_dwordx4 v[228:229], off
	s_waitcnt vmcnt(8)
	s_waitcnt lgkmcnt(0)
	s_barrier
	s_setprio 1
	s_waitcnt lgkmcnt(0)
	v_mfma_f32_16x16x32_bf16 v[124:127], v[146:149], v[188:191], v[124:127]
	v_mfma_f32_16x16x32_bf16 v[120:123], v[164:167], v[188:191], v[120:123]
	v_mfma_f32_16x16x32_bf16 v[108:111], v[146:149], v[196:199], v[108:111]
	v_mfma_f32_16x16x32_bf16 v[104:107], v[164:167], v[196:199], v[104:107]
	v_mfma_f32_16x16x32_bf16 v[92:95], v[146:149], v[204:207], v[92:95]
	v_mfma_f32_16x16x32_bf16 v[88:91], v[164:167], v[204:207], v[88:91]
	v_mfma_f32_16x16x32_bf16 v[76:79], v[146:149], v[212:215], v[76:79]
	v_mfma_f32_16x16x32_bf16 v[72:75], v[164:167], v[212:215], v[72:75]
	v_mfma_f32_16x16x32_bf16 v[124:127], v[160:163], v[192:195], v[124:127]
	v_mfma_f32_16x16x32_bf16 v[120:123], v[168:171], v[192:195], v[120:123]
	v_mfma_f32_16x16x32_bf16 v[108:111], v[160:163], v[200:203], v[108:111]
	v_mfma_f32_16x16x32_bf16 v[104:107], v[168:171], v[200:203], v[104:107]
	v_mfma_f32_16x16x32_bf16 v[92:95], v[160:163], v[208:211], v[92:95]
	v_mfma_f32_16x16x32_bf16 v[88:91], v[168:171], v[208:211], v[88:91]
	v_mfma_f32_16x16x32_bf16 v[76:79], v[160:163], v[216:219], v[76:79]
	v_mfma_f32_16x16x32_bf16 v[72:75], v[168:171], v[216:219], v[72:75]
	v_mfma_f32_16x16x32_bf16 v[116:119], v[172:175], v[188:191], v[116:119]
	v_mfma_f32_16x16x32_bf16 v[112:115], v[180:183], v[188:191], v[112:115]
	v_mfma_f32_16x16x32_bf16 v[100:103], v[172:175], v[196:199], v[100:103]
	v_mfma_f32_16x16x32_bf16 v[96:99], v[180:183], v[196:199], v[96:99]
	v_mfma_f32_16x16x32_bf16 v[84:87], v[172:175], v[204:207], v[84:87]
	v_mfma_f32_16x16x32_bf16 v[80:83], v[180:183], v[204:207], v[80:83]
	v_mfma_f32_16x16x32_bf16 v[68:71], v[172:175], v[212:215], v[68:71]
	v_mfma_f32_16x16x32_bf16 v[64:67], v[180:183], v[212:215], v[64:67]
	v_mfma_f32_16x16x32_bf16 v[116:119], v[176:179], v[192:195], v[116:119]
	v_mfma_f32_16x16x32_bf16 v[112:115], v[184:187], v[192:195], v[112:115]
	v_mfma_f32_16x16x32_bf16 v[100:103], v[176:179], v[200:203], v[100:103]
	v_mfma_f32_16x16x32_bf16 v[96:99], v[184:187], v[200:203], v[96:99]
	v_mfma_f32_16x16x32_bf16 v[84:87], v[176:179], v[208:211], v[84:87]
	v_mfma_f32_16x16x32_bf16 v[80:83], v[184:187], v[208:211], v[80:83]
	v_mfma_f32_16x16x32_bf16 v[68:71], v[176:179], v[216:219], v[68:71]
	v_mfma_f32_16x16x32_bf16 v[64:67], v[184:187], v[216:219], v[64:67]
	s_setprio 0
	s_barrier
	ds_read_b128 v[188:191], v157 offset:49152
	ds_read_b128 v[192:195], v157 offset:50176
	ds_read_b128 v[196:199], v157 offset:51200
	ds_read_b128 v[200:203], v157 offset:52224
	ds_read_b128 v[204:207], v157 offset:53248
	ds_read_b128 v[208:211], v157 offset:54272
	ds_read_b128 v[212:215], v157 offset:55296
	ds_read_b128 v[216:219], v157 offset:56320
	s_add_i32 s8, s8, s94
	v_lshl_add_u64 v[220:221], v[220:221], 0, s[22:23]
	s_mov_b32 m0, s8
	s_nop 0
	global_load_lds_dwordx4 v[220:221], off
	s_add_i32 m0, s8, 0x2000
	s_add_u32 s60, s70, 0x20080
	v_lshl_add_u64 v[220:221], v[222:223], 0, s[22:23]
	s_addc_u32 s61, s71, 0
	s_add_i32 s8, s9, s94
	global_load_lds_dwordx4 v[220:221], off
	v_lshl_add_u64 v[220:221], s[60:61], 0, v[130:131]
	s_mov_b32 m0, s8
	s_nop 0
	global_load_lds_dwordx4 v[220:221], off
	v_lshl_add_u64 v[220:221], s[60:61], 0, v[134:135]
	s_add_i32 m0, s8, 0x2000
	s_nop 0
	global_load_lds_dwordx4 v[220:221], off
	v_lshl_add_u64 v[220:221], v[224:225], 0, s[22:23]
	s_mov_b32 m0, s56
	s_nop 0
	global_load_lds_dwordx4 v[220:221], off
	v_lshl_add_u64 v[220:221], v[226:227], 0, s[22:23]
	s_mov_b32 m0, s57
	s_nop 0
	global_load_lds_dwordx4 v[220:221], off
	s_waitcnt vmcnt(8)
	s_waitcnt lgkmcnt(0)
	s_barrier
	s_setprio 1
	s_waitcnt lgkmcnt(0)
	v_mfma_f32_16x16x32_bf16 v[60:63], v[146:149], v[188:191], v[60:63]
	v_mfma_f32_16x16x32_bf16 v[56:59], v[164:167], v[188:191], v[56:59]
	v_mfma_f32_16x16x32_bf16 v[44:47], v[146:149], v[196:199], v[44:47]
	v_mfma_f32_16x16x32_bf16 v[40:43], v[164:167], v[196:199], v[40:43]
	v_mfma_f32_16x16x32_bf16 v[28:31], v[146:149], v[204:207], v[28:31]
	v_mfma_f32_16x16x32_bf16 v[24:27], v[164:167], v[204:207], v[24:27]
	v_mfma_f32_16x16x32_bf16 v[12:15], v[146:149], v[212:215], v[12:15]
	v_mfma_f32_16x16x32_bf16 v[8:11], v[164:167], v[212:215], v[8:11]
	v_mfma_f32_16x16x32_bf16 v[60:63], v[160:163], v[192:195], v[60:63]
	v_mfma_f32_16x16x32_bf16 v[56:59], v[168:171], v[192:195], v[56:59]
	v_mfma_f32_16x16x32_bf16 v[44:47], v[160:163], v[200:203], v[44:47]
	v_mfma_f32_16x16x32_bf16 v[40:43], v[168:171], v[200:203], v[40:43]
	v_mfma_f32_16x16x32_bf16 v[28:31], v[160:163], v[208:211], v[28:31]
	v_mfma_f32_16x16x32_bf16 v[24:27], v[168:171], v[208:211], v[24:27]
	v_mfma_f32_16x16x32_bf16 v[12:15], v[160:163], v[216:219], v[12:15]
	v_mfma_f32_16x16x32_bf16 v[8:11], v[168:171], v[216:219], v[8:11]
	v_mfma_f32_16x16x32_bf16 v[52:55], v[172:175], v[188:191], v[52:55]
	v_mfma_f32_16x16x32_bf16 v[48:51], v[180:183], v[188:191], v[48:51]
	v_mfma_f32_16x16x32_bf16 v[36:39], v[172:175], v[196:199], v[36:39]
	v_mfma_f32_16x16x32_bf16 v[32:35], v[180:183], v[196:199], v[32:35]
	v_mfma_f32_16x16x32_bf16 v[20:23], v[172:175], v[204:207], v[20:23]
	v_mfma_f32_16x16x32_bf16 v[16:19], v[180:183], v[204:207], v[16:19]
	v_mfma_f32_16x16x32_bf16 v[4:7], v[172:175], v[212:215], v[4:7]
	v_mfma_f32_16x16x32_bf16 v[0:3], v[180:183], v[212:215], v[0:3]
	v_mfma_f32_16x16x32_bf16 v[52:55], v[176:179], v[192:195], v[52:55]
	v_mfma_f32_16x16x32_bf16 v[48:51], v[184:187], v[192:195], v[48:51]
	v_mfma_f32_16x16x32_bf16 v[36:39], v[176:179], v[200:203], v[36:39]
	v_mfma_f32_16x16x32_bf16 v[32:35], v[184:187], v[200:203], v[32:35]
	v_mfma_f32_16x16x32_bf16 v[20:23], v[176:179], v[208:211], v[20:23]
	v_mfma_f32_16x16x32_bf16 v[16:19], v[184:187], v[208:211], v[16:19]
	v_mfma_f32_16x16x32_bf16 v[4:7], v[176:179], v[216:219], v[4:7]
	v_mfma_f32_16x16x32_bf16 v[0:3], v[184:187], v[216:219], v[0:3]
	s_setprio 0
	s_barrier
	s_add_i32 s80, s80, 2
	s_add_u32 s78, s78, 0x100
	s_addc_u32 s79, s79, 0
	s_cmp_gt_u32 s80, 5
	s_mov_b64 s[68:69], s[16:17]
	s_cbranch_scc0 .LBB0_2535
	s_and_b64 vcc, exec, s[58:59]
	s_cbranch_vccz .LBB0_2538
	s_barrier

.LBB0_2713:
	ds_read_b128 v[140:143], v149
	ds_read_b128 v[152:155], v149 offset:1024
	ds_read_b128 v[156:159], v149 offset:2048
	ds_read_b128 v[160:163], v149 offset:3072
	ds_read_b128 v[164:167], v150
	ds_read_b128 v[168:171], v150 offset:1024
	ds_read_b128 v[172:175], v150 offset:2048
	ds_read_b128 v[176:179], v150 offset:3072
	ds_read_b128 v[180:183], v151
	ds_read_b128 v[184:187], v151 offset:1024
	ds_read_b128 v[188:191], v151 offset:2048
	ds_read_b128 v[192:195], v151 offset:3072
	ds_read_b128 v[196:199], v151 offset:4096
	ds_read_b128 v[200:203], v151 offset:5120
	ds_read_b128 v[204:207], v151 offset:6144
	ds_read_b128 v[208:211], v151 offset:7168
	s_add_u32 s8, s62, 0xfff80080
	s_addc_u32 s9, s63, -1
	s_cmp_eq_u32 s72, 28
	s_cselect_b32 s67, s43, s9
	s_cselect_b32 s66, s57, s8
	s_cselect_b32 s65, s23, s71
	s_cselect_b32 s64, s69, s70
	v_lshl_add_u64 v[212:213], s[62:63], 0, v[132:133]
	s_add_i32 m0, s12, 0xc000
	s_nop 0
	global_load_lds_dwordx4 v[212:213], off
	v_lshl_add_u64 v[212:213], s[62:63], 0, v[134:135]
	s_add_i32 m0, s12, 0xe000
	s_nop 0
	global_load_lds_dwordx4 v[212:213], off
	s_waitcnt vmcnt(8)
	s_waitcnt lgkmcnt(0)
	s_barrier
	s_setprio 1
	s_waitcnt lgkmcnt(0)
	v_mfma_f32_16x16x32_bf16 v[124:127], v[140:143], v[180:183], v[124:127]
	v_mfma_f32_16x16x32_bf16 v[120:123], v[156:159], v[180:183], v[120:123]
	v_mfma_f32_16x16x32_bf16 v[108:111], v[140:143], v[188:191], v[108:111]
	v_mfma_f32_16x16x32_bf16 v[104:107], v[156:159], v[188:191], v[104:107]
	v_mfma_f32_16x16x32_bf16 v[92:95], v[140:143], v[196:199], v[92:95]
	v_mfma_f32_16x16x32_bf16 v[88:91], v[156:159], v[196:199], v[88:91]
	v_mfma_f32_16x16x32_bf16 v[76:79], v[140:143], v[204:207], v[76:79]
	v_mfma_f32_16x16x32_bf16 v[72:75], v[156:159], v[204:207], v[72:75]
	v_mfma_f32_16x16x32_bf16 v[124:127], v[152:155], v[184:187], v[124:127]
	v_mfma_f32_16x16x32_bf16 v[120:123], v[160:163], v[184:187], v[120:123]
	v_mfma_f32_16x16x32_bf16 v[108:111], v[152:155], v[192:195], v[108:111]
	v_mfma_f32_16x16x32_bf16 v[104:107], v[160:163], v[192:195], v[104:107]
	v_mfma_f32_16x16x32_bf16 v[92:95], v[152:155], v[200:203], v[92:95]
	v_mfma_f32_16x16x32_bf16 v[88:91], v[160:163], v[200:203], v[88:91]
	v_mfma_f32_16x16x32_bf16 v[76:79], v[152:155], v[208:211], v[76:79]
	v_mfma_f32_16x16x32_bf16 v[72:75], v[160:163], v[208:211], v[72:75]
	v_mfma_f32_16x16x32_bf16 v[116:119], v[164:167], v[180:183], v[116:119]
	v_mfma_f32_16x16x32_bf16 v[112:115], v[172:175], v[180:183], v[112:115]
	v_mfma_f32_16x16x32_bf16 v[100:103], v[164:167], v[188:191], v[100:103]
	v_mfma_f32_16x16x32_bf16 v[96:99], v[172:175], v[188:191], v[96:99]
	v_mfma_f32_16x16x32_bf16 v[84:87], v[164:167], v[196:199], v[84:87]
	v_mfma_f32_16x16x32_bf16 v[80:83], v[172:175], v[196:199], v[80:83]
	v_mfma_f32_16x16x32_bf16 v[68:71], v[164:167], v[204:207], v[68:71]
	v_mfma_f32_16x16x32_bf16 v[64:67], v[172:175], v[204:207], v[64:67]
	v_mfma_f32_16x16x32_bf16 v[116:119], v[168:171], v[184:187], v[116:119]
	v_mfma_f32_16x16x32_bf16 v[112:115], v[176:179], v[184:187], v[112:115]
	v_mfma_f32_16x16x32_bf16 v[100:103], v[168:171], v[192:195], v[100:103]
	v_mfma_f32_16x16x32_bf16 v[96:99], v[176:179], v[192:195], v[96:99]
	v_mfma_f32_16x16x32_bf16 v[84:87], v[168:171], v[200:203], v[84:87]
	v_mfma_f32_16x16x32_bf16 v[80:83], v[176:179], v[200:203], v[80:83]
	v_mfma_f32_16x16x32_bf16 v[68:71], v[168:171], v[208:211], v[68:71]
	v_mfma_f32_16x16x32_bf16 v[64:67], v[176:179], v[208:211], v[64:67]
	s_setprio 0
	s_barrier
	ds_read_b128 v[180:183], v151 offset:16384
	ds_read_b128 v[184:187], v151 offset:17408
	ds_read_b128 v[188:191], v151 offset:18432
	ds_read_b128 v[192:195], v151 offset:19456
	ds_read_b128 v[196:199], v151 offset:20480
	ds_read_b128 v[200:203], v151 offset:21504
	ds_read_b128 v[204:207], v151 offset:22528
	ds_read_b128 v[208:211], v151 offset:23552
	s_add_i32 s8, s46, s94
	v_lshl_add_u64 v[212:213], s[64:65], 0, v[128:129]
	s_mov_b32 m0, s8
	s_nop 0
	global_load_lds_dwordx4 v[212:213], off
	s_add_i32 m0, s8, 0x2000
	s_add_u32 s60, s64, 0x80000
	v_lshl_add_u64 v[214:215], s[64:65], 0, v[130:131]
	s_addc_u32 s61, s65, 0
	s_add_i32 s8, s47, s94
	global_load_lds_dwordx4 v[214:215], off
	v_lshl_add_u64 v[216:217], s[60:61], 0, v[128:129]
	s_mov_b32 m0, s8
	v_lshl_add_u64 v[218:219], s[66:67], 0, v[130:131]
	global_load_lds_dwordx4 v[216:217], off
	v_lshl_add_u64 v[216:217], s[60:61], 0, v[130:131]
	s_add_i32 m0, s8, 0x2000
	s_nop 0
	global_load_lds_dwordx4 v[216:217], off
	v_lshl_add_u64 v[216:217], s[66:67], 0, v[128:129]
	s_mov_b32 m0, s12
	s_nop 0
	global_load_lds_dwordx4 v[216:217], off
	s_mov_b32 m0, s13
	s_nop 0
	global_load_lds_dwordx4 v[218:219], off
	s_waitcnt vmcnt(8)
	s_waitcnt lgkmcnt(0)
	s_barrier
	s_setprio 1
	s_waitcnt lgkmcnt(0)
	v_mfma_f32_16x16x32_bf16 v[60:63], v[140:143], v[180:183], v[60:63]
	v_mfma_f32_16x16x32_bf16 v[56:59], v[156:159], v[180:183], v[56:59]
	v_mfma_f32_16x16x32_bf16 v[44:47], v[140:143], v[188:191], v[44:47]
	v_mfma_f32_16x16x32_bf16 v[40:43], v[156:159], v[188:191], v[40:43]
	v_mfma_f32_16x16x32_bf16 v[28:31], v[140:143], v[196:199], v[28:31]
	v_mfma_f32_16x16x32_bf16 v[24:27], v[156:159], v[196:199], v[24:27]
	v_mfma_f32_16x16x32_bf16 v[12:15], v[140:143], v[204:207], v[12:15]
	v_mfma_f32_16x16x32_bf16 v[8:11], v[156:159], v[204:207], v[8:11]
	v_mfma_f32_16x16x32_bf16 v[60:63], v[152:155], v[184:187], v[60:63]
	v_mfma_f32_16x16x32_bf16 v[56:59], v[160:163], v[184:187], v[56:59]
	v_mfma_f32_16x16x32_bf16 v[44:47], v[152:155], v[192:195], v[44:47]
	v_mfma_f32_16x16x32_bf16 v[40:43], v[160:163], v[192:195], v[40:43]
	v_mfma_f32_16x16x32_bf16 v[28:31], v[152:155], v[200:203], v[28:31]
	v_mfma_f32_16x16x32_bf16 v[24:27], v[160:163], v[200:203], v[24:27]
	v_mfma_f32_16x16x32_bf16 v[12:15], v[152:155], v[208:211], v[12:15]
	v_mfma_f32_16x16x32_bf16 v[8:11], v[160:163], v[208:211], v[8:11]
	v_mfma_f32_16x16x32_bf16 v[52:55], v[164:167], v[180:183], v[52:55]
	v_mfma_f32_16x16x32_bf16 v[48:51], v[172:175], v[180:183], v[48:51]
	v_mfma_f32_16x16x32_bf16 v[36:39], v[164:167], v[188:191], v[36:39]
	v_mfma_f32_16x16x32_bf16 v[32:35], v[172:175], v[188:191], v[32:35]
	v_mfma_f32_16x16x32_bf16 v[20:23], v[164:167], v[196:199], v[20:23]
	v_mfma_f32_16x16x32_bf16 v[16:19], v[172:175], v[196:199], v[16:19]
	v_mfma_f32_16x16x32_bf16 v[4:7], v[164:167], v[204:207], v[4:7]
	v_mfma_f32_16x16x32_bf16 v[0:3], v[172:175], v[204:207], v[0:3]
	v_mfma_f32_16x16x32_bf16 v[52:55], v[168:171], v[184:187], v[52:55]
	v_mfma_f32_16x16x32_bf16 v[48:51], v[176:179], v[184:187], v[48:51]
	v_mfma_f32_16x16x32_bf16 v[36:39], v[168:171], v[192:195], v[36:39]
	v_mfma_f32_16x16x32_bf16 v[32:35], v[176:179], v[192:195], v[32:35]
	v_mfma_f32_16x16x32_bf16 v[20:23], v[168:171], v[200:203], v[20:23]
	v_mfma_f32_16x16x32_bf16 v[16:19], v[176:179], v[200:203], v[16:19]
	v_mfma_f32_16x16x32_bf16 v[4:7], v[168:171], v[208:211], v[4:7]
	v_mfma_f32_16x16x32_bf16 v[0:3], v[176:179], v[208:211], v[0:3]
	s_setprio 0
	s_barrier
	s_add_i32 s8, 0, 0x18000
	s_add_i32 s9, 0, 0x1c000
	v_add_u32_e32 v160, s8, v145
	ds_read_b128 v[140:143], v160
	ds_read_b128 v[152:155], v160 offset:1024
	ds_read_b128 v[156:159], v160 offset:2048
	ds_read_b128 v[160:163], v160 offset:3072
	v_add_u32_e32 v176, s9, v145
	ds_read_b128 v[164:167], v176
	ds_read_b128 v[168:171], v176 offset:1024
	ds_read_b128 v[172:175], v176 offset:2048
	ds_read_b128 v[176:179], v176 offset:3072
	ds_read_b128 v[180:183], v151 offset:32768
	ds_read_b128 v[184:187], v151 offset:33792
	ds_read_b128 v[188:191], v151 offset:34816
	ds_read_b128 v[192:195], v151 offset:35840
	ds_read_b128 v[196:199], v151 offset:36864
	ds_read_b128 v[200:203], v151 offset:37888
	ds_read_b128 v[204:207], v151 offset:38912
	ds_read_b128 v[208:211], v151 offset:39936
	s_add_u32 s60, s66, 0x80000
	s_addc_u32 s61, s67, 0
	s_mov_b32 m0, s29
	v_lshl_add_u64 v[220:221], s[60:61], 0, v[128:129]
	global_load_lds_dwordx4 v[220:221], off
	v_lshl_add_u64 v[220:221], s[60:61], 0, v[130:131]
	s_mov_b32 m0, s30
	s_nop 0
	global_load_lds_dwordx4 v[220:221], off
	s_waitcnt vmcnt(8)
	s_waitcnt lgkmcnt(0)
	s_barrier
	s_setprio 1
	s_waitcnt lgkmcnt(0)
	v_mfma_f32_16x16x32_bf16 v[124:127], v[140:143], v[180:183], v[124:127]
	v_mfma_f32_16x16x32_bf16 v[120:123], v[156:159], v[180:183], v[120:123]
	v_mfma_f32_16x16x32_bf16 v[108:111], v[140:143], v[188:191], v[108:111]
	v_mfma_f32_16x16x32_bf16 v[104:107], v[156:159], v[188:191], v[104:107]
	v_mfma_f32_16x16x32_bf16 v[92:95], v[140:143], v[196:199], v[92:95]
	v_mfma_f32_16x16x32_bf16 v[88:91], v[156:159], v[196:199], v[88:91]
	v_mfma_f32_16x16x32_bf16 v[76:79], v[140:143], v[204:207], v[76:79]
	v_mfma_f32_16x16x32_bf16 v[72:75], v[156:159], v[204:207], v[72:75]
	v_mfma_f32_16x16x32_bf16 v[124:127], v[152:155], v[184:187], v[124:127]
	v_mfma_f32_16x16x32_bf16 v[120:123], v[160:163], v[184:187], v[120:123]
	v_mfma_f32_16x16x32_bf16 v[108:111], v[152:155], v[192:195], v[108:111]
	v_mfma_f32_16x16x32_bf16 v[104:107], v[160:163], v[192:195], v[104:107]
	v_mfma_f32_16x16x32_bf16 v[92:95], v[152:155], v[200:203], v[92:95]
	v_mfma_f32_16x16x32_bf16 v[88:91], v[160:163], v[200:203], v[88:91]
	v_mfma_f32_16x16x32_bf16 v[76:79], v[152:155], v[208:211], v[76:79]
	v_mfma_f32_16x16x32_bf16 v[72:75], v[160:163], v[208:211], v[72:75]
	v_mfma_f32_16x16x32_bf16 v[116:119], v[164:167], v[180:183], v[116:119]
	v_mfma_f32_16x16x32_bf16 v[112:115], v[172:175], v[180:183], v[112:115]
	v_mfma_f32_16x16x32_bf16 v[100:103], v[164:167], v[188:191], v[100:103]
	v_mfma_f32_16x16x32_bf16 v[96:99], v[172:175], v[188:191], v[96:99]
	v_mfma_f32_16x16x32_bf16 v[84:87], v[164:167], v[196:199], v[84:87]
	v_mfma_f32_16x16x32_bf16 v[80:83], v[172:175], v[196:199], v[80:83]
	v_mfma_f32_16x16x32_bf16 v[68:71], v[164:167], v[204:207], v[68:71]
	v_mfma_f32_16x16x32_bf16 v[64:67], v[172:175], v[204:207], v[64:67]
	v_mfma_f32_16x16x32_bf16 v[116:119], v[168:171], v[184:187], v[116:119]
	v_mfma_f32_16x16x32_bf16 v[112:115], v[176:179], v[184:187], v[112:115]
	v_mfma_f32_16x16x32_bf16 v[100:103], v[168:171], v[192:195], v[100:103]
	v_mfma_f32_16x16x32_bf16 v[96:99], v[176:179], v[192:195], v[96:99]
	v_mfma_f32_16x16x32_bf16 v[84:87], v[168:171], v[200:203], v[84:87]
	v_mfma_f32_16x16x32_bf16 v[80:83], v[176:179], v[200:203], v[80:83]
	v_mfma_f32_16x16x32_bf16 v[68:71], v[168:171], v[208:211], v[68:71]
	v_mfma_f32_16x16x32_bf16 v[64:67], v[176:179], v[208:211], v[64:67]
	s_setprio 0
	s_barrier
	ds_read_b128 v[180:183], v151 offset:49152
	ds_read_b128 v[184:187], v151 offset:50176
	ds_read_b128 v[188:191], v151 offset:51200
	ds_read_b128 v[192:195], v151 offset:52224
	ds_read_b128 v[196:199], v151 offset:53248
	ds_read_b128 v[200:203], v151 offset:54272
	ds_read_b128 v[204:207], v151 offset:55296
	ds_read_b128 v[208:211], v151 offset:56320
	s_add_i32 s8, s8, s94
	v_lshl_add_u64 v[212:213], v[212:213], 0, s[20:21]
	s_mov_b32 m0, s8
	s_nop 0
	global_load_lds_dwordx4 v[212:213], off
	s_add_i32 m0, s8, 0x2000
	s_add_u32 s60, s64, 0x80080
	v_lshl_add_u64 v[212:213], v[214:215], 0, s[20:21]
	s_addc_u32 s61, s65, 0
	s_add_i32 s8, s9, s94
	global_load_lds_dwordx4 v[212:213], off
	v_lshl_add_u64 v[212:213], s[60:61], 0, v[128:129]
	s_mov_b32 m0, s8
	s_nop 0
	global_load_lds_dwordx4 v[212:213], off
	v_lshl_add_u64 v[212:213], s[60:61], 0, v[130:131]
	s_add_i32 m0, s8, 0x2000
	s_nop 0
	global_load_lds_dwordx4 v[212:213], off
	v_lshl_add_u64 v[212:213], v[216:217], 0, s[20:21]
	s_mov_b32 m0, s34
	s_nop 0
	global_load_lds_dwordx4 v[212:213], off
	v_lshl_add_u64 v[212:213], v[218:219], 0, s[20:21]
	s_mov_b32 m0, s35
	s_nop 0
	global_load_lds_dwordx4 v[212:213], off
	s_waitcnt vmcnt(8)
	s_waitcnt lgkmcnt(0)
	s_barrier
	s_setprio 1
	s_waitcnt lgkmcnt(0)
	v_mfma_f32_16x16x32_bf16 v[60:63], v[140:143], v[180:183], v[60:63]
	v_mfma_f32_16x16x32_bf16 v[56:59], v[156:159], v[180:183], v[56:59]
	v_mfma_f32_16x16x32_bf16 v[44:47], v[140:143], v[188:191], v[44:47]
	v_mfma_f32_16x16x32_bf16 v[40:43], v[156:159], v[188:191], v[40:43]
	v_mfma_f32_16x16x32_bf16 v[28:31], v[140:143], v[196:199], v[28:31]
	v_mfma_f32_16x16x32_bf16 v[24:27], v[156:159], v[196:199], v[24:27]
	v_mfma_f32_16x16x32_bf16 v[12:15], v[140:143], v[204:207], v[12:15]
	v_mfma_f32_16x16x32_bf16 v[8:11], v[156:159], v[204:207], v[8:11]
	v_mfma_f32_16x16x32_bf16 v[60:63], v[152:155], v[184:187], v[60:63]
	v_mfma_f32_16x16x32_bf16 v[56:59], v[160:163], v[184:187], v[56:59]
	v_mfma_f32_16x16x32_bf16 v[44:47], v[152:155], v[192:195], v[44:47]
	v_mfma_f32_16x16x32_bf16 v[40:43], v[160:163], v[192:195], v[40:43]
	v_mfma_f32_16x16x32_bf16 v[28:31], v[152:155], v[200:203], v[28:31]
	v_mfma_f32_16x16x32_bf16 v[24:27], v[160:163], v[200:203], v[24:27]
	v_mfma_f32_16x16x32_bf16 v[12:15], v[152:155], v[208:211], v[12:15]
	v_mfma_f32_16x16x32_bf16 v[8:11], v[160:163], v[208:211], v[8:11]
	v_mfma_f32_16x16x32_bf16 v[52:55], v[164:167], v[180:183], v[52:55]
	v_mfma_f32_16x16x32_bf16 v[48:51], v[172:175], v[180:183], v[48:51]
	v_mfma_f32_16x16x32_bf16 v[36:39], v[164:167], v[188:191], v[36:39]
	v_mfma_f32_16x16x32_bf16 v[32:35], v[172:175], v[188:191], v[32:35]
	v_mfma_f32_16x16x32_bf16 v[20:23], v[164:167], v[196:199], v[20:23]
	v_mfma_f32_16x16x32_bf16 v[16:19], v[172:175], v[196:199], v[16:19]
	v_mfma_f32_16x16x32_bf16 v[4:7], v[164:167], v[204:207], v[4:7]
	v_mfma_f32_16x16x32_bf16 v[0:3], v[172:175], v[204:207], v[0:3]
	v_mfma_f32_16x16x32_bf16 v[52:55], v[168:171], v[184:187], v[52:55]
	v_mfma_f32_16x16x32_bf16 v[48:51], v[176:179], v[184:187], v[48:51]
	v_mfma_f32_16x16x32_bf16 v[36:39], v[168:171], v[192:195], v[36:39]
	v_mfma_f32_16x16x32_bf16 v[32:35], v[176:179], v[192:195], v[32:35]
	v_mfma_f32_16x16x32_bf16 v[20:23], v[168:171], v[200:203], v[20:23]
	v_mfma_f32_16x16x32_bf16 v[16:19], v[176:179], v[200:203], v[16:19]
	v_mfma_f32_16x16x32_bf16 v[4:7], v[168:171], v[208:211], v[4:7]
	v_mfma_f32_16x16x32_bf16 v[0:3], v[176:179], v[208:211], v[0:3]
	s_setprio 0
	s_barrier
	s_add_i32 s72, s72, 2
	s_add_u32 s62, s62, 0x100
	s_addc_u32 s63, s63, 0
	s_add_u32 s70, s70, 0x100
	s_addc_u32 s71, s71, 0
	s_cmp_gt_u32 s72, 29
	s_cbranch_scc0 .LBB0_2713
	s_and_b64 vcc, exec, s[58:59]
	s_cbranch_vccz .LBB0_2716
	s_barrier

.LBB0_2805:
	ds_read_b128 v[146:149], v155
	ds_read_b128 v[160:163], v155 offset:1024
	ds_read_b128 v[164:167], v155 offset:2048
	ds_read_b128 v[168:171], v155 offset:3072
	ds_read_b128 v[172:175], v156
	ds_read_b128 v[176:179], v156 offset:1024
	ds_read_b128 v[180:183], v156 offset:2048
	ds_read_b128 v[184:187], v156 offset:3072
	ds_read_b128 v[188:191], v157
	ds_read_b128 v[192:195], v157 offset:1024
	ds_read_b128 v[196:199], v157 offset:2048
	ds_read_b128 v[200:203], v157 offset:3072
	ds_read_b128 v[204:207], v157 offset:4096
	ds_read_b128 v[208:211], v157 offset:5120
	ds_read_b128 v[212:215], v157 offset:6144
	ds_read_b128 v[216:219], v157 offset:7168
	s_add_u32 s8, s48, 0xfff80080
	s_addc_u32 s9, s49, -1
	s_cmp_eq_u32 s67, 28
	s_cselect_b32 s61, s21, s9
	s_cselect_b32 s60, s43, s8
	s_cselect_b32 s57, s19, s66
	s_cselect_b32 s56, s45, s65
	v_lshl_add_u64 v[220:221], s[48:49], 0, v[138:139]
	s_add_i32 m0, s29, 0xc000
	s_nop 0
	global_load_lds_dwordx4 v[220:221], off
	v_lshl_add_u64 v[220:221], s[48:49], 0, v[140:141]
	s_add_i32 m0, s29, 0xe000
	s_nop 0
	global_load_lds_dwordx4 v[220:221], off
	s_waitcnt vmcnt(8)
	s_waitcnt lgkmcnt(0)
	s_barrier
	s_setprio 1
	s_waitcnt lgkmcnt(0)
	v_mfma_f32_16x16x32_bf16 v[124:127], v[146:149], v[188:191], v[124:127]
	v_mfma_f32_16x16x32_bf16 v[120:123], v[164:167], v[188:191], v[120:123]
	v_mfma_f32_16x16x32_bf16 v[108:111], v[146:149], v[196:199], v[108:111]
	v_mfma_f32_16x16x32_bf16 v[104:107], v[164:167], v[196:199], v[104:107]
	v_mfma_f32_16x16x32_bf16 v[92:95], v[146:149], v[204:207], v[92:95]
	v_mfma_f32_16x16x32_bf16 v[88:91], v[164:167], v[204:207], v[88:91]
	v_mfma_f32_16x16x32_bf16 v[76:79], v[146:149], v[212:215], v[76:79]
	v_mfma_f32_16x16x32_bf16 v[72:75], v[164:167], v[212:215], v[72:75]
	v_mfma_f32_16x16x32_bf16 v[124:127], v[160:163], v[192:195], v[124:127]
	v_mfma_f32_16x16x32_bf16 v[120:123], v[168:171], v[192:195], v[120:123]
	v_mfma_f32_16x16x32_bf16 v[108:111], v[160:163], v[200:203], v[108:111]
	v_mfma_f32_16x16x32_bf16 v[104:107], v[168:171], v[200:203], v[104:107]
	v_mfma_f32_16x16x32_bf16 v[92:95], v[160:163], v[208:211], v[92:95]
	v_mfma_f32_16x16x32_bf16 v[88:91], v[168:171], v[208:211], v[88:91]
	v_mfma_f32_16x16x32_bf16 v[76:79], v[160:163], v[216:219], v[76:79]
	v_mfma_f32_16x16x32_bf16 v[72:75], v[168:171], v[216:219], v[72:75]
	v_mfma_f32_16x16x32_bf16 v[116:119], v[172:175], v[188:191], v[116:119]
	v_mfma_f32_16x16x32_bf16 v[112:115], v[180:183], v[188:191], v[112:115]
	v_mfma_f32_16x16x32_bf16 v[100:103], v[172:175], v[196:199], v[100:103]
	v_mfma_f32_16x16x32_bf16 v[96:99], v[180:183], v[196:199], v[96:99]
	v_mfma_f32_16x16x32_bf16 v[84:87], v[172:175], v[204:207], v[84:87]
	v_mfma_f32_16x16x32_bf16 v[80:83], v[180:183], v[204:207], v[80:83]
	v_mfma_f32_16x16x32_bf16 v[68:71], v[172:175], v[212:215], v[68:71]
	v_mfma_f32_16x16x32_bf16 v[64:67], v[180:183], v[212:215], v[64:67]
	v_mfma_f32_16x16x32_bf16 v[116:119], v[176:179], v[192:195], v[116:119]
	v_mfma_f32_16x16x32_bf16 v[112:115], v[184:187], v[192:195], v[112:115]
	v_mfma_f32_16x16x32_bf16 v[100:103], v[176:179], v[200:203], v[100:103]
	v_mfma_f32_16x16x32_bf16 v[96:99], v[184:187], v[200:203], v[96:99]
	v_mfma_f32_16x16x32_bf16 v[84:87], v[176:179], v[208:211], v[84:87]
	v_mfma_f32_16x16x32_bf16 v[80:83], v[184:187], v[208:211], v[80:83]
	v_mfma_f32_16x16x32_bf16 v[68:71], v[176:179], v[216:219], v[68:71]
	v_mfma_f32_16x16x32_bf16 v[64:67], v[184:187], v[216:219], v[64:67]
	s_setprio 0
	s_barrier
	ds_read_b128 v[188:191], v157 offset:16384
	ds_read_b128 v[192:195], v157 offset:17408
	ds_read_b128 v[196:199], v157 offset:18432
	ds_read_b128 v[200:203], v157 offset:19456
	ds_read_b128 v[204:207], v157 offset:20480
	ds_read_b128 v[208:211], v157 offset:21504
	ds_read_b128 v[212:215], v157 offset:22528
	ds_read_b128 v[216:219], v157 offset:23552
	s_add_i32 s8, s63, s94
	v_lshl_add_u64 v[220:221], s[56:57], 0, v[130:131]
	s_mov_b32 m0, s8
	s_nop 0
	global_load_lds_dwordx4 v[220:221], off
	s_add_i32 m0, s8, 0x2000
	s_add_u32 s68, s56, 0x80000
	v_lshl_add_u64 v[222:223], s[56:57], 0, v[134:135]
	s_addc_u32 s69, s57, 0
	s_add_i32 s8, s64, s94
	global_load_lds_dwordx4 v[222:223], off
	v_lshl_add_u64 v[224:225], s[68:69], 0, v[130:131]
	s_mov_b32 m0, s8
	v_lshl_add_u64 v[226:227], s[60:61], 0, v[132:133]
	global_load_lds_dwordx4 v[224:225], off
	v_lshl_add_u64 v[224:225], s[68:69], 0, v[134:135]
	s_add_i32 m0, s8, 0x2000
	s_nop 0
	global_load_lds_dwordx4 v[224:225], off
	v_lshl_add_u64 v[224:225], s[60:61], 0, v[128:129]
	s_mov_b32 m0, s29
	s_nop 0
	global_load_lds_dwordx4 v[224:225], off
	s_mov_b32 m0, s30
	s_nop 0
	global_load_lds_dwordx4 v[226:227], off
	s_waitcnt vmcnt(8)
	s_waitcnt lgkmcnt(0)
	s_barrier
	s_setprio 1
	s_waitcnt lgkmcnt(0)
	v_mfma_f32_16x16x32_bf16 v[60:63], v[146:149], v[188:191], v[60:63]
	v_mfma_f32_16x16x32_bf16 v[56:59], v[164:167], v[188:191], v[56:59]
	v_mfma_f32_16x16x32_bf16 v[44:47], v[146:149], v[196:199], v[44:47]
	v_mfma_f32_16x16x32_bf16 v[40:43], v[164:167], v[196:199], v[40:43]
	v_mfma_f32_16x16x32_bf16 v[28:31], v[146:149], v[204:207], v[28:31]
	v_mfma_f32_16x16x32_bf16 v[24:27], v[164:167], v[204:207], v[24:27]
	v_mfma_f32_16x16x32_bf16 v[12:15], v[146:149], v[212:215], v[12:15]
	v_mfma_f32_16x16x32_bf16 v[8:11], v[164:167], v[212:215], v[8:11]
	v_mfma_f32_16x16x32_bf16 v[60:63], v[160:163], v[192:195], v[60:63]
	v_mfma_f32_16x16x32_bf16 v[56:59], v[168:171], v[192:195], v[56:59]
	v_mfma_f32_16x16x32_bf16 v[44:47], v[160:163], v[200:203], v[44:47]
	v_mfma_f32_16x16x32_bf16 v[40:43], v[168:171], v[200:203], v[40:43]
	v_mfma_f32_16x16x32_bf16 v[28:31], v[160:163], v[208:211], v[28:31]
	v_mfma_f32_16x16x32_bf16 v[24:27], v[168:171], v[208:211], v[24:27]
	v_mfma_f32_16x16x32_bf16 v[12:15], v[160:163], v[216:219], v[12:15]
	v_mfma_f32_16x16x32_bf16 v[8:11], v[168:171], v[216:219], v[8:11]
	v_mfma_f32_16x16x32_bf16 v[52:55], v[172:175], v[188:191], v[52:55]
	v_mfma_f32_16x16x32_bf16 v[48:51], v[180:183], v[188:191], v[48:51]
	v_mfma_f32_16x16x32_bf16 v[36:39], v[172:175], v[196:199], v[36:39]
	v_mfma_f32_16x16x32_bf16 v[32:35], v[180:183], v[196:199], v[32:35]
	v_mfma_f32_16x16x32_bf16 v[20:23], v[172:175], v[204:207], v[20:23]
	v_mfma_f32_16x16x32_bf16 v[16:19], v[180:183], v[204:207], v[16:19]
	v_mfma_f32_16x16x32_bf16 v[4:7], v[172:175], v[212:215], v[4:7]
	v_mfma_f32_16x16x32_bf16 v[0:3], v[180:183], v[212:215], v[0:3]
	v_mfma_f32_16x16x32_bf16 v[52:55], v[176:179], v[192:195], v[52:55]
	v_mfma_f32_16x16x32_bf16 v[48:51], v[184:187], v[192:195], v[48:51]
	v_mfma_f32_16x16x32_bf16 v[36:39], v[176:179], v[200:203], v[36:39]
	v_mfma_f32_16x16x32_bf16 v[32:35], v[184:187], v[200:203], v[32:35]
	v_mfma_f32_16x16x32_bf16 v[20:23], v[176:179], v[208:211], v[20:23]
	v_mfma_f32_16x16x32_bf16 v[16:19], v[184:187], v[208:211], v[16:19]
	v_mfma_f32_16x16x32_bf16 v[4:7], v[176:179], v[216:219], v[4:7]
	v_mfma_f32_16x16x32_bf16 v[0:3], v[184:187], v[216:219], v[0:3]
	s_setprio 0
	s_barrier
	s_add_i32 s8, 0, 0x18000
	v_add_u32_e32 v159, s8, v151
	ds_read_b128 v[146:149], v159
	ds_read_b128 v[160:163], v159 offset:1024
	ds_read_b128 v[164:167], v159 offset:2048
	ds_read_b128 v[168:171], v159 offset:3072
	s_add_i32 s9, 0, 0x1c000
	v_add_u32_e32 v159, s9, v151
	ds_read_b128 v[172:175], v159
	ds_read_b128 v[176:179], v159 offset:1024
	ds_read_b128 v[180:183], v159 offset:2048
	ds_read_b128 v[184:187], v159 offset:3072
	ds_read_b128 v[188:191], v157 offset:32768
	ds_read_b128 v[192:195], v157 offset:33792
	ds_read_b128 v[196:199], v157 offset:34816
	ds_read_b128 v[200:203], v157 offset:35840
	ds_read_b128 v[204:207], v157 offset:36864
	ds_read_b128 v[208:211], v157 offset:37888
	ds_read_b128 v[212:215], v157 offset:38912
	ds_read_b128 v[216:219], v157 offset:39936
	s_add_u32 s60, s60, 0x80000
	s_addc_u32 s61, s61, 0
	s_mov_b32 m0, s34
	v_lshl_add_u64 v[228:229], s[60:61], 0, v[128:129]
	global_load_lds_dwordx4 v[228:229], off
	v_lshl_add_u64 v[228:229], s[60:61], 0, v[132:133]
	s_mov_b32 m0, s35
	s_nop 0
	global_load_lds_dwordx4 v[228:229], off
	s_waitcnt vmcnt(8)
	s_waitcnt lgkmcnt(0)
	s_barrier
	s_setprio 1
	s_waitcnt lgkmcnt(0)
	v_mfma_f32_16x16x32_bf16 v[124:127], v[146:149], v[188:191], v[124:127]
	v_mfma_f32_16x16x32_bf16 v[120:123], v[164:167], v[188:191], v[120:123]
	v_mfma_f32_16x16x32_bf16 v[108:111], v[146:149], v[196:199], v[108:111]
	v_mfma_f32_16x16x32_bf16 v[104:107], v[164:167], v[196:199], v[104:107]
	v_mfma_f32_16x16x32_bf16 v[92:95], v[146:149], v[204:207], v[92:95]
	v_mfma_f32_16x16x32_bf16 v[88:91], v[164:167], v[204:207], v[88:91]
	v_mfma_f32_16x16x32_bf16 v[76:79], v[146:149], v[212:215], v[76:79]
	v_mfma_f32_16x16x32_bf16 v[72:75], v[164:167], v[212:215], v[72:75]
	v_mfma_f32_16x16x32_bf16 v[124:127], v[160:163], v[192:195], v[124:127]
	v_mfma_f32_16x16x32_bf16 v[120:123], v[168:171], v[192:195], v[120:123]
	v_mfma_f32_16x16x32_bf16 v[108:111], v[160:163], v[200:203], v[108:111]
	v_mfma_f32_16x16x32_bf16 v[104:107], v[168:171], v[200:203], v[104:107]
	v_mfma_f32_16x16x32_bf16 v[92:95], v[160:163], v[208:211], v[92:95]
	v_mfma_f32_16x16x32_bf16 v[88:91], v[168:171], v[208:211], v[88:91]
	v_mfma_f32_16x16x32_bf16 v[76:79], v[160:163], v[216:219], v[76:79]
	v_mfma_f32_16x16x32_bf16 v[72:75], v[168:171], v[216:219], v[72:75]
	v_mfma_f32_16x16x32_bf16 v[116:119], v[172:175], v[188:191], v[116:119]
	v_mfma_f32_16x16x32_bf16 v[112:115], v[180:183], v[188:191], v[112:115]
	v_mfma_f32_16x16x32_bf16 v[100:103], v[172:175], v[196:199], v[100:103]
	v_mfma_f32_16x16x32_bf16 v[96:99], v[180:183], v[196:199], v[96:99]
	v_mfma_f32_16x16x32_bf16 v[84:87], v[172:175], v[204:207], v[84:87]
	v_mfma_f32_16x16x32_bf16 v[80:83], v[180:183], v[204:207], v[80:83]
	v_mfma_f32_16x16x32_bf16 v[68:71], v[172:175], v[212:215], v[68:71]
	v_mfma_f32_16x16x32_bf16 v[64:67], v[180:183], v[212:215], v[64:67]
	v_mfma_f32_16x16x32_bf16 v[116:119], v[176:179], v[192:195], v[116:119]
	v_mfma_f32_16x16x32_bf16 v[112:115], v[184:187], v[192:195], v[112:115]
	v_mfma_f32_16x16x32_bf16 v[100:103], v[176:179], v[200:203], v[100:103]
	v_mfma_f32_16x16x32_bf16 v[96:99], v[184:187], v[200:203], v[96:99]
	v_mfma_f32_16x16x32_bf16 v[84:87], v[176:179], v[208:211], v[84:87]
	v_mfma_f32_16x16x32_bf16 v[80:83], v[184:187], v[208:211], v[80:83]
	v_mfma_f32_16x16x32_bf16 v[68:71], v[176:179], v[216:219], v[68:71]
	v_mfma_f32_16x16x32_bf16 v[64:67], v[184:187], v[216:219], v[64:67]
	s_setprio 0
	s_barrier
	ds_read_b128 v[188:191], v157 offset:49152
	ds_read_b128 v[192:195], v157 offset:50176
	ds_read_b128 v[196:199], v157 offset:51200
	ds_read_b128 v[200:203], v157 offset:52224
	ds_read_b128 v[204:207], v157 offset:53248
	ds_read_b128 v[208:211], v157 offset:54272
	ds_read_b128 v[212:215], v157 offset:55296
	ds_read_b128 v[216:219], v157 offset:56320
	s_add_i32 s8, s8, s94
	v_lshl_add_u64 v[220:221], v[220:221], 0, s[16:17]
	s_mov_b32 m0, s8
	s_nop 0
	global_load_lds_dwordx4 v[220:221], off
	s_add_i32 m0, s8, 0x2000
	s_add_u32 s56, s56, 0x80080
	v_lshl_add_u64 v[220:221], v[222:223], 0, s[16:17]
	s_addc_u32 s57, s57, 0
	s_add_i32 s8, s9, s94
	global_load_lds_dwordx4 v[220:221], off
	v_lshl_add_u64 v[220:221], s[56:57], 0, v[130:131]
	s_mov_b32 m0, s8
	s_nop 0
	global_load_lds_dwordx4 v[220:221], off
	v_lshl_add_u64 v[220:221], s[56:57], 0, v[134:135]
	s_add_i32 m0, s8, 0x2000
	s_nop 0
	global_load_lds_dwordx4 v[220:221], off
	v_lshl_add_u64 v[220:221], v[224:225], 0, s[16:17]
	s_mov_b32 m0, s47
	s_nop 0
	global_load_lds_dwordx4 v[220:221], off
	v_lshl_add_u64 v[220:221], v[226:227], 0, s[16:17]
	s_mov_b32 m0, s62
	s_nop 0
	global_load_lds_dwordx4 v[220:221], off
	s_waitcnt vmcnt(8)
	s_waitcnt lgkmcnt(0)
	s_barrier
	s_setprio 1
	s_waitcnt lgkmcnt(0)
	v_mfma_f32_16x16x32_bf16 v[60:63], v[146:149], v[188:191], v[60:63]
	v_mfma_f32_16x16x32_bf16 v[56:59], v[164:167], v[188:191], v[56:59]
	v_mfma_f32_16x16x32_bf16 v[44:47], v[146:149], v[196:199], v[44:47]
	v_mfma_f32_16x16x32_bf16 v[40:43], v[164:167], v[196:199], v[40:43]
	v_mfma_f32_16x16x32_bf16 v[28:31], v[146:149], v[204:207], v[28:31]
	v_mfma_f32_16x16x32_bf16 v[24:27], v[164:167], v[204:207], v[24:27]
	v_mfma_f32_16x16x32_bf16 v[12:15], v[146:149], v[212:215], v[12:15]
	v_mfma_f32_16x16x32_bf16 v[8:11], v[164:167], v[212:215], v[8:11]
	v_mfma_f32_16x16x32_bf16 v[60:63], v[160:163], v[192:195], v[60:63]
	v_mfma_f32_16x16x32_bf16 v[56:59], v[168:171], v[192:195], v[56:59]
	v_mfma_f32_16x16x32_bf16 v[44:47], v[160:163], v[200:203], v[44:47]
	v_mfma_f32_16x16x32_bf16 v[40:43], v[168:171], v[200:203], v[40:43]
	v_mfma_f32_16x16x32_bf16 v[28:31], v[160:163], v[208:211], v[28:31]
	v_mfma_f32_16x16x32_bf16 v[24:27], v[168:171], v[208:211], v[24:27]
	v_mfma_f32_16x16x32_bf16 v[12:15], v[160:163], v[216:219], v[12:15]
	v_mfma_f32_16x16x32_bf16 v[8:11], v[168:171], v[216:219], v[8:11]
	v_mfma_f32_16x16x32_bf16 v[52:55], v[172:175], v[188:191], v[52:55]
	v_mfma_f32_16x16x32_bf16 v[48:51], v[180:183], v[188:191], v[48:51]
	v_mfma_f32_16x16x32_bf16 v[36:39], v[172:175], v[196:199], v[36:39]
	v_mfma_f32_16x16x32_bf16 v[32:35], v[180:183], v[196:199], v[32:35]
	v_mfma_f32_16x16x32_bf16 v[20:23], v[172:175], v[204:207], v[20:23]
	v_mfma_f32_16x16x32_bf16 v[16:19], v[180:183], v[204:207], v[16:19]
	v_mfma_f32_16x16x32_bf16 v[4:7], v[172:175], v[212:215], v[4:7]
	v_mfma_f32_16x16x32_bf16 v[0:3], v[180:183], v[212:215], v[0:3]
	v_mfma_f32_16x16x32_bf16 v[52:55], v[176:179], v[192:195], v[52:55]
	v_mfma_f32_16x16x32_bf16 v[48:51], v[184:187], v[192:195], v[48:51]
	v_mfma_f32_16x16x32_bf16 v[36:39], v[176:179], v[200:203], v[36:39]
	v_mfma_f32_16x16x32_bf16 v[32:35], v[184:187], v[200:203], v[32:35]
	v_mfma_f32_16x16x32_bf16 v[20:23], v[176:179], v[208:211], v[20:23]
	v_mfma_f32_16x16x32_bf16 v[16:19], v[184:187], v[208:211], v[16:19]
	v_mfma_f32_16x16x32_bf16 v[4:7], v[176:179], v[216:219], v[4:7]
	v_mfma_f32_16x16x32_bf16 v[0:3], v[184:187], v[216:219], v[0:3]
	s_setprio 0
	s_barrier
	s_add_i32 s67, s67, 2
	s_add_u32 s48, s48, 0x100
	s_addc_u32 s49, s49, 0
	s_add_u32 s65, s65, 0x100
	s_addc_u32 s66, s66, 0
	s_cmp_gt_u32 s67, 29
	s_cbranch_scc0 .LBB0_2805
	s_and_b64 vcc, exec, s[58:59]
	s_cbranch_vccz .LBB0_2808
	s_barrier

.LBB0_2917:
	ds_read_b128 v[140:143], v149
	ds_read_b128 v[152:155], v149 offset:1024
	ds_read_b128 v[156:159], v149 offset:2048
	ds_read_b128 v[160:163], v149 offset:3072
	ds_read_b128 v[164:167], v150
	ds_read_b128 v[168:171], v150 offset:1024
	ds_read_b128 v[172:175], v150 offset:2048
	ds_read_b128 v[176:179], v150 offset:3072
	ds_read_b128 v[180:183], v151
	ds_read_b128 v[184:187], v151 offset:1024
	ds_read_b128 v[188:191], v151 offset:2048
	ds_read_b128 v[192:195], v151 offset:3072
	ds_read_b128 v[196:199], v151 offset:4096
	ds_read_b128 v[200:203], v151 offset:5120
	ds_read_b128 v[204:207], v151 offset:6144
	ds_read_b128 v[208:211], v151 offset:7168
	s_add_u32 s42, s40, 0xffe00080
	s_addc_u32 s43, s41, -1
	s_cmpk_eq_i32 s64, 0x7c
	s_cselect_b32 s45, s21, s43
	s_cselect_b32 s44, s39, s42
	s_cselect_b32 s43, s19, s63
	s_cselect_b32 s42, s61, s62
	v_lshl_add_u64 v[212:213], s[40:41], 0, v[132:133]
	s_add_i32 m0, s29, 0xc000
	s_nop 0
	global_load_lds_dwordx4 v[212:213], off
	v_lshl_add_u64 v[212:213], s[40:41], 0, v[134:135]
	s_add_i32 m0, s29, 0xe000
	s_nop 0
	global_load_lds_dwordx4 v[212:213], off
	s_waitcnt vmcnt(8)
	s_waitcnt lgkmcnt(0)
	s_barrier
	s_setprio 1
	s_waitcnt lgkmcnt(0)
	v_mfma_f32_16x16x32_bf16 v[124:127], v[140:143], v[180:183], v[124:127]
	v_mfma_f32_16x16x32_bf16 v[120:123], v[156:159], v[180:183], v[120:123]
	v_mfma_f32_16x16x32_bf16 v[108:111], v[140:143], v[188:191], v[108:111]
	v_mfma_f32_16x16x32_bf16 v[104:107], v[156:159], v[188:191], v[104:107]
	v_mfma_f32_16x16x32_bf16 v[92:95], v[140:143], v[196:199], v[92:95]
	v_mfma_f32_16x16x32_bf16 v[88:91], v[156:159], v[196:199], v[88:91]
	v_mfma_f32_16x16x32_bf16 v[76:79], v[140:143], v[204:207], v[76:79]
	v_mfma_f32_16x16x32_bf16 v[72:75], v[156:159], v[204:207], v[72:75]
	v_mfma_f32_16x16x32_bf16 v[124:127], v[152:155], v[184:187], v[124:127]
	v_mfma_f32_16x16x32_bf16 v[120:123], v[160:163], v[184:187], v[120:123]
	v_mfma_f32_16x16x32_bf16 v[108:111], v[152:155], v[192:195], v[108:111]
	v_mfma_f32_16x16x32_bf16 v[104:107], v[160:163], v[192:195], v[104:107]
	v_mfma_f32_16x16x32_bf16 v[92:95], v[152:155], v[200:203], v[92:95]
	v_mfma_f32_16x16x32_bf16 v[88:91], v[160:163], v[200:203], v[88:91]
	v_mfma_f32_16x16x32_bf16 v[76:79], v[152:155], v[208:211], v[76:79]
	v_mfma_f32_16x16x32_bf16 v[72:75], v[160:163], v[208:211], v[72:75]
	v_mfma_f32_16x16x32_bf16 v[116:119], v[164:167], v[180:183], v[116:119]
	v_mfma_f32_16x16x32_bf16 v[112:115], v[172:175], v[180:183], v[112:115]
	v_mfma_f32_16x16x32_bf16 v[100:103], v[164:167], v[188:191], v[100:103]
	v_mfma_f32_16x16x32_bf16 v[96:99], v[172:175], v[188:191], v[96:99]
	v_mfma_f32_16x16x32_bf16 v[84:87], v[164:167], v[196:199], v[84:87]
	v_mfma_f32_16x16x32_bf16 v[80:83], v[172:175], v[196:199], v[80:83]
	v_mfma_f32_16x16x32_bf16 v[68:71], v[164:167], v[204:207], v[68:71]
	v_mfma_f32_16x16x32_bf16 v[64:67], v[172:175], v[204:207], v[64:67]
	v_mfma_f32_16x16x32_bf16 v[116:119], v[168:171], v[184:187], v[116:119]
	v_mfma_f32_16x16x32_bf16 v[112:115], v[176:179], v[184:187], v[112:115]
	v_mfma_f32_16x16x32_bf16 v[100:103], v[168:171], v[192:195], v[100:103]
	v_mfma_f32_16x16x32_bf16 v[96:99], v[176:179], v[192:195], v[96:99]
	v_mfma_f32_16x16x32_bf16 v[84:87], v[168:171], v[200:203], v[84:87]
	v_mfma_f32_16x16x32_bf16 v[80:83], v[176:179], v[200:203], v[80:83]
	v_mfma_f32_16x16x32_bf16 v[68:71], v[168:171], v[208:211], v[68:71]
	v_mfma_f32_16x16x32_bf16 v[64:67], v[176:179], v[208:211], v[64:67]
	s_setprio 0
	s_barrier
	ds_read_b128 v[180:183], v151 offset:16384
	ds_read_b128 v[184:187], v151 offset:17408
	ds_read_b128 v[188:191], v151 offset:18432
	ds_read_b128 v[192:195], v151 offset:19456
	ds_read_b128 v[196:199], v151 offset:20480
	ds_read_b128 v[200:203], v151 offset:21504
	ds_read_b128 v[204:207], v151 offset:22528
	ds_read_b128 v[208:211], v151 offset:23552
	s_add_i32 s65, s56, s94
	v_lshl_add_u64 v[212:213], s[42:43], 0, v[128:129]
	s_mov_b32 m0, s65
	s_nop 0
	global_load_lds_dwordx4 v[212:213], off
	s_add_i32 m0, s65, 0x2000
	s_add_u32 s66, s42, 0x200000
	v_lshl_add_u64 v[214:215], s[42:43], 0, v[130:131]
	s_addc_u32 s67, s43, 0
	s_add_i32 s65, s57, s94
	global_load_lds_dwordx4 v[214:215], off
	v_lshl_add_u64 v[216:217], s[66:67], 0, v[128:129]
	s_mov_b32 m0, s65
	v_lshl_add_u64 v[218:219], s[44:45], 0, v[130:131]
	global_load_lds_dwordx4 v[216:217], off
	v_lshl_add_u64 v[216:217], s[66:67], 0, v[130:131]
	s_add_i32 m0, s65, 0x2000
	s_nop 0
	global_load_lds_dwordx4 v[216:217], off
	v_lshl_add_u64 v[216:217], s[44:45], 0, v[128:129]
	s_mov_b32 m0, s29
	s_nop 0
	global_load_lds_dwordx4 v[216:217], off
	s_mov_b32 m0, s30
	s_nop 0
	global_load_lds_dwordx4 v[218:219], off
	s_waitcnt vmcnt(8)
	s_waitcnt lgkmcnt(0)
	s_barrier
	s_setprio 1
	s_waitcnt lgkmcnt(0)
	v_mfma_f32_16x16x32_bf16 v[60:63], v[140:143], v[180:183], v[60:63]
	v_mfma_f32_16x16x32_bf16 v[56:59], v[156:159], v[180:183], v[56:59]
	v_mfma_f32_16x16x32_bf16 v[44:47], v[140:143], v[188:191], v[44:47]
	v_mfma_f32_16x16x32_bf16 v[40:43], v[156:159], v[188:191], v[40:43]
	v_mfma_f32_16x16x32_bf16 v[28:31], v[140:143], v[196:199], v[28:31]
	v_mfma_f32_16x16x32_bf16 v[24:27], v[156:159], v[196:199], v[24:27]
	v_mfma_f32_16x16x32_bf16 v[12:15], v[140:143], v[204:207], v[12:15]
	v_mfma_f32_16x16x32_bf16 v[8:11], v[156:159], v[204:207], v[8:11]
	v_mfma_f32_16x16x32_bf16 v[60:63], v[152:155], v[184:187], v[60:63]
	v_mfma_f32_16x16x32_bf16 v[56:59], v[160:163], v[184:187], v[56:59]
	v_mfma_f32_16x16x32_bf16 v[44:47], v[152:155], v[192:195], v[44:47]
	v_mfma_f32_16x16x32_bf16 v[40:43], v[160:163], v[192:195], v[40:43]
	v_mfma_f32_16x16x32_bf16 v[28:31], v[152:155], v[200:203], v[28:31]
	v_mfma_f32_16x16x32_bf16 v[24:27], v[160:163], v[200:203], v[24:27]
	v_mfma_f32_16x16x32_bf16 v[12:15], v[152:155], v[208:211], v[12:15]
	v_mfma_f32_16x16x32_bf16 v[8:11], v[160:163], v[208:211], v[8:11]
	v_mfma_f32_16x16x32_bf16 v[52:55], v[164:167], v[180:183], v[52:55]
	v_mfma_f32_16x16x32_bf16 v[48:51], v[172:175], v[180:183], v[48:51]
	v_mfma_f32_16x16x32_bf16 v[36:39], v[164:167], v[188:191], v[36:39]
	v_mfma_f32_16x16x32_bf16 v[32:35], v[172:175], v[188:191], v[32:35]
	v_mfma_f32_16x16x32_bf16 v[20:23], v[164:167], v[196:199], v[20:23]
	v_mfma_f32_16x16x32_bf16 v[16:19], v[172:175], v[196:199], v[16:19]
	v_mfma_f32_16x16x32_bf16 v[4:7], v[164:167], v[204:207], v[4:7]
	v_mfma_f32_16x16x32_bf16 v[0:3], v[172:175], v[204:207], v[0:3]
	v_mfma_f32_16x16x32_bf16 v[52:55], v[168:171], v[184:187], v[52:55]
	v_mfma_f32_16x16x32_bf16 v[48:51], v[176:179], v[184:187], v[48:51]
	v_mfma_f32_16x16x32_bf16 v[36:39], v[168:171], v[192:195], v[36:39]
	v_mfma_f32_16x16x32_bf16 v[32:35], v[176:179], v[192:195], v[32:35]
	v_mfma_f32_16x16x32_bf16 v[20:23], v[168:171], v[200:203], v[20:23]
	v_mfma_f32_16x16x32_bf16 v[16:19], v[176:179], v[200:203], v[16:19]
	v_mfma_f32_16x16x32_bf16 v[4:7], v[168:171], v[208:211], v[4:7]
	v_mfma_f32_16x16x32_bf16 v[0:3], v[176:179], v[208:211], v[0:3]
	s_setprio 0
	s_barrier
	s_add_i32 s65, 0, 0x18000
	s_add_i32 s66, 0, 0x1c000
	v_add_u32_e32 v160, s65, v145
	ds_read_b128 v[140:143], v160
	ds_read_b128 v[152:155], v160 offset:1024
	ds_read_b128 v[156:159], v160 offset:2048
	ds_read_b128 v[160:163], v160 offset:3072
	v_add_u32_e32 v176, s66, v145
	ds_read_b128 v[164:167], v176
	ds_read_b128 v[168:171], v176 offset:1024
	ds_read_b128 v[172:175], v176 offset:2048
	ds_read_b128 v[176:179], v176 offset:3072
	ds_read_b128 v[180:183], v151 offset:32768
	ds_read_b128 v[184:187], v151 offset:33792
	ds_read_b128 v[188:191], v151 offset:34816
	ds_read_b128 v[192:195], v151 offset:35840
	ds_read_b128 v[196:199], v151 offset:36864
	ds_read_b128 v[200:203], v151 offset:37888
	ds_read_b128 v[204:207], v151 offset:38912
	ds_read_b128 v[208:211], v151 offset:39936
	s_add_u32 s44, s44, 0x200000
	s_addc_u32 s45, s45, 0
	s_mov_b32 m0, s46
	v_lshl_add_u64 v[220:221], s[44:45], 0, v[128:129]
	global_load_lds_dwordx4 v[220:221], off
	v_lshl_add_u64 v[220:221], s[44:45], 0, v[130:131]
	s_mov_b32 m0, s47
	s_nop 0
	global_load_lds_dwordx4 v[220:221], off
	s_waitcnt vmcnt(8)
	s_waitcnt lgkmcnt(0)
	s_barrier
	s_setprio 1
	s_waitcnt lgkmcnt(0)
	v_mfma_f32_16x16x32_bf16 v[124:127], v[140:143], v[180:183], v[124:127]
	v_mfma_f32_16x16x32_bf16 v[120:123], v[156:159], v[180:183], v[120:123]
	v_mfma_f32_16x16x32_bf16 v[108:111], v[140:143], v[188:191], v[108:111]
	v_mfma_f32_16x16x32_bf16 v[104:107], v[156:159], v[188:191], v[104:107]
	v_mfma_f32_16x16x32_bf16 v[92:95], v[140:143], v[196:199], v[92:95]
	v_mfma_f32_16x16x32_bf16 v[88:91], v[156:159], v[196:199], v[88:91]
	v_mfma_f32_16x16x32_bf16 v[76:79], v[140:143], v[204:207], v[76:79]
	v_mfma_f32_16x16x32_bf16 v[72:75], v[156:159], v[204:207], v[72:75]
	v_mfma_f32_16x16x32_bf16 v[124:127], v[152:155], v[184:187], v[124:127]
	v_mfma_f32_16x16x32_bf16 v[120:123], v[160:163], v[184:187], v[120:123]
	v_mfma_f32_16x16x32_bf16 v[108:111], v[152:155], v[192:195], v[108:111]
	v_mfma_f32_16x16x32_bf16 v[104:107], v[160:163], v[192:195], v[104:107]
	v_mfma_f32_16x16x32_bf16 v[92:95], v[152:155], v[200:203], v[92:95]
	v_mfma_f32_16x16x32_bf16 v[88:91], v[160:163], v[200:203], v[88:91]
	v_mfma_f32_16x16x32_bf16 v[76:79], v[152:155], v[208:211], v[76:79]
	v_mfma_f32_16x16x32_bf16 v[72:75], v[160:163], v[208:211], v[72:75]
	v_mfma_f32_16x16x32_bf16 v[116:119], v[164:167], v[180:183], v[116:119]
	v_mfma_f32_16x16x32_bf16 v[112:115], v[172:175], v[180:183], v[112:115]
	v_mfma_f32_16x16x32_bf16 v[100:103], v[164:167], v[188:191], v[100:103]
	v_mfma_f32_16x16x32_bf16 v[96:99], v[172:175], v[188:191], v[96:99]
	v_mfma_f32_16x16x32_bf16 v[84:87], v[164:167], v[196:199], v[84:87]
	v_mfma_f32_16x16x32_bf16 v[80:83], v[172:175], v[196:199], v[80:83]
	v_mfma_f32_16x16x32_bf16 v[68:71], v[164:167], v[204:207], v[68:71]
	v_mfma_f32_16x16x32_bf16 v[64:67], v[172:175], v[204:207], v[64:67]
	v_mfma_f32_16x16x32_bf16 v[116:119], v[168:171], v[184:187], v[116:119]
	v_mfma_f32_16x16x32_bf16 v[112:115], v[176:179], v[184:187], v[112:115]
	v_mfma_f32_16x16x32_bf16 v[100:103], v[168:171], v[192:195], v[100:103]
	v_mfma_f32_16x16x32_bf16 v[96:99], v[176:179], v[192:195], v[96:99]
	v_mfma_f32_16x16x32_bf16 v[84:87], v[168:171], v[200:203], v[84:87]
	v_mfma_f32_16x16x32_bf16 v[80:83], v[176:179], v[200:203], v[80:83]
	v_mfma_f32_16x16x32_bf16 v[68:71], v[168:171], v[208:211], v[68:71]
	v_mfma_f32_16x16x32_bf16 v[64:67], v[176:179], v[208:211], v[64:67]
	s_setprio 0
	s_barrier
	ds_read_b128 v[180:183], v151 offset:49152
	ds_read_b128 v[184:187], v151 offset:50176
	ds_read_b128 v[188:191], v151 offset:51200
	ds_read_b128 v[192:195], v151 offset:52224
	ds_read_b128 v[196:199], v151 offset:53248
	ds_read_b128 v[200:203], v151 offset:54272
	ds_read_b128 v[204:207], v151 offset:55296
	ds_read_b128 v[208:211], v151 offset:56320
	s_add_i32 s44, s65, s94
	v_lshl_add_u64 v[212:213], v[212:213], 0, s[16:17]
	s_mov_b32 m0, s44
	s_nop 0
	global_load_lds_dwordx4 v[212:213], off
	s_add_i32 m0, s44, 0x2000
	s_add_u32 s42, s42, 0x200080
	v_lshl_add_u64 v[212:213], v[214:215], 0, s[16:17]
	s_addc_u32 s43, s43, 0
	s_add_i32 s44, s66, s94
	global_load_lds_dwordx4 v[212:213], off
	v_lshl_add_u64 v[212:213], s[42:43], 0, v[128:129]
	s_mov_b32 m0, s44
	s_nop 0
	global_load_lds_dwordx4 v[212:213], off
	v_lshl_add_u64 v[212:213], s[42:43], 0, v[130:131]
	s_add_i32 m0, s44, 0x2000
	s_nop 0
	global_load_lds_dwordx4 v[212:213], off
	v_lshl_add_u64 v[212:213], v[216:217], 0, s[16:17]
	s_mov_b32 m0, s48
	s_nop 0
	global_load_lds_dwordx4 v[212:213], off
	v_lshl_add_u64 v[212:213], v[218:219], 0, s[16:17]
	s_mov_b32 m0, s49
	s_nop 0
	global_load_lds_dwordx4 v[212:213], off
	s_waitcnt vmcnt(8)
	s_waitcnt lgkmcnt(0)
	s_barrier
	s_setprio 1
	s_waitcnt lgkmcnt(0)
	v_mfma_f32_16x16x32_bf16 v[60:63], v[140:143], v[180:183], v[60:63]
	v_mfma_f32_16x16x32_bf16 v[56:59], v[156:159], v[180:183], v[56:59]
	v_mfma_f32_16x16x32_bf16 v[44:47], v[140:143], v[188:191], v[44:47]
	v_mfma_f32_16x16x32_bf16 v[40:43], v[156:159], v[188:191], v[40:43]
	v_mfma_f32_16x16x32_bf16 v[28:31], v[140:143], v[196:199], v[28:31]
	v_mfma_f32_16x16x32_bf16 v[24:27], v[156:159], v[196:199], v[24:27]
	v_mfma_f32_16x16x32_bf16 v[12:15], v[140:143], v[204:207], v[12:15]
	v_mfma_f32_16x16x32_bf16 v[8:11], v[156:159], v[204:207], v[8:11]
	v_mfma_f32_16x16x32_bf16 v[60:63], v[152:155], v[184:187], v[60:63]
	v_mfma_f32_16x16x32_bf16 v[56:59], v[160:163], v[184:187], v[56:59]
	v_mfma_f32_16x16x32_bf16 v[44:47], v[152:155], v[192:195], v[44:47]
	v_mfma_f32_16x16x32_bf16 v[40:43], v[160:163], v[192:195], v[40:43]
	v_mfma_f32_16x16x32_bf16 v[28:31], v[152:155], v[200:203], v[28:31]
	v_mfma_f32_16x16x32_bf16 v[24:27], v[160:163], v[200:203], v[24:27]
	v_mfma_f32_16x16x32_bf16 v[12:15], v[152:155], v[208:211], v[12:15]
	v_mfma_f32_16x16x32_bf16 v[8:11], v[160:163], v[208:211], v[8:11]
	v_mfma_f32_16x16x32_bf16 v[52:55], v[164:167], v[180:183], v[52:55]
	v_mfma_f32_16x16x32_bf16 v[48:51], v[172:175], v[180:183], v[48:51]
	v_mfma_f32_16x16x32_bf16 v[36:39], v[164:167], v[188:191], v[36:39]
	v_mfma_f32_16x16x32_bf16 v[32:35], v[172:175], v[188:191], v[32:35]
	v_mfma_f32_16x16x32_bf16 v[20:23], v[164:167], v[196:199], v[20:23]
	v_mfma_f32_16x16x32_bf16 v[16:19], v[172:175], v[196:199], v[16:19]
	v_mfma_f32_16x16x32_bf16 v[4:7], v[164:167], v[204:207], v[4:7]
	v_mfma_f32_16x16x32_bf16 v[0:3], v[172:175], v[204:207], v[0:3]
	v_mfma_f32_16x16x32_bf16 v[52:55], v[168:171], v[184:187], v[52:55]
	v_mfma_f32_16x16x32_bf16 v[48:51], v[176:179], v[184:187], v[48:51]
	v_mfma_f32_16x16x32_bf16 v[36:39], v[168:171], v[192:195], v[36:39]
	v_mfma_f32_16x16x32_bf16 v[32:35], v[176:179], v[192:195], v[32:35]
	v_mfma_f32_16x16x32_bf16 v[20:23], v[168:171], v[200:203], v[20:23]
	v_mfma_f32_16x16x32_bf16 v[16:19], v[176:179], v[200:203], v[16:19]
	v_mfma_f32_16x16x32_bf16 v[4:7], v[168:171], v[208:211], v[4:7]
	v_mfma_f32_16x16x32_bf16 v[0:3], v[176:179], v[208:211], v[0:3]
	s_setprio 0
	s_barrier
	s_add_i32 s64, s64, 2
	s_add_u32 s40, s40, 0x100
	s_addc_u32 s41, s41, 0
	s_add_u32 s62, s62, 0x100
	s_addc_u32 s63, s63, 0
	s_cmpk_gt_u32 s64, 0x7d
	s_cbranch_scc0 .LBB0_2917
	s_and_b64 vcc, exec, s[58:59]
	s_cbranch_vccz .LBB0_2920
	s_barrier
